# more wave_sum butterflies: in-place exact VALU shuffles (DPP row_ror/quad_perm/row_shl+shr, permlane swap+select) instead of ds_bpermute
# baseline (speedup 1.0000x reference)
.LBB0_40:
	s_nop 0
	v_mov_b32_e32 v1, v139
	v_cmp_lt_i32_e32 vcc, v179, v178
	v_ashrrev_i32_e32 v0, 5, v1
	v_and_b32_e32 v0, -2, v0
	v_add_u32_e32 v0, s5, v0
	v_lshlrev_b32_e32 v1, 2, v1
	v_and_b32_e32 v4, 0xfc, v1
	v_ashrrev_i32_e32 v1, 31, v0
	v_lshlrev_b64 v[2:3], 12, v[0:1]
	v_lshl_add_u64 v[2:3], s[14:15], 0, v[2:3]
	v_lshlrev_b32_e32 v136, 1, v4
	s_waitcnt vmcnt(8)
	v_lshl_add_u64 v[32:33], v[2:3], 0, v[136:137]
	global_load_dwordx2 v[36:37], v[32:33], off offset:2048
	global_load_dwordx2 v[38:39], v[32:33], off offset:2560
	global_load_dwordx2 v[40:41], v[32:33], off offset:3072
	global_load_dwordx2 v[42:43], v[32:33], off offset:3584
	v_add_u32_e32 v0, 1, v0
	v_ashrrev_i32_e32 v1, 31, v0
	v_lshlrev_b64 v[0:1], 12, v[0:1]
	v_lshl_add_u64 v[0:1], s[14:15], 0, v[0:1]
	v_lshl_add_u64 v[34:35], v[0:1], 0, v[136:137]
	global_load_dwordx2 v[44:45], v[34:35], off offset:2048
	global_load_dwordx2 v[46:47], v[34:35], off offset:2560
	global_load_dwordx2 v[48:49], v[34:35], off offset:3072
	global_load_dwordx2 v[50:51], v[34:35], off offset:3584
	v_cndmask_b32_e32 v52, v176, v179, vcc
	v_cmp_lt_i32_e32 vcc, v180, v178
	v_lshlrev_b32_e32 v84, 2, v52
	v_lshlrev_b32_e32 v4, 2, v4
	v_cndmask_b32_e32 v52, v176, v180, vcc
	v_cmp_lt_i32_e32 vcc, v181, v178
	v_lshlrev_b32_e32 v85, 2, v52
	global_load_dwordx4 v[24:27], v4, s[34:35]
	global_load_dwordx4 v[28:31], v4, s[96:97]
	global_load_dwordx4 v[16:19], v4, s[34:35] offset:1024
	global_load_dwordx4 v[20:23], v4, s[96:97] offset:1024
	global_load_dwordx4 v[8:11], v4, s[34:35] offset:2048
	global_load_dwordx4 v[12:15], v4, s[96:97] offset:2048
	global_load_dwordx4 v[0:3], v4, s[34:35] offset:3072
	s_nop 0
	global_load_dwordx4 v[4:7], v4, s[96:97] offset:3072
	v_cndmask_b32_e32 v52, v176, v181, vcc
	v_cmp_lt_i32_e32 vcc, v182, v178
	v_lshlrev_b32_e32 v86, 2, v52
	s_add_i32 s6, s6, s10
	v_cndmask_b32_e32 v52, v176, v182, vcc
	v_cmp_lt_i32_e32 vcc, v183, v178
	v_lshlrev_b32_e32 v87, 2, v52
	s_add_i32 s5, s5, s4
	v_cndmask_b32_e32 v52, v176, v183, vcc
	v_cmp_lt_i32_e32 vcc, v184, v178
	v_lshlrev_b32_e32 v88, 2, v52
	s_cmpk_gt_i32 s6, 0x5ff
	v_cndmask_b32_e32 v52, v176, v184, vcc
	v_lshlrev_b32_e32 v89, 2, v52
	s_waitcnt vmcnt(15)
	v_lshlrev_b32_e32 v60, 16, v36
	v_and_b32_e32 v61, 0xffff0000, v36
	s_waitcnt vmcnt(13)
	v_lshlrev_b32_e32 v54, 16, v40
	s_waitcnt vmcnt(12)
	v_lshlrev_b32_e32 v52, 16, v42
	v_and_b32_e32 v53, 0xffff0000, v42
	v_and_b32_e32 v55, 0xffff0000, v40
	v_lshlrev_b32_e32 v42, 16, v43
	v_lshlrev_b32_e32 v40, 16, v41
	v_mov_b32_e32 v56, v54
	v_mov_b32_e32 v57, v52
	v_mov_b32_e32 v58, v55
	v_mov_b32_e32 v59, v53
	v_and_b32_e32 v43, 0xffff0000, v43
	v_and_b32_e32 v41, 0xffff0000, v41
	v_pk_add_f32 v[56:57], v[56:57], v[58:59]
	v_mov_b32_e32 v58, v40
	v_mov_b32_e32 v59, v42
	v_pk_add_f32 v[56:57], v[56:57], v[58:59]
	v_mov_b32_e32 v58, v41
	v_mov_b32_e32 v59, v43
	v_pk_add_f32 v[56:57], v[56:57], v[58:59]
	v_lshlrev_b32_e32 v58, 16, v38
	v_and_b32_e32 v59, 0xffff0000, v38
	v_lshlrev_b32_e32 v38, 16, v39
	v_lshlrev_b32_e32 v36, 16, v37
	v_mov_b32_e32 v62, v60
	v_mov_b32_e32 v63, v58
	v_mov_b32_e32 v64, v61
	v_mov_b32_e32 v65, v59
	v_and_b32_e32 v39, 0xffff0000, v39
	v_and_b32_e32 v37, 0xffff0000, v37
	v_pk_add_f32 v[62:63], v[62:63], v[64:65]
	v_mov_b32_e32 v64, v36
	v_mov_b32_e32 v65, v38
	v_pk_add_f32 v[62:63], v[62:63], v[64:65]
	v_mov_b32_e32 v64, v37
	v_mov_b32_e32 v65, v39
	v_pk_add_f32 v[62:63], v[62:63], v[64:65]
	s_waitcnt vmcnt(9)
	v_lshlrev_b32_e32 v66, 16, v48
	v_add_f32_e32 v62, 0, v62
	v_add_f32_e32 v62, v62, v63
	v_add_f32_e32 v56, v62, v56
	v_add_f32_e32 v56, v56, v57
	s_nop 1
	v_mov_b32_e32 v254, v56
	v_mov_b32_e32 v57, v56
	v_cmp_gt_u32_e64 s[98:99], 32, v176
	s_nop 0
	v_permlane32_swap_b32_e32 v57, v254
	v_cndmask_b32_e64 v57, v57, v254, s[98:99]
	v_and_b32_e32 v67, 0xffff0000, v48
	v_lshlrev_b32_e32 v48, 16, v49
	v_mov_b32_e32 v68, v66
	v_mov_b32_e32 v70, v67
	s_waitcnt lgkmcnt(0)
	v_add_f32_e32 v56, v56, v57
	s_nop 1
	v_mov_b32_e32 v254, v56
	v_mov_b32_e32 v57, v56
	v_and_b32_e32 v255, 16, v176
	v_cmp_eq_u32_e64 s[98:99], 0, v255
	s_nop 0
	v_permlane16_swap_b32_e32 v57, v254
	v_cndmask_b32_e64 v57, v57, v254, s[98:99]
	v_and_b32_e32 v49, 0xffff0000, v49
	v_lshlrev_b32_e32 v72, 16, v44
	v_and_b32_e32 v73, 0xffff0000, v44
	v_lshlrev_b32_e32 v44, 16, v45
	s_waitcnt lgkmcnt(0)
	v_add_f32_e32 v56, v56, v57
	s_nop 1
	v_mov_b32_dpp v57, v56 row_ror:8 row_mask:0xf bank_mask:0xf
	v_mov_b32_e32 v74, v72
	v_mov_b32_e32 v76, v73
	v_and_b32_e32 v45, 0xffff0000, v45
	s_waitcnt lgkmcnt(0)
	v_add_f32_e32 v56, v56, v57
	s_nop 1
	v_mov_b32_dpp v57, v56 row_shl:4 row_mask:0xf bank_mask:0x5
	v_mov_b32_dpp v57, v56 row_shr:4 row_mask:0xf bank_mask:0xa
	s_waitcnt lgkmcnt(0)
	v_add_f32_e32 v56, v56, v57
	s_nop 1
	v_mov_b32_dpp v57, v56 quad_perm:[2,3,0,1] row_mask:0xf bank_mask:0xf
	s_waitcnt lgkmcnt(0)
	v_add_f32_e32 v56, v56, v57
	s_nop 1
	v_mov_b32_dpp v57, v56 quad_perm:[1,0,3,2] row_mask:0xf bank_mask:0xf
	s_waitcnt lgkmcnt(0)
	v_add_f32_e32 v56, v56, v57
	v_mul_f32_e32 v56, 0x3a800000, v56
	v_pk_add_f32 v[60:61], v[60:61], v[56:57] op_sel_hi:[1,0] neg_lo:[0,1] neg_hi:[0,1]
	v_pk_add_f32 v[36:37], v[36:37], v[56:57] op_sel_hi:[1,0] neg_lo:[0,1] neg_hi:[0,1]
	v_pk_add_f32 v[58:59], v[58:59], v[56:57] op_sel_hi:[1,0] neg_lo:[0,1] neg_hi:[0,1]
	v_pk_add_f32 v[62:63], v[38:39], v[56:57] op_sel_hi:[1,0] neg_lo:[0,1] neg_hi:[0,1]
	v_pk_add_f32 v[54:55], v[54:55], v[56:57] op_sel_hi:[1,0] neg_lo:[0,1] neg_hi:[0,1]
	v_pk_add_f32 v[64:65], v[40:41], v[56:57] op_sel_hi:[1,0] neg_lo:[0,1] neg_hi:[0,1]
	v_pk_add_f32 v[52:53], v[52:53], v[56:57] op_sel_hi:[1,0] neg_lo:[0,1] neg_hi:[0,1]
	v_pk_add_f32 v[56:57], v[42:43], v[56:57] op_sel_hi:[1,0] neg_lo:[0,1] neg_hi:[0,1]
	s_waitcnt vmcnt(8)
	v_lshlrev_b32_e32 v42, 16, v50
	v_and_b32_e32 v43, 0xffff0000, v50
	v_lshlrev_b32_e32 v50, 16, v51
	v_mov_b32_e32 v69, v42
	v_mov_b32_e32 v71, v43
	v_and_b32_e32 v51, 0xffff0000, v51
	v_pk_add_f32 v[68:69], v[68:69], v[70:71]
	v_mov_b32_e32 v70, v48
	v_mov_b32_e32 v71, v50
	v_pk_add_f32 v[68:69], v[68:69], v[70:71]
	v_mov_b32_e32 v70, v49
	v_mov_b32_e32 v71, v51
	v_pk_add_f32 v[68:69], v[68:69], v[70:71]
	v_lshlrev_b32_e32 v70, 16, v46
	v_and_b32_e32 v71, 0xffff0000, v46
	v_lshlrev_b32_e32 v46, 16, v47
	v_mov_b32_e32 v75, v70
	v_mov_b32_e32 v77, v71
	v_and_b32_e32 v47, 0xffff0000, v47
	v_pk_add_f32 v[74:75], v[74:75], v[76:77]
	v_mov_b32_e32 v76, v44
	v_mov_b32_e32 v77, v46
	v_pk_add_f32 v[74:75], v[74:75], v[76:77]
	v_mov_b32_e32 v76, v45
	v_mov_b32_e32 v77, v47
	v_pk_add_f32 v[74:75], v[74:75], v[76:77]
	v_mov_b32_e32 v77, v61
	v_add_f32_e32 v74, 0, v74
	v_add_f32_e32 v74, v74, v75
	v_add_f32_e32 v68, v74, v68
	v_add_f32_e32 v68, v68, v69
	s_nop 1
	v_mov_b32_e32 v254, v68
	v_mov_b32_e32 v69, v68
	v_cmp_gt_u32_e64 s[98:99], 32, v176
	s_nop 0
	v_permlane32_swap_b32_e32 v69, v254
	v_cndmask_b32_e64 v69, v69, v254, s[98:99]
	v_mov_b32_e32 v75, v60
	v_pk_mul_f32 v[38:39], v[52:53], v[52:53]
	v_pk_mul_f32 v[40:41], v[56:57], v[56:57]
	s_waitcnt lgkmcnt(0)
	v_add_f32_e32 v68, v68, v69
	s_nop 1
	v_mov_b32_e32 v254, v68
	v_mov_b32_e32 v69, v68
	v_and_b32_e32 v255, 16, v176
	v_cmp_eq_u32_e64 s[98:99], 0, v255
	s_nop 0
	v_permlane16_swap_b32_e32 v69, v254
	v_cndmask_b32_e64 v69, v69, v254, s[98:99]
	s_waitcnt lgkmcnt(0)
	v_add_f32_e32 v68, v68, v69
	s_nop 1
	v_mov_b32_dpp v69, v68 row_ror:8 row_mask:0xf bank_mask:0xf
	s_waitcnt lgkmcnt(0)
	v_add_f32_e32 v68, v68, v69
	s_nop 1
	v_mov_b32_dpp v69, v68 row_shl:4 row_mask:0xf bank_mask:0x5
	v_mov_b32_dpp v69, v68 row_shr:4 row_mask:0xf bank_mask:0xa
	s_waitcnt lgkmcnt(0)
	v_add_f32_e32 v68, v68, v69
	s_nop 1
	v_mov_b32_dpp v69, v68 quad_perm:[2,3,0,1] row_mask:0xf bank_mask:0xf
	s_waitcnt lgkmcnt(0)
	v_add_f32_e32 v68, v68, v69
	s_nop 1
	v_mov_b32_dpp v69, v68 quad_perm:[1,0,3,2] row_mask:0xf bank_mask:0xf
	s_waitcnt lgkmcnt(0)
	v_add_f32_e32 v68, v68, v69
	v_mul_f32_e32 v68, 0x3a800000, v68
	v_pk_add_f32 v[72:73], v[72:73], v[68:69] op_sel_hi:[1,0] neg_lo:[0,1] neg_hi:[0,1]
	v_pk_add_f32 v[70:71], v[70:71], v[68:69] op_sel_hi:[1,0] neg_lo:[0,1] neg_hi:[0,1]
	v_mov_b32_e32 v76, v73
	v_mov_b32_e32 v74, v72
	v_pk_mul_f32 v[76:77], v[76:77], v[76:77]
	v_pk_add_f32 v[78:79], v[46:47], v[68:69] op_sel_hi:[1,0] neg_lo:[0,1] neg_hi:[0,1]
	v_pk_fma_f32 v[74:75], v[74:75], v[74:75], v[76:77]
	v_pk_add_f32 v[76:77], v[44:45], v[68:69] op_sel_hi:[1,0] neg_lo:[0,1] neg_hi:[0,1]
	v_mov_b32_e32 v45, v36
	v_mov_b32_e32 v44, v76
	v_pk_fma_f32 v[44:45], v[44:45], v[44:45], v[74:75]
	v_mov_b32_e32 v46, v77
	v_mov_b32_e32 v47, v37
	v_pk_fma_f32 v[44:45], v[46:47], v[46:47], v[44:45]
	v_mov_b32_e32 v46, v70
	v_mov_b32_e32 v47, v58
	v_pk_fma_f32 v[44:45], v[46:47], v[46:47], v[44:45]
	v_mov_b32_e32 v46, v71
	v_mov_b32_e32 v47, v59
	v_pk_fma_f32 v[44:45], v[46:47], v[46:47], v[44:45]
	v_mov_b32_e32 v46, v78
	v_mov_b32_e32 v47, v62
	v_pk_add_f32 v[66:67], v[66:67], v[68:69] op_sel_hi:[1,0] neg_lo:[0,1] neg_hi:[0,1]
	v_pk_fma_f32 v[44:45], v[46:47], v[46:47], v[44:45]
	v_mov_b32_e32 v46, v79
	v_mov_b32_e32 v47, v63
	v_pk_fma_f32 v[44:45], v[46:47], v[46:47], v[44:45]
	v_mov_b32_e32 v46, v66
	v_mov_b32_e32 v47, v54
	v_pk_add_f32 v[80:81], v[48:49], v[68:69] op_sel_hi:[1,0] neg_lo:[0,1] neg_hi:[0,1]
	v_pk_fma_f32 v[44:45], v[46:47], v[46:47], v[44:45]
	v_mov_b32_e32 v46, v67
	v_mov_b32_e32 v47, v55
	v_pk_add_f32 v[82:83], v[42:43], v[68:69] op_sel_hi:[1,0] neg_lo:[0,1] neg_hi:[0,1]
	v_pk_fma_f32 v[44:45], v[46:47], v[46:47], v[44:45]
	v_mov_b32_e32 v46, v80
	v_mov_b32_e32 v47, v64
	v_pk_mul_f32 v[42:43], v[82:83], v[82:83]
	v_pk_fma_f32 v[44:45], v[46:47], v[46:47], v[44:45]
	v_mov_b32_e32 v46, v81
	v_mov_b32_e32 v47, v65
	v_pk_fma_f32 v[44:45], v[46:47], v[46:47], v[44:45]
	v_mov_b32_e32 v46, v42
	v_mov_b32_e32 v47, v38
	v_pk_add_f32 v[68:69], v[50:51], v[68:69] op_sel_hi:[1,0] neg_lo:[0,1] neg_hi:[0,1]
	v_pk_add_f32 v[44:45], v[46:47], v[44:45]
	v_pk_mul_f32 v[46:47], v[68:69], v[68:69]
	v_mov_b32_e32 v38, v43
	v_pk_add_f32 v[38:39], v[38:39], v[44:45]
	v_mov_b32_e32 v42, v46
	v_mov_b32_e32 v43, v40
	v_pk_add_f32 v[38:39], v[42:43], v[38:39]
	v_mov_b32_e32 v40, v47
	v_pk_add_f32 v[38:39], v[40:41], v[38:39]
	v_mov_b32_e32 v40, v38
	v_mov_b32_e32 v41, v39
	s_nop 1
	v_permlane32_swap_b32_e32 v40, v38
	v_permlane32_swap_b32_e32 v41, v39
	v_pk_add_f32 v[38:39], v[38:39], v[40:41]
	v_mov_b32_e32 v40, v38
	v_mov_b32_e32 v41, v39
	s_nop 1
	v_permlane16_swap_b32_e32 v40, v38
	v_permlane16_swap_b32_e32 v41, v39
	v_pk_add_f32 v[38:39], v[38:39], v[40:41]
	s_nop 1
	v_add_f32_dpp v38, v38, v38 row_ror:8 row_mask:0xf bank_mask:0xf
	v_add_f32_dpp v39, v39, v39 row_ror:8 row_mask:0xf bank_mask:0xf
	s_nop 0
	v_add_f32_dpp v38, v38, v38 row_ror:4 row_mask:0xf bank_mask:0xf
	v_add_f32_dpp v39, v39, v39 row_ror:4 row_mask:0xf bank_mask:0xf
	s_nop 0
	v_add_f32_dpp v38, v38, v38 row_ror:2 row_mask:0xf bank_mask:0xf
	v_add_f32_dpp v39, v39, v39 row_ror:2 row_mask:0xf bank_mask:0xf
	s_nop 0
	v_add_f32_dpp v38, v38, v38 row_ror:1 row_mask:0xf bank_mask:0xf
	v_add_f32_dpp v39, v39, v39 row_ror:1 row_mask:0xf bank_mask:0xf
	s_nop 0
	v_pk_fma_f32 v[74:75], v[38:39], s[8:9], v[138:139] op_sel_hi:[1,0,0]
	s_nop 0
	v_mul_f32_e32 v38, 0x4b800000, v75
	v_cmp_gt_f32_e64 s[0:1], s33, v75
	v_cmp_gt_f32_e32 vcc, s33, v74
	s_nop 0
	v_cndmask_b32_e64 v38, v75, v38, s[0:1]
	v_rsq_f32_e32 v38, v38
	s_nop 0
	v_mul_f32_e32 v39, 0x45800000, v38
	v_cndmask_b32_e64 v48, v38, v39, s[0:1]
	v_pk_mul_f32 v[40:41], v[60:61], v[48:49] op_sel_hi:[1,0]
	v_pk_mul_f32 v[36:37], v[36:37], v[48:49] op_sel_hi:[1,0]
	v_pk_mul_f32 v[42:43], v[62:63], v[48:49] op_sel_hi:[1,0]
	s_waitcnt vmcnt(6)
	v_pk_fma_f32 v[38:39], v[26:27], v[36:37], v[30:31]
	v_pk_fma_f32 v[36:37], v[24:25], v[40:41], v[28:29]
	v_pk_mul_f32 v[40:41], v[58:59], v[48:49] op_sel_hi:[1,0]
	v_pk_mul_f32 v[44:45], v[54:55], v[48:49] op_sel_hi:[1,0]
	v_pk_mul_f32 v[46:47], v[64:65], v[48:49] op_sel_hi:[1,0]
	v_pk_mul_f32 v[52:53], v[52:53], v[48:49] op_sel_hi:[1,0]
	v_pk_mul_f32 v[48:49], v[56:57], v[48:49] op_sel_hi:[1,0]
	s_waitcnt vmcnt(4)
	v_pk_fma_f32 v[40:41], v[16:17], v[40:41], v[20:21]
	s_waitcnt vmcnt(0)
	v_pk_fma_f32 v[50:51], v[2:3], v[48:49], v[6:7]
	v_pk_fma_f32 v[48:49], v[0:1], v[52:53], v[4:5]
	v_mul_f32_e32 v52, 0x4b800000, v74
	v_cndmask_b32_e32 v52, v74, v52, vcc
	v_rsq_f32_e32 v52, v52
	v_pk_fma_f32 v[44:45], v[8:9], v[44:45], v[12:13]
	v_pk_fma_f32 v[42:43], v[18:19], v[42:43], v[22:23]
	v_pk_fma_f32 v[46:47], v[10:11], v[46:47], v[14:15]
	v_mul_f32_e32 v53, 0x45800000, v52
	v_cndmask_b32_e32 v52, v52, v53, vcc
	v_pk_mul_f32 v[54:55], v[72:73], v[52:53] op_sel_hi:[1,0]
	v_pk_mul_f32 v[56:57], v[76:77], v[52:53] op_sel_hi:[1,0]
	v_pk_fma_f32 v[24:25], v[24:25], v[54:55], v[28:29]
	v_pk_mul_f32 v[28:29], v[70:71], v[52:53] op_sel_hi:[1,0]
	v_pk_fma_f32 v[26:27], v[26:27], v[56:57], v[30:31]
	v_pk_fma_f32 v[16:17], v[16:17], v[28:29], v[20:21]
	v_pk_mul_f32 v[20:21], v[66:67], v[52:53] op_sel_hi:[1,0]
	v_pk_mul_f32 v[30:31], v[78:79], v[52:53] op_sel_hi:[1,0]
	v_pk_fma_f32 v[8:9], v[8:9], v[20:21], v[12:13]
	v_pk_mul_f32 v[12:13], v[82:83], v[52:53] op_sel_hi:[1,0]
	v_pk_fma_f32 v[18:19], v[18:19], v[30:31], v[22:23]
	v_pk_mul_f32 v[22:23], v[80:81], v[52:53] op_sel_hi:[1,0]
	v_pk_fma_f32 v[0:1], v[0:1], v[12:13], v[4:5]
	v_lshl_add_u64 v[4:5], v[32:33], 0, v[136:137]
	v_pk_fma_f32 v[10:11], v[10:11], v[22:23], v[14:15]
	v_pk_mul_f32 v[14:15], v[68:69], v[52:53] op_sel_hi:[1,0]
	global_store_dwordx4 v[4:5], v[36:39], off
	global_store_dwordx4 v[4:5], v[40:43], off offset:1024
	global_store_dwordx4 v[4:5], v[44:47], off offset:2048
	global_store_dwordx4 v[4:5], v[48:51], off offset:3072
	v_lshl_add_u64 v[4:5], v[34:35], 0, v[136:137]
	v_pk_fma_f32 v[2:3], v[2:3], v[14:15], v[6:7]
	global_store_dwordx4 v[4:5], v[24:27], off
	global_store_dwordx4 v[4:5], v[16:19], off offset:1024
	global_store_dwordx4 v[4:5], v[8:11], off offset:2048
	global_store_dwordx4 v[4:5], v[0:3], off offset:3072
	s_cbranch_scc0 .LBB0_40

.LBB0_123:
	v_mov_b32_e32 v0, v139
	v_readlane_b32 s40, v247, 57
	v_ashrrev_i32_e32 v1, 5, v0
	v_and_b32_e32 v1, -2, v1
	v_add_u32_e32 v38, s12, v1
	v_lshlrev_b32_e32 v0, 2, v0
	v_ashrrev_i32_e32 v39, 31, v38
	v_and_b32_e32 v2, 0xfc, v0
	v_lshlrev_b64 v[0:1], 12, v[38:39]
	v_readlane_b32 s50, v246, 3
	v_readlane_b32 s51, v246, 4
	v_lshlrev_b32_e32 v136, 1, v2
	s_waitcnt vmcnt(8)
	v_add_u32_e32 v34, 1, v38
	v_lshl_add_u64 v[0:1], s[50:51], 0, v[0:1]
	v_lshl_add_u64 v[36:37], v[0:1], 0, v[136:137]
	global_load_dwordx2 v[42:43], v[36:37], off offset:2048
	global_load_dwordx2 v[44:45], v[36:37], off offset:2560
	global_load_dwordx2 v[46:47], v[36:37], off offset:3072
	global_load_dwordx2 v[48:49], v[36:37], off offset:3584
	v_ashrrev_i32_e32 v35, 31, v34
	v_lshlrev_b64 v[0:1], 12, v[34:35]
	v_lshl_add_u64 v[0:1], s[50:51], 0, v[0:1]
	v_lshl_add_u64 v[32:33], v[0:1], 0, v[136:137]
	global_load_dwordx2 v[50:51], v[32:33], off offset:2048
	global_load_dwordx2 v[52:53], v[32:33], off offset:2560
	global_load_dwordx2 v[54:55], v[32:33], off offset:3072
	global_load_dwordx2 v[56:57], v[32:33], off offset:3584
	v_cmp_lt_i32_e32 vcc, v179, v178
	v_lshlrev_b32_e32 v40, 2, v2
	global_load_dwordx4 v[24:27], v40, s[6:7]
	global_load_dwordx4 v[28:31], v40, s[8:9]
	global_load_dwordx4 v[16:19], v40, s[6:7] offset:1024
	global_load_dwordx4 v[20:23], v40, s[8:9] offset:1024
	global_load_dwordx4 v[8:11], v40, s[6:7] offset:2048
	global_load_dwordx4 v[12:15], v40, s[8:9] offset:2048
	global_load_dwordx4 v[0:3], v40, s[6:7] offset:3072
	global_load_dwordx4 v[4:7], v40, s[8:9] offset:3072
	v_cndmask_b32_e32 v35, v176, v179, vcc
	v_cmp_lt_i32_e32 vcc, v180, v178
	v_lshlrev_b32_e32 v35, 2, v35
	v_mov_b32_e32 v41, v137
	v_cndmask_b32_e32 v39, v176, v180, vcc
	v_cmp_lt_i32_e32 vcc, v181, v178
	v_lshlrev_b32_e32 v39, 2, v39
	s_add_i32 s13, s13, s90
	v_cndmask_b32_e32 v58, v176, v181, vcc
	v_cmp_lt_i32_e32 vcc, v182, v178
	v_lshlrev_b32_e32 v86, 2, v58
	s_add_i32 s12, s12, s5
	v_cndmask_b32_e32 v58, v176, v182, vcc
	v_cmp_lt_i32_e32 vcc, v183, v178
	v_lshlrev_b32_e32 v87, 2, v58
	s_cmpk_gt_i32 s13, 0xbf
	v_cndmask_b32_e32 v58, v176, v183, vcc
	v_cmp_lt_i32_e32 vcc, v184, v178
	v_lshlrev_b32_e32 v88, 2, v58
	v_readlane_b32 s41, v247, 58
	v_cndmask_b32_e32 v58, v176, v184, vcc
	v_lshlrev_b32_e32 v89, 2, v58
	v_readlane_b32 s42, v247, 59
	v_readlane_b32 s43, v247, 60
	v_readlane_b32 s44, v247, 61
	v_readlane_b32 s45, v247, 62
	v_readlane_b32 s46, v247, 63
	v_readlane_b32 s47, v246, 0
	v_readlane_b32 s48, v246, 1
	v_readlane_b32 s49, v246, 2
	v_readlane_b32 s52, v246, 5
	v_readlane_b32 s53, v246, 6
	v_readlane_b32 s54, v246, 7
	v_readlane_b32 s55, v246, 8
	s_waitcnt vmcnt(15)
	v_lshlrev_b32_e32 v68, 16, v42
	s_waitcnt vmcnt(14)
	v_lshlrev_b32_e32 v66, 16, v44
	s_waitcnt vmcnt(13)
	v_lshlrev_b32_e32 v62, 16, v46
	s_waitcnt vmcnt(12)
	v_lshlrev_b32_e32 v60, 16, v48
	v_and_b32_e32 v61, 0xffff0000, v48
	v_and_b32_e32 v63, 0xffff0000, v46
	v_lshlrev_b32_e32 v58, 16, v49
	v_and_b32_e32 v59, 0xffff0000, v49
	v_lshlrev_b32_e32 v48, 16, v47
	v_and_b32_e32 v49, 0xffff0000, v47
	v_mov_b32_e32 v46, v62
	v_mov_b32_e32 v47, v60
	v_mov_b32_e32 v64, v63
	v_mov_b32_e32 v65, v61
	v_pk_add_f32 v[46:47], v[46:47], v[64:65]
	v_mov_b32_e32 v64, v48
	v_mov_b32_e32 v65, v58
	v_pk_add_f32 v[46:47], v[46:47], v[64:65]
	v_mov_b32_e32 v64, v49
	v_mov_b32_e32 v65, v59
	v_and_b32_e32 v67, 0xffff0000, v44
	v_and_b32_e32 v69, 0xffff0000, v42
	v_pk_add_f32 v[46:47], v[46:47], v[64:65]
	v_lshlrev_b32_e32 v64, 16, v45
	v_and_b32_e32 v65, 0xffff0000, v45
	v_lshlrev_b32_e32 v44, 16, v43
	v_and_b32_e32 v45, 0xffff0000, v43
	v_mov_b32_e32 v42, v68
	v_mov_b32_e32 v43, v66
	v_mov_b32_e32 v70, v69
	v_mov_b32_e32 v71, v67
	v_pk_add_f32 v[42:43], v[42:43], v[70:71]
	v_mov_b32_e32 v70, v44
	v_mov_b32_e32 v71, v64
	v_pk_add_f32 v[42:43], v[42:43], v[70:71]
	v_mov_b32_e32 v70, v45
	v_mov_b32_e32 v71, v65
	s_waitcnt vmcnt(8)
	v_lshlrev_b32_e32 v72, 16, v56
	v_and_b32_e32 v73, 0xffff0000, v56
	v_lshlrev_b32_e32 v74, 16, v54
	v_and_b32_e32 v75, 0xffff0000, v54
	v_pk_add_f32 v[42:43], v[42:43], v[70:71]
	v_lshlrev_b32_e32 v70, 16, v57
	v_and_b32_e32 v71, 0xffff0000, v57
	v_lshlrev_b32_e32 v56, 16, v55
	v_and_b32_e32 v57, 0xffff0000, v55
	v_mov_b32_e32 v54, v74
	v_mov_b32_e32 v55, v72
	v_mov_b32_e32 v76, v75
	v_mov_b32_e32 v77, v73
	v_pk_add_f32 v[54:55], v[54:55], v[76:77]
	v_mov_b32_e32 v76, v56
	v_mov_b32_e32 v77, v70
	v_pk_add_f32 v[54:55], v[54:55], v[76:77]
	v_mov_b32_e32 v76, v57
	v_mov_b32_e32 v77, v71
	v_lshlrev_b32_e32 v78, 16, v52
	v_and_b32_e32 v79, 0xffff0000, v52
	v_lshlrev_b32_e32 v80, 16, v50
	v_and_b32_e32 v81, 0xffff0000, v50
	v_pk_add_f32 v[54:55], v[54:55], v[76:77]
	v_lshlrev_b32_e32 v76, 16, v53
	v_and_b32_e32 v77, 0xffff0000, v53
	v_lshlrev_b32_e32 v52, 16, v51
	v_and_b32_e32 v53, 0xffff0000, v51
	v_mov_b32_e32 v50, v80
	v_mov_b32_e32 v51, v78
	v_mov_b32_e32 v82, v81
	v_mov_b32_e32 v83, v79
	v_pk_add_f32 v[50:51], v[50:51], v[82:83]
	v_mov_b32_e32 v82, v52
	v_mov_b32_e32 v83, v76
	v_pk_add_f32 v[50:51], v[50:51], v[82:83]
	v_mov_b32_e32 v82, v53
	v_mov_b32_e32 v83, v77
	v_pk_add_f32 v[50:51], v[50:51], v[82:83]
	v_add_f32_e32 v42, 0, v42
	v_add_f32_e32 v50, 0, v50
	v_add_f32_e32 v42, v42, v43
	v_add_f32_e32 v50, v50, v51
	v_add_f32_e32 v42, v42, v46
	v_add_f32_e32 v50, v50, v54
	v_add_f32_e32 v42, v42, v47
	v_add_f32_e32 v50, v50, v55
	s_nop 1
	v_mov_b32_e32 v254, v42
	v_mov_b32_e32 v43, v42
	v_cmp_gt_u32_e64 s[98:99], 32, v176
	s_nop 0
	v_permlane32_swap_b32_e32 v43, v254
	v_cndmask_b32_e64 v43, v43, v254, s[98:99]
	s_nop 1
	v_mov_b32_e32 v254, v50
	v_mov_b32_e32 v51, v50
	v_cmp_gt_u32_e64 s[98:99], 32, v176
	s_nop 0
	v_permlane32_swap_b32_e32 v51, v254
	v_cndmask_b32_e64 v51, v51, v254, s[98:99]
	s_waitcnt lgkmcnt(1)
	v_add_f32_e32 v42, v42, v43
	s_waitcnt lgkmcnt(0)
	v_add_f32_e32 v50, v50, v51
	s_nop 1
	v_mov_b32_e32 v254, v42
	v_mov_b32_e32 v43, v42
	v_and_b32_e32 v255, 16, v176
	v_cmp_eq_u32_e64 s[98:99], 0, v255
	s_nop 0
	v_permlane16_swap_b32_e32 v43, v254
	v_cndmask_b32_e64 v43, v43, v254, s[98:99]
	s_nop 1
	v_mov_b32_e32 v254, v50
	v_mov_b32_e32 v51, v50
	v_and_b32_e32 v255, 16, v176
	v_cmp_eq_u32_e64 s[98:99], 0, v255
	s_nop 0
	v_permlane16_swap_b32_e32 v51, v254
	v_cndmask_b32_e64 v51, v51, v254, s[98:99]
	s_waitcnt lgkmcnt(1)
	v_add_f32_e32 v42, v42, v43
	s_waitcnt lgkmcnt(0)
	v_add_f32_e32 v50, v50, v51
	s_nop 1
	v_mov_b32_dpp v43, v42 row_ror:8 row_mask:0xf bank_mask:0xf
	s_nop 1
	v_mov_b32_dpp v51, v50 row_ror:8 row_mask:0xf bank_mask:0xf
	s_waitcnt lgkmcnt(1)
	v_add_f32_e32 v42, v42, v43
	s_waitcnt lgkmcnt(0)
	v_add_f32_e32 v50, v50, v51
	s_nop 1
	v_mov_b32_dpp v43, v42 row_shl:4 row_mask:0xf bank_mask:0x5
	v_mov_b32_dpp v43, v42 row_shr:4 row_mask:0xf bank_mask:0xa
	s_nop 1
	v_mov_b32_dpp v51, v50 row_shl:4 row_mask:0xf bank_mask:0x5
	v_mov_b32_dpp v51, v50 row_shr:4 row_mask:0xf bank_mask:0xa
	s_waitcnt lgkmcnt(1)
	v_add_f32_e32 v42, v42, v43
	s_waitcnt lgkmcnt(0)
	v_add_f32_e32 v50, v50, v51
	s_nop 1
	v_mov_b32_dpp v43, v42 quad_perm:[2,3,0,1] row_mask:0xf bank_mask:0xf
	s_nop 1
	v_mov_b32_dpp v51, v50 quad_perm:[2,3,0,1] row_mask:0xf bank_mask:0xf
	s_waitcnt lgkmcnt(1)
	v_add_f32_e32 v42, v42, v43
	s_waitcnt lgkmcnt(0)
	v_add_f32_e32 v50, v50, v51
	s_nop 1
	v_mov_b32_dpp v43, v42 quad_perm:[1,0,3,2] row_mask:0xf bank_mask:0xf
	s_nop 1
	v_mov_b32_dpp v51, v50 quad_perm:[1,0,3,2] row_mask:0xf bank_mask:0xf
	s_waitcnt lgkmcnt(1)
	v_add_f32_e32 v42, v42, v43
	s_waitcnt lgkmcnt(0)
	v_add_f32_e32 v50, v50, v51
	v_mul_f32_e32 v42, 0x3a800000, v42
	v_mul_f32_e32 v50, 0x3a800000, v50
	v_pk_add_f32 v[46:47], v[68:69], v[42:43] op_sel_hi:[1,0] neg_lo:[0,1] neg_hi:[0,1]
	v_pk_add_f32 v[80:81], v[80:81], v[50:51] op_sel_hi:[1,0] neg_lo:[0,1] neg_hi:[0,1]
	v_mov_b32_e32 v83, v47
	v_mov_b32_e32 v82, v81
	v_mov_b32_e32 v54, v80
	v_mov_b32_e32 v55, v46
	v_pk_mul_f32 v[82:83], v[82:83], v[82:83]
	v_pk_add_f32 v[44:45], v[44:45], v[42:43] op_sel_hi:[1,0] neg_lo:[0,1] neg_hi:[0,1]
	v_pk_fma_f32 v[54:55], v[54:55], v[54:55], v[82:83]
	v_pk_add_f32 v[82:83], v[52:53], v[50:51] op_sel_hi:[1,0] neg_lo:[0,1] neg_hi:[0,1]
	v_mov_b32_e32 v53, v44
	v_mov_b32_e32 v52, v82
	v_pk_add_f32 v[66:67], v[66:67], v[42:43] op_sel_hi:[1,0] neg_lo:[0,1] neg_hi:[0,1]
	v_pk_add_f32 v[78:79], v[78:79], v[50:51] op_sel_hi:[1,0] neg_lo:[0,1] neg_hi:[0,1]
	v_pk_fma_f32 v[52:53], v[52:53], v[52:53], v[54:55]
	v_mov_b32_e32 v54, v83
	v_mov_b32_e32 v55, v45
	v_pk_fma_f32 v[52:53], v[54:55], v[54:55], v[52:53]
	v_mov_b32_e32 v54, v78
	v_mov_b32_e32 v55, v66
	v_pk_add_f32 v[64:65], v[64:65], v[42:43] op_sel_hi:[1,0] neg_lo:[0,1] neg_hi:[0,1]
	v_pk_add_f32 v[76:77], v[76:77], v[50:51] op_sel_hi:[1,0] neg_lo:[0,1] neg_hi:[0,1]
	v_pk_fma_f32 v[52:53], v[54:55], v[54:55], v[52:53]
	v_mov_b32_e32 v54, v79
	v_mov_b32_e32 v55, v67
	v_pk_fma_f32 v[52:53], v[54:55], v[54:55], v[52:53]
	v_mov_b32_e32 v54, v76
	v_mov_b32_e32 v55, v64
	v_pk_add_f32 v[62:63], v[62:63], v[42:43] op_sel_hi:[1,0] neg_lo:[0,1] neg_hi:[0,1]
	v_pk_add_f32 v[74:75], v[74:75], v[50:51] op_sel_hi:[1,0] neg_lo:[0,1] neg_hi:[0,1]
	v_pk_fma_f32 v[52:53], v[54:55], v[54:55], v[52:53]
	v_mov_b32_e32 v54, v77
	v_mov_b32_e32 v55, v65
	v_pk_fma_f32 v[52:53], v[54:55], v[54:55], v[52:53]
	v_mov_b32_e32 v54, v74
	v_mov_b32_e32 v55, v62
	v_pk_add_f32 v[68:69], v[48:49], v[42:43] op_sel_hi:[1,0] neg_lo:[0,1] neg_hi:[0,1]
	v_pk_add_f32 v[84:85], v[56:57], v[50:51] op_sel_hi:[1,0] neg_lo:[0,1] neg_hi:[0,1]
	v_pk_fma_f32 v[52:53], v[54:55], v[54:55], v[52:53]
	v_mov_b32_e32 v54, v75
	v_mov_b32_e32 v55, v63
	v_pk_add_f32 v[60:61], v[60:61], v[42:43] op_sel_hi:[1,0] neg_lo:[0,1] neg_hi:[0,1]
	v_pk_add_f32 v[72:73], v[72:73], v[50:51] op_sel_hi:[1,0] neg_lo:[0,1] neg_hi:[0,1]
	v_pk_fma_f32 v[52:53], v[54:55], v[54:55], v[52:53]
	v_mov_b32_e32 v54, v84
	v_mov_b32_e32 v55, v68
	v_pk_mul_f32 v[48:49], v[60:61], v[60:61]
	v_pk_mul_f32 v[56:57], v[72:73], v[72:73]
	v_pk_fma_f32 v[52:53], v[54:55], v[54:55], v[52:53]
	v_mov_b32_e32 v54, v85
	v_mov_b32_e32 v55, v69
	v_pk_add_f32 v[42:43], v[58:59], v[42:43] op_sel_hi:[1,0] neg_lo:[0,1] neg_hi:[0,1]
	v_pk_fma_f32 v[52:53], v[54:55], v[54:55], v[52:53]
	v_mov_b32_e32 v54, v56
	v_mov_b32_e32 v55, v48
	v_pk_add_f32 v[70:71], v[70:71], v[50:51] op_sel_hi:[1,0] neg_lo:[0,1] neg_hi:[0,1]
	v_pk_mul_f32 v[58:59], v[42:43], v[42:43]
	v_pk_add_f32 v[52:53], v[54:55], v[52:53]
	v_pk_mul_f32 v[50:51], v[70:71], v[70:71]
	v_mov_b32_e32 v48, v57
	v_pk_add_f32 v[48:49], v[48:49], v[52:53]
	v_mov_b32_e32 v52, v50
	v_mov_b32_e32 v53, v58
	v_pk_add_f32 v[48:49], v[52:53], v[48:49]
	v_mov_b32_e32 v58, v51
	v_pk_add_f32 v[48:49], v[58:59], v[48:49]
	v_mov_b32_e32 v50, v48
	v_mov_b32_e32 v51, v49
	s_nop 1
	v_permlane32_swap_b32_e32 v50, v48
	v_permlane32_swap_b32_e32 v51, v49
	v_pk_add_f32 v[48:49], v[48:49], v[50:51]
	v_mov_b32_e32 v50, v48
	v_mov_b32_e32 v51, v49
	s_nop 1
	v_permlane16_swap_b32_e32 v50, v48
	v_permlane16_swap_b32_e32 v51, v49
	v_pk_add_f32 v[48:49], v[48:49], v[50:51]
	s_nop 1
	v_add_f32_dpp v48, v48, v48 row_ror:8 row_mask:0xf bank_mask:0xf
	v_add_f32_dpp v49, v49, v49 row_ror:8 row_mask:0xf bank_mask:0xf
	s_nop 0
	v_add_f32_dpp v48, v48, v48 row_ror:4 row_mask:0xf bank_mask:0xf
	v_add_f32_dpp v49, v49, v49 row_ror:4 row_mask:0xf bank_mask:0xf
	s_nop 0
	v_add_f32_dpp v48, v48, v48 row_ror:2 row_mask:0xf bank_mask:0xf
	v_add_f32_dpp v49, v49, v49 row_ror:2 row_mask:0xf bank_mask:0xf
	s_nop 0
	v_add_f32_dpp v48, v48, v48 row_ror:1 row_mask:0xf bank_mask:0xf
	v_add_f32_dpp v49, v49, v49 row_ror:1 row_mask:0xf bank_mask:0xf
	s_nop 0
	v_pk_fma_f32 v[58:59], v[48:49], s[20:21], v[138:139] op_sel_hi:[1,0,0]
	s_nop 0
	v_mul_f32_e32 v35, 0x4b800000, v59
	v_cmp_gt_f32_e64 s[0:1], s33, v59
	v_cmp_gt_f32_e32 vcc, s33, v58
	s_nop 0
	v_cndmask_b32_e64 v35, v59, v35, s[0:1]
	v_rsq_f32_e32 v35, v35
	s_nop 0
	v_mul_f32_e32 v39, 0x45800000, v35
	v_cndmask_b32_e64 v86, v35, v39, s[0:1]
	v_mul_f32_e32 v35, 0x4b800000, v58
	v_cndmask_b32_e32 v35, v58, v35, vcc
	v_rsq_f32_e32 v35, v35
	v_pk_mul_f32 v[44:45], v[44:45], v[86:87] op_sel_hi:[1,0]
	v_pk_mul_f32 v[46:47], v[46:47], v[86:87] op_sel_hi:[1,0]
	s_waitcnt vmcnt(6)
	v_pk_fma_f32 v[54:55], v[26:27], v[44:45], v[30:31]
	v_pk_mul_f32 v[44:45], v[66:67], v[86:87] op_sel_hi:[1,0]
	v_mul_f32_e32 v39, 0x45800000, v35
	s_waitcnt vmcnt(4)
	v_pk_fma_f32 v[52:53], v[16:17], v[44:45], v[20:21]
	v_pk_mul_f32 v[44:45], v[64:65], v[86:87] op_sel_hi:[1,0]
	v_cndmask_b32_e32 v58, v35, v39, vcc
	v_pk_fma_f32 v[50:51], v[18:19], v[44:45], v[22:23]
	v_pk_mul_f32 v[44:45], v[62:63], v[86:87] op_sel_hi:[1,0]
	v_pk_fma_f32 v[56:57], v[24:25], v[46:47], v[28:29]
	s_waitcnt vmcnt(2)
	v_pk_fma_f32 v[48:49], v[8:9], v[44:45], v[12:13]
	v_pk_mul_f32 v[44:45], v[68:69], v[86:87] op_sel_hi:[1,0]
	v_pk_mul_f32 v[42:43], v[42:43], v[86:87] op_sel_hi:[1,0]
	v_pk_fma_f32 v[46:47], v[10:11], v[44:45], v[14:15]
	v_pk_mul_f32 v[44:45], v[60:61], v[86:87] op_sel_hi:[1,0]
	v_pk_mul_f32 v[60:61], v[80:81], v[58:59] op_sel_hi:[1,0]
	s_waitcnt vmcnt(0)
	v_pk_fma_f32 v[44:45], v[0:1], v[44:45], v[4:5]
	v_pk_fma_f32 v[24:25], v[24:25], v[60:61], v[28:29]
	v_pk_mul_f32 v[28:29], v[82:83], v[58:59] op_sel_hi:[1,0]
	v_pk_fma_f32 v[42:43], v[2:3], v[42:43], v[6:7]
	v_pk_fma_f32 v[26:27], v[26:27], v[28:29], v[30:31]
	v_pk_mul_f32 v[28:29], v[78:79], v[58:59] op_sel_hi:[1,0]
	v_cmp_lt_i32_e32 vcc, s16, v38
	v_pk_fma_f32 v[16:17], v[16:17], v[28:29], v[20:21]
	v_pk_mul_f32 v[20:21], v[76:77], v[58:59] op_sel_hi:[1,0]
	s_nop 0
	v_pk_fma_f32 v[18:19], v[18:19], v[20:21], v[22:23]
	v_pk_mul_f32 v[20:21], v[74:75], v[58:59] op_sel_hi:[1,0]
	s_nop 0
	v_pk_fma_f32 v[8:9], v[8:9], v[20:21], v[12:13]
	v_pk_mul_f32 v[12:13], v[84:85], v[58:59] op_sel_hi:[1,0]
	s_nop 0
	v_pk_fma_f32 v[10:11], v[10:11], v[12:13], v[14:15]
	v_pk_mul_f32 v[12:13], v[72:73], v[58:59] op_sel_hi:[1,0]
	s_nop 0
	v_pk_fma_f32 v[0:1], v[0:1], v[12:13], v[4:5]
	v_pk_mul_f32 v[4:5], v[70:71], v[58:59] op_sel_hi:[1,0]
	s_nop 0
	v_pk_fma_f32 v[2:3], v[2:3], v[4:5], v[6:7]
	v_add_u32_e32 v4, 0xfffff000, v38
	v_lshrrev_b32_e32 v4, 12, v4
	v_add_u32_e32 v4, 1, v4
	v_cndmask_b32_e32 v4, 0, v4, vcc
	v_mov_b32_e32 v5, v137
	v_lshl_add_u64 v[4:5], v[4:5], 0, s[10:11]
	v_mov_b64_e32 v[6:7], s[56:57]
	v_mad_u64_u32 v[6:7], s[0:1], v4, s15, v[6:7]
	v_mad_i32_i24 v7, v5, s15, v7
	v_lshl_add_u64 v[4:5], v[6:7], 0, v[40:41]
	v_add_co_u32_e32 v12, vcc, s14, v4
	v_lshl_add_u64 v[70:71], v[4:5], 0, s[24:25]
	s_nop 0
	v_addc_co_u32_e32 v13, vcc, 0, v5, vcc
	v_lshl_add_u64 v[40:41], v[4:5], 0, s[18:19]
	global_load_dwordx4 v[4:7], v[12:13], off offset:-4096
	s_nop 0
	global_load_dwordx4 v[12:15], v[12:13], off
	s_nop 0
	global_load_dwordx4 v[20:23], v[40:41], off offset:1024
	global_load_dwordx4 v[28:31], v[70:71], off offset:1024
	global_load_dwordx4 v[58:61], v[40:41], off offset:2048
	global_load_dwordx4 v[62:65], v[70:71], off offset:2048
	global_load_dwordx4 v[66:69], v[40:41], off offset:3072
	s_nop 0
	global_load_dwordx4 v[70:73], v[70:71], off offset:3072
	v_cvt_pk_bf16_f32 v40, v56, v57
	v_cvt_pk_bf16_f32 v41, v54, v55
	global_store_dwordx2 v[36:37], v[40:41], off
	s_waitcnt vmcnt(7)
	v_pk_add_f32 v[12:13], v[12:13], 1.0 op_sel_hi:[1,0]
	v_pk_add_f32 v[14:15], v[14:15], 1.0 op_sel_hi:[1,0]
	v_pk_fma_f32 v[40:41], v[12:13], v[56:57], v[4:5]
	v_pk_fma_f32 v[54:55], v[14:15], v[54:55], v[6:7]
	v_cvt_pk_bf16_f32 v40, v40, v41
	v_cvt_pk_bf16_f32 v41, v54, v55
	v_mov_b64_e32 v[54:55], s[62:63]
	v_mad_i64_i32 v[38:39], s[0:1], v38, s36, v[54:55]
	v_lshl_add_u64 v[38:39], v[38:39], 0, v[136:137]
	global_store_dwordx2 v[38:39], v[40:41], off
	v_cvt_pk_bf16_f32 v40, v52, v53
	v_cvt_pk_bf16_f32 v41, v50, v51
	s_waitcnt vmcnt(6)
	v_pk_add_f32 v[28:29], v[28:29], 1.0 op_sel_hi:[1,0]
	v_pk_add_f32 v[30:31], v[30:31], 1.0 op_sel_hi:[1,0]
	global_store_dwordx2 v[36:37], v[40:41], off offset:512
	v_pk_fma_f32 v[40:41], v[28:29], v[52:53], v[20:21]
	v_pk_fma_f32 v[50:51], v[30:31], v[50:51], v[22:23]
	v_cvt_pk_bf16_f32 v40, v40, v41
	v_cvt_pk_bf16_f32 v41, v50, v51
	global_store_dwordx2 v[38:39], v[40:41], off offset:512
	v_cvt_pk_bf16_f32 v40, v48, v49
	v_cvt_pk_bf16_f32 v41, v46, v47
	global_store_dwordx2 v[36:37], v[40:41], off offset:1024
	s_waitcnt vmcnt(7)
	v_pk_add_f32 v[40:41], v[62:63], 1.0 op_sel_hi:[1,0]
	v_pk_add_f32 v[50:51], v[64:65], 1.0 op_sel_hi:[1,0]
	v_pk_fma_f32 v[48:49], v[40:41], v[48:49], v[58:59]
	v_pk_fma_f32 v[46:47], v[50:51], v[46:47], v[60:61]
	v_cvt_pk_bf16_f32 v48, v48, v49
	v_cvt_pk_bf16_f32 v49, v46, v47
	v_cvt_pk_bf16_f32 v46, v44, v45
	v_cvt_pk_bf16_f32 v47, v42, v43
	global_store_dwordx2 v[38:39], v[48:49], off offset:1024
	global_store_dwordx2 v[36:37], v[46:47], off offset:1536
	s_waitcnt vmcnt(7)
	v_pk_add_f32 v[36:37], v[70:71], 1.0 op_sel_hi:[1,0]
	v_pk_add_f32 v[46:47], v[72:73], 1.0 op_sel_hi:[1,0]
	v_pk_fma_f32 v[44:45], v[36:37], v[44:45], v[66:67]
	v_pk_fma_f32 v[42:43], v[46:47], v[42:43], v[68:69]
	v_pk_fma_f32 v[4:5], v[12:13], v[24:25], v[4:5]
	v_pk_fma_f32 v[6:7], v[14:15], v[26:27], v[6:7]
	v_cvt_pk_bf16_f32 v44, v44, v45
	v_cvt_pk_bf16_f32 v45, v42, v43
	v_cvt_pk_bf16_f32 v4, v4, v5
	v_cvt_pk_bf16_f32 v5, v6, v7
	v_mad_i64_i32 v[6:7], s[0:1], v34, s36, v[54:55]
	global_store_dwordx2 v[38:39], v[44:45], off offset:1536
	v_cvt_pk_bf16_f32 v38, v24, v25
	v_cvt_pk_bf16_f32 v39, v26, v27
	v_lshl_add_u64 v[6:7], v[6:7], 0, v[136:137]
	global_store_dwordx2 v[32:33], v[38:39], off
	global_store_dwordx2 v[6:7], v[4:5], off
	v_cvt_pk_bf16_f32 v4, v16, v17
	v_cvt_pk_bf16_f32 v5, v18, v19
	global_store_dwordx2 v[32:33], v[4:5], off offset:512
	v_pk_fma_f32 v[4:5], v[28:29], v[16:17], v[20:21]
	v_pk_fma_f32 v[12:13], v[30:31], v[18:19], v[22:23]
	v_cvt_pk_bf16_f32 v4, v4, v5
	v_cvt_pk_bf16_f32 v5, v12, v13
	global_store_dwordx2 v[6:7], v[4:5], off offset:512
	v_cvt_pk_bf16_f32 v4, v8, v9
	v_cvt_pk_bf16_f32 v5, v10, v11
	global_store_dwordx2 v[32:33], v[4:5], off offset:1024
	v_pk_fma_f32 v[4:5], v[40:41], v[8:9], v[58:59]
	v_pk_fma_f32 v[8:9], v[50:51], v[10:11], v[60:61]
	v_cvt_pk_bf16_f32 v4, v4, v5
	v_cvt_pk_bf16_f32 v5, v8, v9
	global_store_dwordx2 v[6:7], v[4:5], off offset:1024
	v_cvt_pk_bf16_f32 v4, v0, v1
	v_cvt_pk_bf16_f32 v5, v2, v3
	v_pk_fma_f32 v[0:1], v[36:37], v[0:1], v[66:67]
	v_pk_fma_f32 v[2:3], v[46:47], v[2:3], v[68:69]
	v_cvt_pk_bf16_f32 v0, v0, v1
	v_cvt_pk_bf16_f32 v1, v2, v3
	global_store_dwordx2 v[32:33], v[4:5], off offset:1536
	global_store_dwordx2 v[6:7], v[0:1], off offset:1536
	s_cbranch_scc0 .LBB0_123

.LBB0_157:
	v_mov_b32_e32 v0, v139
	v_cmp_lt_i32_e32 vcc, v179, v178
	v_ashrrev_i32_e32 v1, 5, v0
	v_and_b32_e32 v1, -2, v1
	v_add_u32_e32 v38, s9, v1
	v_lshlrev_b32_e32 v0, 2, v0
	v_ashrrev_i32_e32 v39, 31, v38
	v_and_b32_e32 v2, 0xfc, v0
	v_lshlrev_b64 v[0:1], 12, v[38:39]
	v_lshl_add_u64 v[0:1], s[46:47], 0, v[0:1]
	v_lshlrev_b32_e32 v136, 1, v2
	v_lshl_add_u64 v[36:37], v[0:1], 0, v[136:137]
	global_load_dwordx2 v[42:43], v[36:37], off offset:2048
	global_load_dwordx2 v[44:45], v[36:37], off offset:2560
	global_load_dwordx2 v[46:47], v[36:37], off offset:3072
	global_load_dwordx2 v[48:49], v[36:37], off offset:3584
	s_waitcnt vmcnt(12)
	v_add_u32_e32 v34, 1, v38
	v_ashrrev_i32_e32 v35, 31, v34
	v_lshlrev_b64 v[0:1], 12, v[34:35]
	v_lshl_add_u64 v[0:1], s[46:47], 0, v[0:1]
	v_lshl_add_u64 v[32:33], v[0:1], 0, v[136:137]
	global_load_dwordx2 v[50:51], v[32:33], off offset:2048
	global_load_dwordx2 v[52:53], v[32:33], off offset:2560
	global_load_dwordx2 v[54:55], v[32:33], off offset:3072
	global_load_dwordx2 v[56:57], v[32:33], off offset:3584
	v_cndmask_b32_e32 v35, v176, v179, vcc
	v_cmp_lt_i32_e32 vcc, v180, v178
	v_lshlrev_b32_e32 v35, 2, v35
	v_lshlrev_b32_e32 v40, 2, v2
	v_cndmask_b32_e32 v39, v176, v180, vcc
	v_cmp_lt_i32_e32 vcc, v181, v178
	v_lshlrev_b32_e32 v39, 2, v39
	global_load_dwordx4 v[24:27], v40, s[4:5]
	global_load_dwordx4 v[28:31], v40, s[6:7]
	global_load_dwordx4 v[16:19], v40, s[4:5] offset:1024
	global_load_dwordx4 v[20:23], v40, s[6:7] offset:1024
	global_load_dwordx4 v[8:11], v40, s[4:5] offset:2048
	global_load_dwordx4 v[12:15], v40, s[6:7] offset:2048
	global_load_dwordx4 v[0:3], v40, s[4:5] offset:3072
	global_load_dwordx4 v[4:7], v40, s[6:7] offset:3072
	v_cndmask_b32_e32 v58, v176, v181, vcc
	v_cmp_lt_i32_e32 vcc, v182, v178
	v_lshlrev_b32_e32 v86, 2, v58
	v_mov_b32_e32 v41, v137
	v_cndmask_b32_e32 v58, v176, v182, vcc
	v_cmp_lt_i32_e32 vcc, v183, v178
	v_lshlrev_b32_e32 v87, 2, v58
	s_add_i32 s10, s10, s20
	v_cndmask_b32_e32 v58, v176, v183, vcc
	v_cmp_lt_i32_e32 vcc, v184, v178
	v_lshlrev_b32_e32 v88, 2, v58
	s_add_i32 s9, s9, s8
	v_cndmask_b32_e32 v58, v176, v184, vcc
	v_lshlrev_b32_e32 v89, 2, v58
	s_cmpk_gt_i32 s10, 0x5ff
	s_waitcnt vmcnt(15)
	v_lshlrev_b32_e32 v68, 16, v42
	s_waitcnt vmcnt(14)
	v_lshlrev_b32_e32 v66, 16, v44
	s_waitcnt vmcnt(13)
	v_lshlrev_b32_e32 v62, 16, v46
	s_waitcnt vmcnt(12)
	v_lshlrev_b32_e32 v60, 16, v48
	v_and_b32_e32 v61, 0xffff0000, v48
	v_and_b32_e32 v63, 0xffff0000, v46
	v_lshlrev_b32_e32 v58, 16, v49
	v_and_b32_e32 v59, 0xffff0000, v49
	v_lshlrev_b32_e32 v48, 16, v47
	v_and_b32_e32 v49, 0xffff0000, v47
	v_mov_b32_e32 v46, v62
	v_mov_b32_e32 v47, v60
	v_mov_b32_e32 v64, v63
	v_mov_b32_e32 v65, v61
	v_pk_add_f32 v[46:47], v[46:47], v[64:65]
	v_mov_b32_e32 v64, v48
	v_mov_b32_e32 v65, v58
	v_pk_add_f32 v[46:47], v[46:47], v[64:65]
	v_mov_b32_e32 v64, v49
	v_mov_b32_e32 v65, v59
	v_and_b32_e32 v67, 0xffff0000, v44
	v_and_b32_e32 v69, 0xffff0000, v42
	v_pk_add_f32 v[46:47], v[46:47], v[64:65]
	v_lshlrev_b32_e32 v64, 16, v45
	v_and_b32_e32 v65, 0xffff0000, v45
	v_lshlrev_b32_e32 v44, 16, v43
	v_and_b32_e32 v45, 0xffff0000, v43
	v_mov_b32_e32 v42, v68
	v_mov_b32_e32 v43, v66
	v_mov_b32_e32 v70, v69
	v_mov_b32_e32 v71, v67
	v_pk_add_f32 v[42:43], v[42:43], v[70:71]
	v_mov_b32_e32 v70, v44
	v_mov_b32_e32 v71, v64
	v_pk_add_f32 v[42:43], v[42:43], v[70:71]
	v_mov_b32_e32 v70, v45
	v_mov_b32_e32 v71, v65
	s_waitcnt vmcnt(8)
	v_lshlrev_b32_e32 v72, 16, v56
	v_and_b32_e32 v73, 0xffff0000, v56
	v_lshlrev_b32_e32 v74, 16, v54
	v_and_b32_e32 v75, 0xffff0000, v54
	v_pk_add_f32 v[42:43], v[42:43], v[70:71]
	v_lshlrev_b32_e32 v70, 16, v57
	v_and_b32_e32 v71, 0xffff0000, v57
	v_lshlrev_b32_e32 v56, 16, v55
	v_and_b32_e32 v57, 0xffff0000, v55
	v_mov_b32_e32 v54, v74
	v_mov_b32_e32 v55, v72
	v_mov_b32_e32 v76, v75
	v_mov_b32_e32 v77, v73
	v_pk_add_f32 v[54:55], v[54:55], v[76:77]
	v_mov_b32_e32 v76, v56
	v_mov_b32_e32 v77, v70
	v_pk_add_f32 v[54:55], v[54:55], v[76:77]
	v_mov_b32_e32 v76, v57
	v_mov_b32_e32 v77, v71
	v_lshlrev_b32_e32 v78, 16, v52
	v_and_b32_e32 v79, 0xffff0000, v52
	v_lshlrev_b32_e32 v80, 16, v50
	v_and_b32_e32 v81, 0xffff0000, v50
	v_pk_add_f32 v[54:55], v[54:55], v[76:77]
	v_lshlrev_b32_e32 v76, 16, v53
	v_and_b32_e32 v77, 0xffff0000, v53
	v_lshlrev_b32_e32 v52, 16, v51
	v_and_b32_e32 v53, 0xffff0000, v51
	v_mov_b32_e32 v50, v80
	v_mov_b32_e32 v51, v78
	v_mov_b32_e32 v82, v81
	v_mov_b32_e32 v83, v79
	v_pk_add_f32 v[50:51], v[50:51], v[82:83]
	v_mov_b32_e32 v82, v52
	v_mov_b32_e32 v83, v76
	v_pk_add_f32 v[50:51], v[50:51], v[82:83]
	v_mov_b32_e32 v82, v53
	v_mov_b32_e32 v83, v77
	v_pk_add_f32 v[50:51], v[50:51], v[82:83]
	v_add_f32_e32 v42, 0, v42
	v_add_f32_e32 v50, 0, v50
	v_add_f32_e32 v42, v42, v43
	v_add_f32_e32 v50, v50, v51
	v_add_f32_e32 v42, v42, v46
	v_add_f32_e32 v50, v50, v54
	v_add_f32_e32 v42, v42, v47
	v_add_f32_e32 v50, v50, v55
	s_nop 1
	v_mov_b32_e32 v254, v42
	v_mov_b32_e32 v43, v42
	v_cmp_gt_u32_e64 s[98:99], 32, v176
	s_nop 0
	v_permlane32_swap_b32_e32 v43, v254
	v_cndmask_b32_e64 v43, v43, v254, s[98:99]
	s_nop 1
	v_mov_b32_e32 v254, v50
	v_mov_b32_e32 v51, v50
	v_cmp_gt_u32_e64 s[98:99], 32, v176
	s_nop 0
	v_permlane32_swap_b32_e32 v51, v254
	v_cndmask_b32_e64 v51, v51, v254, s[98:99]
	s_waitcnt lgkmcnt(1)
	v_add_f32_e32 v42, v42, v43
	s_waitcnt lgkmcnt(0)
	v_add_f32_e32 v50, v50, v51
	s_nop 1
	v_mov_b32_e32 v254, v42
	v_mov_b32_e32 v43, v42
	v_and_b32_e32 v255, 16, v176
	v_cmp_eq_u32_e64 s[98:99], 0, v255
	s_nop 0
	v_permlane16_swap_b32_e32 v43, v254
	v_cndmask_b32_e64 v43, v43, v254, s[98:99]
	s_nop 1
	v_mov_b32_e32 v254, v50
	v_mov_b32_e32 v51, v50
	v_and_b32_e32 v255, 16, v176
	v_cmp_eq_u32_e64 s[98:99], 0, v255
	s_nop 0
	v_permlane16_swap_b32_e32 v51, v254
	v_cndmask_b32_e64 v51, v51, v254, s[98:99]
	s_waitcnt lgkmcnt(1)
	v_add_f32_e32 v42, v42, v43
	s_waitcnt lgkmcnt(0)
	v_add_f32_e32 v50, v50, v51
	s_nop 1
	v_mov_b32_dpp v43, v42 row_ror:8 row_mask:0xf bank_mask:0xf
	s_nop 1
	v_mov_b32_dpp v51, v50 row_ror:8 row_mask:0xf bank_mask:0xf
	s_waitcnt lgkmcnt(1)
	v_add_f32_e32 v42, v42, v43
	s_waitcnt lgkmcnt(0)
	v_add_f32_e32 v50, v50, v51
	s_nop 1
	v_mov_b32_dpp v43, v42 row_shl:4 row_mask:0xf bank_mask:0x5
	v_mov_b32_dpp v43, v42 row_shr:4 row_mask:0xf bank_mask:0xa
	s_nop 1
	v_mov_b32_dpp v51, v50 row_shl:4 row_mask:0xf bank_mask:0x5
	v_mov_b32_dpp v51, v50 row_shr:4 row_mask:0xf bank_mask:0xa
	s_waitcnt lgkmcnt(1)
	v_add_f32_e32 v42, v42, v43
	s_waitcnt lgkmcnt(0)
	v_add_f32_e32 v50, v50, v51
	s_nop 1
	v_mov_b32_dpp v43, v42 quad_perm:[2,3,0,1] row_mask:0xf bank_mask:0xf
	s_nop 1
	v_mov_b32_dpp v51, v50 quad_perm:[2,3,0,1] row_mask:0xf bank_mask:0xf
	s_waitcnt lgkmcnt(1)
	v_add_f32_e32 v42, v42, v43
	s_waitcnt lgkmcnt(0)
	v_add_f32_e32 v50, v50, v51
	s_nop 1
	v_mov_b32_dpp v43, v42 quad_perm:[1,0,3,2] row_mask:0xf bank_mask:0xf
	s_nop 1
	v_mov_b32_dpp v51, v50 quad_perm:[1,0,3,2] row_mask:0xf bank_mask:0xf
	s_waitcnt lgkmcnt(1)
	v_add_f32_e32 v42, v42, v43
	s_waitcnt lgkmcnt(0)
	v_add_f32_e32 v50, v50, v51
	v_mul_f32_e32 v42, 0x3a800000, v42
	v_mul_f32_e32 v50, 0x3a800000, v50
	v_pk_add_f32 v[46:47], v[68:69], v[42:43] op_sel_hi:[1,0] neg_lo:[0,1] neg_hi:[0,1]
	v_pk_add_f32 v[80:81], v[80:81], v[50:51] op_sel_hi:[1,0] neg_lo:[0,1] neg_hi:[0,1]
	v_mov_b32_e32 v83, v47
	v_mov_b32_e32 v82, v81
	v_mov_b32_e32 v54, v80
	v_mov_b32_e32 v55, v46
	v_pk_mul_f32 v[82:83], v[82:83], v[82:83]
	v_pk_add_f32 v[44:45], v[44:45], v[42:43] op_sel_hi:[1,0] neg_lo:[0,1] neg_hi:[0,1]
	v_pk_fma_f32 v[54:55], v[54:55], v[54:55], v[82:83]
	v_pk_add_f32 v[82:83], v[52:53], v[50:51] op_sel_hi:[1,0] neg_lo:[0,1] neg_hi:[0,1]
	v_mov_b32_e32 v53, v44
	v_mov_b32_e32 v52, v82
	v_pk_add_f32 v[66:67], v[66:67], v[42:43] op_sel_hi:[1,0] neg_lo:[0,1] neg_hi:[0,1]
	v_pk_add_f32 v[78:79], v[78:79], v[50:51] op_sel_hi:[1,0] neg_lo:[0,1] neg_hi:[0,1]
	v_pk_fma_f32 v[52:53], v[52:53], v[52:53], v[54:55]
	v_mov_b32_e32 v54, v83
	v_mov_b32_e32 v55, v45
	v_pk_fma_f32 v[52:53], v[54:55], v[54:55], v[52:53]
	v_mov_b32_e32 v54, v78
	v_mov_b32_e32 v55, v66
	v_pk_add_f32 v[64:65], v[64:65], v[42:43] op_sel_hi:[1,0] neg_lo:[0,1] neg_hi:[0,1]
	v_pk_add_f32 v[76:77], v[76:77], v[50:51] op_sel_hi:[1,0] neg_lo:[0,1] neg_hi:[0,1]
	v_pk_fma_f32 v[52:53], v[54:55], v[54:55], v[52:53]
	v_mov_b32_e32 v54, v79
	v_mov_b32_e32 v55, v67
	v_pk_fma_f32 v[52:53], v[54:55], v[54:55], v[52:53]
	v_mov_b32_e32 v54, v76
	v_mov_b32_e32 v55, v64
	v_pk_add_f32 v[62:63], v[62:63], v[42:43] op_sel_hi:[1,0] neg_lo:[0,1] neg_hi:[0,1]
	v_pk_add_f32 v[74:75], v[74:75], v[50:51] op_sel_hi:[1,0] neg_lo:[0,1] neg_hi:[0,1]
	v_pk_fma_f32 v[52:53], v[54:55], v[54:55], v[52:53]
	v_mov_b32_e32 v54, v77
	v_mov_b32_e32 v55, v65
	v_pk_fma_f32 v[52:53], v[54:55], v[54:55], v[52:53]
	v_mov_b32_e32 v54, v74
	v_mov_b32_e32 v55, v62
	v_pk_add_f32 v[68:69], v[48:49], v[42:43] op_sel_hi:[1,0] neg_lo:[0,1] neg_hi:[0,1]
	v_pk_add_f32 v[84:85], v[56:57], v[50:51] op_sel_hi:[1,0] neg_lo:[0,1] neg_hi:[0,1]
	v_pk_fma_f32 v[52:53], v[54:55], v[54:55], v[52:53]
	v_mov_b32_e32 v54, v75
	v_mov_b32_e32 v55, v63
	v_pk_add_f32 v[60:61], v[60:61], v[42:43] op_sel_hi:[1,0] neg_lo:[0,1] neg_hi:[0,1]
	v_pk_add_f32 v[72:73], v[72:73], v[50:51] op_sel_hi:[1,0] neg_lo:[0,1] neg_hi:[0,1]
	v_pk_fma_f32 v[52:53], v[54:55], v[54:55], v[52:53]
	v_mov_b32_e32 v54, v84
	v_mov_b32_e32 v55, v68
	v_pk_mul_f32 v[48:49], v[60:61], v[60:61]
	v_pk_mul_f32 v[56:57], v[72:73], v[72:73]
	v_pk_fma_f32 v[52:53], v[54:55], v[54:55], v[52:53]
	v_mov_b32_e32 v54, v85
	v_mov_b32_e32 v55, v69
	v_pk_add_f32 v[42:43], v[58:59], v[42:43] op_sel_hi:[1,0] neg_lo:[0,1] neg_hi:[0,1]
	v_pk_fma_f32 v[52:53], v[54:55], v[54:55], v[52:53]
	v_mov_b32_e32 v54, v56
	v_mov_b32_e32 v55, v48
	v_pk_add_f32 v[70:71], v[70:71], v[50:51] op_sel_hi:[1,0] neg_lo:[0,1] neg_hi:[0,1]
	v_pk_mul_f32 v[58:59], v[42:43], v[42:43]
	v_pk_add_f32 v[52:53], v[54:55], v[52:53]
	v_pk_mul_f32 v[50:51], v[70:71], v[70:71]
	v_mov_b32_e32 v48, v57
	v_pk_add_f32 v[48:49], v[48:49], v[52:53]
	v_mov_b32_e32 v52, v50
	v_mov_b32_e32 v53, v58
	v_pk_add_f32 v[48:49], v[52:53], v[48:49]
	v_mov_b32_e32 v58, v51
	v_pk_add_f32 v[48:49], v[58:59], v[48:49]
	v_mov_b32_e32 v50, v48
	v_mov_b32_e32 v51, v49
	s_nop 1
	v_permlane32_swap_b32_e32 v50, v48
	v_permlane32_swap_b32_e32 v51, v49
	v_pk_add_f32 v[48:49], v[48:49], v[50:51]
	v_mov_b32_e32 v50, v48
	v_mov_b32_e32 v51, v49
	s_nop 1
	v_permlane16_swap_b32_e32 v50, v48
	v_permlane16_swap_b32_e32 v51, v49
	v_pk_add_f32 v[48:49], v[48:49], v[50:51]
	s_nop 1
	v_add_f32_dpp v48, v48, v48 row_ror:8 row_mask:0xf bank_mask:0xf
	v_add_f32_dpp v49, v49, v49 row_ror:8 row_mask:0xf bank_mask:0xf
	s_nop 0
	v_add_f32_dpp v48, v48, v48 row_ror:4 row_mask:0xf bank_mask:0xf
	v_add_f32_dpp v49, v49, v49 row_ror:4 row_mask:0xf bank_mask:0xf
	s_nop 0
	v_add_f32_dpp v48, v48, v48 row_ror:2 row_mask:0xf bank_mask:0xf
	v_add_f32_dpp v49, v49, v49 row_ror:2 row_mask:0xf bank_mask:0xf
	s_nop 0
	v_add_f32_dpp v48, v48, v48 row_ror:1 row_mask:0xf bank_mask:0xf
	v_add_f32_dpp v49, v49, v49 row_ror:1 row_mask:0xf bank_mask:0xf
	s_nop 0
	v_pk_fma_f32 v[58:59], v[48:49], s[16:17], v[138:139] op_sel_hi:[1,0,0]
	s_nop 0
	v_mul_f32_e32 v35, 0x4b800000, v59
	v_cmp_gt_f32_e64 s[0:1], s33, v59
	v_cmp_gt_f32_e32 vcc, s33, v58
	s_nop 0
	v_cndmask_b32_e64 v35, v59, v35, s[0:1]
	v_rsq_f32_e32 v35, v35
	s_nop 0
	v_mul_f32_e32 v39, 0x45800000, v35
	v_cndmask_b32_e64 v86, v35, v39, s[0:1]
	v_mul_f32_e32 v35, 0x4b800000, v58
	v_cndmask_b32_e32 v35, v58, v35, vcc
	v_rsq_f32_e32 v35, v35
	v_pk_mul_f32 v[44:45], v[44:45], v[86:87] op_sel_hi:[1,0]
	v_pk_mul_f32 v[46:47], v[46:47], v[86:87] op_sel_hi:[1,0]
	s_waitcnt vmcnt(6)
	v_pk_fma_f32 v[54:55], v[26:27], v[44:45], v[30:31]
	v_pk_mul_f32 v[44:45], v[66:67], v[86:87] op_sel_hi:[1,0]
	v_mul_f32_e32 v39, 0x45800000, v35
	s_waitcnt vmcnt(4)
	v_pk_fma_f32 v[52:53], v[16:17], v[44:45], v[20:21]
	v_pk_mul_f32 v[44:45], v[64:65], v[86:87] op_sel_hi:[1,0]
	v_cndmask_b32_e32 v58, v35, v39, vcc
	v_pk_fma_f32 v[50:51], v[18:19], v[44:45], v[22:23]
	v_pk_mul_f32 v[44:45], v[62:63], v[86:87] op_sel_hi:[1,0]
	v_pk_fma_f32 v[56:57], v[24:25], v[46:47], v[28:29]
	s_waitcnt vmcnt(2)
	v_pk_fma_f32 v[48:49], v[8:9], v[44:45], v[12:13]
	v_pk_mul_f32 v[44:45], v[68:69], v[86:87] op_sel_hi:[1,0]
	v_pk_mul_f32 v[42:43], v[42:43], v[86:87] op_sel_hi:[1,0]
	v_pk_fma_f32 v[46:47], v[10:11], v[44:45], v[14:15]
	v_pk_mul_f32 v[44:45], v[60:61], v[86:87] op_sel_hi:[1,0]
	v_pk_mul_f32 v[60:61], v[80:81], v[58:59] op_sel_hi:[1,0]
	s_waitcnt vmcnt(0)
	v_pk_fma_f32 v[44:45], v[0:1], v[44:45], v[4:5]
	v_pk_fma_f32 v[24:25], v[24:25], v[60:61], v[28:29]
	v_pk_mul_f32 v[28:29], v[82:83], v[58:59] op_sel_hi:[1,0]
	v_pk_fma_f32 v[42:43], v[2:3], v[42:43], v[6:7]
	v_pk_fma_f32 v[26:27], v[26:27], v[28:29], v[30:31]
	v_pk_mul_f32 v[28:29], v[78:79], v[58:59] op_sel_hi:[1,0]
	v_cmp_lt_i32_e32 vcc, s13, v38
	v_pk_fma_f32 v[16:17], v[16:17], v[28:29], v[20:21]
	v_pk_mul_f32 v[20:21], v[76:77], v[58:59] op_sel_hi:[1,0]
	s_nop 0
	v_pk_fma_f32 v[18:19], v[18:19], v[20:21], v[22:23]
	v_pk_mul_f32 v[20:21], v[74:75], v[58:59] op_sel_hi:[1,0]
	s_nop 0
	v_pk_fma_f32 v[8:9], v[8:9], v[20:21], v[12:13]
	v_pk_mul_f32 v[12:13], v[84:85], v[58:59] op_sel_hi:[1,0]
	s_nop 0
	v_pk_fma_f32 v[10:11], v[10:11], v[12:13], v[14:15]
	v_pk_mul_f32 v[12:13], v[72:73], v[58:59] op_sel_hi:[1,0]
	s_nop 0
	v_pk_fma_f32 v[0:1], v[0:1], v[12:13], v[4:5]
	v_pk_mul_f32 v[4:5], v[70:71], v[58:59] op_sel_hi:[1,0]
	s_nop 0
	v_pk_fma_f32 v[2:3], v[2:3], v[4:5], v[6:7]
	v_add_u32_e32 v4, 0xfffff000, v38
	v_lshrrev_b32_e32 v4, 12, v4
	v_add_u32_e32 v4, 1, v4
	v_cndmask_b32_e32 v4, 0, v4, vcc
	v_mov_b32_e32 v5, v137
	v_lshl_add_u64 v[4:5], v[4:5], 0, s[2:3]
	v_mov_b64_e32 v[6:7], s[56:57]
	v_mad_u64_u32 v[6:7], s[0:1], v4, s12, v[6:7]
	v_mad_i32_i24 v7, v5, s12, v7
	v_lshl_add_u64 v[4:5], v[6:7], 0, v[40:41]
	v_add_co_u32_e32 v12, vcc, s11, v4
	v_lshl_add_u64 v[70:71], v[4:5], 0, s[18:19]
	s_nop 0
	v_addc_co_u32_e32 v13, vcc, 0, v5, vcc
	v_lshl_add_u64 v[40:41], v[4:5], 0, s[14:15]
	global_load_dwordx4 v[4:7], v[12:13], off offset:-4096
	s_nop 0
	global_load_dwordx4 v[12:15], v[12:13], off
	s_nop 0
	global_load_dwordx4 v[20:23], v[40:41], off offset:1024
	global_load_dwordx4 v[28:31], v[70:71], off offset:1024
	global_load_dwordx4 v[58:61], v[40:41], off offset:2048
	global_load_dwordx4 v[62:65], v[70:71], off offset:2048
	global_load_dwordx4 v[66:69], v[40:41], off offset:3072
	s_nop 0
	global_load_dwordx4 v[70:73], v[70:71], off offset:3072
	v_cvt_pk_bf16_f32 v40, v56, v57
	v_cvt_pk_bf16_f32 v41, v54, v55
	global_store_dwordx2 v[36:37], v[40:41], off
	s_waitcnt vmcnt(7)
	v_pk_add_f32 v[12:13], v[12:13], 1.0 op_sel_hi:[1,0]
	v_pk_add_f32 v[14:15], v[14:15], 1.0 op_sel_hi:[1,0]
	v_pk_fma_f32 v[40:41], v[12:13], v[56:57], v[4:5]
	v_pk_fma_f32 v[54:55], v[14:15], v[54:55], v[6:7]
	v_cvt_pk_bf16_f32 v40, v40, v41
	v_cvt_pk_bf16_f32 v41, v54, v55
	v_mov_b64_e32 v[54:55], s[62:63]
	v_mad_i64_i32 v[38:39], s[0:1], v38, s36, v[54:55]
	v_lshl_add_u64 v[38:39], v[38:39], 0, v[136:137]
	global_store_dwordx2 v[38:39], v[40:41], off
	v_cvt_pk_bf16_f32 v40, v52, v53
	v_cvt_pk_bf16_f32 v41, v50, v51
	s_waitcnt vmcnt(6)
	v_pk_add_f32 v[28:29], v[28:29], 1.0 op_sel_hi:[1,0]
	v_pk_add_f32 v[30:31], v[30:31], 1.0 op_sel_hi:[1,0]
	global_store_dwordx2 v[36:37], v[40:41], off offset:512
	v_pk_fma_f32 v[40:41], v[28:29], v[52:53], v[20:21]
	v_pk_fma_f32 v[50:51], v[30:31], v[50:51], v[22:23]
	v_cvt_pk_bf16_f32 v40, v40, v41
	v_cvt_pk_bf16_f32 v41, v50, v51
	global_store_dwordx2 v[38:39], v[40:41], off offset:512
	v_cvt_pk_bf16_f32 v40, v48, v49
	v_cvt_pk_bf16_f32 v41, v46, v47
	global_store_dwordx2 v[36:37], v[40:41], off offset:1024
	s_waitcnt vmcnt(7)
	v_pk_add_f32 v[40:41], v[62:63], 1.0 op_sel_hi:[1,0]
	v_pk_add_f32 v[50:51], v[64:65], 1.0 op_sel_hi:[1,0]
	v_pk_fma_f32 v[48:49], v[40:41], v[48:49], v[58:59]
	v_pk_fma_f32 v[46:47], v[50:51], v[46:47], v[60:61]
	v_cvt_pk_bf16_f32 v48, v48, v49
	v_cvt_pk_bf16_f32 v49, v46, v47
	v_cvt_pk_bf16_f32 v46, v44, v45
	v_cvt_pk_bf16_f32 v47, v42, v43
	global_store_dwordx2 v[38:39], v[48:49], off offset:1024
	global_store_dwordx2 v[36:37], v[46:47], off offset:1536
	s_waitcnt vmcnt(7)
	v_pk_add_f32 v[36:37], v[70:71], 1.0 op_sel_hi:[1,0]
	v_pk_add_f32 v[46:47], v[72:73], 1.0 op_sel_hi:[1,0]
	v_pk_fma_f32 v[44:45], v[36:37], v[44:45], v[66:67]
	v_pk_fma_f32 v[42:43], v[46:47], v[42:43], v[68:69]
	v_pk_fma_f32 v[4:5], v[12:13], v[24:25], v[4:5]
	v_pk_fma_f32 v[6:7], v[14:15], v[26:27], v[6:7]
	v_cvt_pk_bf16_f32 v44, v44, v45
	v_cvt_pk_bf16_f32 v45, v42, v43
	v_cvt_pk_bf16_f32 v4, v4, v5
	v_cvt_pk_bf16_f32 v5, v6, v7
	v_mad_i64_i32 v[6:7], s[0:1], v34, s36, v[54:55]
	global_store_dwordx2 v[38:39], v[44:45], off offset:1536
	v_cvt_pk_bf16_f32 v38, v24, v25
	v_cvt_pk_bf16_f32 v39, v26, v27
	v_lshl_add_u64 v[6:7], v[6:7], 0, v[136:137]
	global_store_dwordx2 v[32:33], v[38:39], off
	global_store_dwordx2 v[6:7], v[4:5], off
	v_cvt_pk_bf16_f32 v4, v16, v17
	v_cvt_pk_bf16_f32 v5, v18, v19
	global_store_dwordx2 v[32:33], v[4:5], off offset:512
	v_pk_fma_f32 v[4:5], v[28:29], v[16:17], v[20:21]
	v_pk_fma_f32 v[12:13], v[30:31], v[18:19], v[22:23]
	v_cvt_pk_bf16_f32 v4, v4, v5
	v_cvt_pk_bf16_f32 v5, v12, v13
	global_store_dwordx2 v[6:7], v[4:5], off offset:512
	v_cvt_pk_bf16_f32 v4, v8, v9
	v_cvt_pk_bf16_f32 v5, v10, v11
	global_store_dwordx2 v[32:33], v[4:5], off offset:1024
	v_pk_fma_f32 v[4:5], v[40:41], v[8:9], v[58:59]
	v_pk_fma_f32 v[8:9], v[50:51], v[10:11], v[60:61]
	v_cvt_pk_bf16_f32 v4, v4, v5
	v_cvt_pk_bf16_f32 v5, v8, v9
	global_store_dwordx2 v[6:7], v[4:5], off offset:1024
	v_cvt_pk_bf16_f32 v4, v0, v1
	v_cvt_pk_bf16_f32 v5, v2, v3
	v_pk_fma_f32 v[0:1], v[36:37], v[0:1], v[66:67]
	v_pk_fma_f32 v[2:3], v[46:47], v[2:3], v[68:69]
	v_cvt_pk_bf16_f32 v0, v0, v1
	v_cvt_pk_bf16_f32 v1, v2, v3
	global_store_dwordx2 v[32:33], v[4:5], off offset:1536
	global_store_dwordx2 v[6:7], v[0:1], off offset:1536
	s_cbranch_scc0 .LBB0_157

.LBB0_689:
	s_cmpk_gt_i32 s94, 0x17f
	s_mov_b64 s[0:1], -1
	s_cbranch_scc0 .LBB0_968
	s_cmpk_gt_u32 s94, 0x2ff
	s_cbranch_scc0 .LBB0_837
	s_cmpk_gt_u32 s94, 0x47f
	s_cbranch_scc0 .LBB0_797
	v_mov_b32_e32 v5, v139
	v_readlane_b32 s0, v243, 36
	s_waitcnt vmcnt(8)
	v_and_b32_e32 v12, 63, v5
	v_lshlrev_b32_e32 v0, 4, v12
	v_readlane_b32 s1, v243, 37
	v_lshlrev_b32_e32 v4, 1, v12
	v_ashrrev_i32_e32 v8, 6, v5
	v_lshlrev_b32_e32 v136, 2, v12
	v_and_b32_e32 v13, 31, v5
	v_lshlrev_b32_e32 v30, 3, v12
	s_waitcnt lgkmcnt(0)
	global_load_dwordx4 v[0:3], v0, s[0:1]
	v_readlane_b32 s0, v243, 34
	v_mov_b32_e32 v31, v137
	v_lshlrev_b32_e32 v16, 1, v13
	v_or_b32_e32 v6, s0, v4
	v_readlane_b32 s0, v247, 25
	s_lshl_b32 s0, s94, 5
	v_ashrrev_i32_e32 v7, 31, v6
	v_readlane_b32 s1, v247, 26
	v_readlane_b32 s2, v247, 27
	v_readlane_b32 s3, v247, 28
	v_readlane_b32 s4, v247, 29
	v_readlane_b32 s5, v247, 30
	v_readlane_b32 s6, v247, 31
	v_readlane_b32 s7, v247, 32
	v_readlane_b32 s8, v247, 33
	v_readlane_b32 s9, v247, 34
	v_readlane_b32 s10, v247, 35
	v_readlane_b32 s11, v247, 36
	v_readlane_b32 s12, v247, 37
	v_readlane_b32 s13, v247, 38
	v_readlane_b32 s14, v247, 39
	v_readlane_b32 s15, v247, 40
	s_add_i32 s0, s0, 0xffff7000
	v_lshl_add_u64 v[6:7], v[6:7], 2, s[8:9]
	v_add_u32_e32 v8, s0, v8
	v_readlane_b32 s0, v246, 25
	v_readlane_b32 s1, v246, 26
	v_readlane_b32 s3, v246, 28
	s_movk_i32 s3, 0x1a00
	s_waitcnt vmcnt(3)
	v_mov_b64_e32 v[20:21], s[0:1]
	v_readlane_b32 s2, v246, 27
	v_mad_i64_i32 v[18:19], s[0:1], v8, s3, v[20:21]
	v_lshl_add_u64 v[14:15], v[18:19], 0, v[136:137]
	s_movk_i32 s2, 0x1000
	v_add_co_u32_e32 v14, vcc, s2, v14
	v_mov_b32_e32 v17, v137
	v_lshl_add_u64 v[10:11], v[18:19], 0, v[30:31]
	v_addc_co_u32_e32 v15, vcc, 0, v15, vcc
	v_lshl_add_u64 v[18:19], v[18:19], 0, v[16:17]
	v_add_co_u32_e32 v18, vcc, s2, v18
	v_add_u32_e32 v26, 4, v8
	s_nop 0
	v_addc_co_u32_e32 v19, vcc, 0, v19, vcc
	global_load_dwordx2 v[10:11], v[10:11], off offset:3616
	v_ashrrev_i32_e32 v9, 31, v8
	global_load_dword v14, v[14:15], off offset:32
	s_movk_i32 s20, 0x1000
	global_load_ushort v13, v[18:19], off offset:288
	v_mad_i64_i32 v[18:19], s[0:1], v26, s3, v[20:21]
	v_lshl_add_u64 v[22:23], v[18:19], 0, v[30:31]
	global_load_dwordx2 v[28:29], v[22:23], off offset:3616
	v_lshl_add_u64 v[22:23], v[18:19], 0, v[136:137]
	v_add_co_u32_e32 v22, vcc, s2, v22
	v_lshl_add_u64 v[18:19], v[18:19], 0, v[16:17]
	s_nop 0
	v_addc_co_u32_e32 v23, vcc, 0, v23, vcc
	v_add_co_u32_e32 v18, vcc, s2, v18
	global_load_dword v46, v[22:23], off offset:32
	s_nop 0
	v_addc_co_u32_e32 v19, vcc, 0, v19, vcc
	v_add_u32_e32 v22, 8, v8
	global_load_ushort v23, v[18:19], off offset:288
	v_mad_i64_i32 v[18:19], s[0:1], v22, s3, v[20:21]
	v_lshl_add_u64 v[32:33], v[18:19], 0, v[136:137]
	v_add_co_u32_e32 v32, vcc, s2, v32
	v_lshl_add_u64 v[24:25], v[18:19], 0, v[30:31]
	s_nop 0
	v_addc_co_u32_e32 v33, vcc, 0, v33, vcc
	v_lshl_add_u64 v[18:19], v[18:19], 0, v[16:17]
	v_add_co_u32_e32 v18, vcc, s2, v18
	global_load_dwordx2 v[24:25], v[24:25], off offset:3616
	s_nop 0
	v_addc_co_u32_e32 v19, vcc, 0, v19, vcc
	global_load_dword v45, v[32:33], off offset:32
	v_readlane_b32 s4, v246, 29
	global_load_ushort v19, v[18:19], off offset:288
	v_add_u32_e32 v18, 12, v8
	v_mad_i64_i32 v[32:33], s[0:1], v18, s3, v[20:21]
	v_lshl_add_u64 v[20:21], v[32:33], 0, v[30:31]
	v_lshl_add_u64 v[30:31], v[32:33], 0, v[136:137]
	v_add_co_u32_e32 v30, vcc, 0x1000, v30
	global_load_dwordx2 v[20:21], v[20:21], off offset:3616
	s_nop 0
	v_addc_co_u32_e32 v31, vcc, 0, v31, vcc
	global_load_dword v44, v[30:31], off offset:32
	v_lshl_add_u64 v[30:31], v[32:33], 0, v[16:17]
	v_add_co_u32_e32 v30, vcc, 0x1000, v30
	global_load_dwordx2 v[6:7], v[6:7], off
	s_nop 0
	v_addc_co_u32_e32 v31, vcc, 0, v31, vcc
	global_load_ushort v17, v[30:31], off offset:288
	s_movk_i32 s0, 0xfff
	v_cmp_lt_i32_e32 vcc, s0, v8
	v_readlane_b32 s5, v246, 30
	v_readlane_b32 s6, v246, 31
	v_readlane_b32 s7, v246, 32
	v_readlane_b32 s8, v246, 33
	v_readlane_b32 s9, v246, 34
	v_readlane_b32 s10, v246, 35
	v_readlane_b32 s11, v246, 36
	v_readlane_b32 s12, v246, 37
	v_readlane_b32 s13, v246, 38
	v_readlane_b32 s14, v246, 39
	v_readlane_b32 s15, v246, 40
	s_and_saveexec_b64 s[0:1], vcc
	s_xor_b64 s[0:1], exec, s[0:1]
	v_add_u32_e32 v9, 0xfffff000, v8
	v_lshrrev_b32_e32 v9, 12, v9
	v_add_u32_e32 v33, 16, v9
	v_and_b32_e32 v27, 0xfff, v8
	v_mul_u32_u24_e32 v9, 0x1100, v9
	v_add3_u32 v30, v9, v27, s20
	v_mov_b32_e32 v31, v137
	s_andn2_saveexec_b64 s[0:1], s[0:1]
	v_ashrrev_i32_e32 v33, 8, v8
	v_and_b32_e32 v27, 0xff, v8
	v_mov_b64_e32 v[30:31], v[8:9]
	s_or_b64 exec, exec, s[0:1]
	s_waitcnt vmcnt(12)
	v_lshlrev_b32_e32 v34, 16, v10
	v_and_b32_e32 v35, 0xffff0000, v10
	v_lshlrev_b32_e32 v36, 16, v11
	v_and_b32_e32 v11, 0xffff0000, v11
	v_and_b32_e32 v10, s0, v10
	v_mov_b32_e32 v37, v11
	v_pk_mul_f32 v[10:11], v[10:11], v[10:11]
	s_waitcnt vmcnt(11)
	v_lshlrev_b32_e32 v48, 16, v14
	v_mul_f32_e32 v10, v35, v35
	v_pk_fma_f32 v[40:41], v[34:35], v[34:35], v[10:11] op_sel_hi:[1,1,0]
	v_and_b32_e32 v49, 0xffff0000, v14
	v_cmp_lt_i32_e32 vcc, v179, v178
	v_pk_fma_f32 v[40:41], v[36:37], v[36:37], v[40:41]
	v_pk_mul_f32 v[14:15], v[48:49], v[48:49]
	v_cndmask_b32_e32 v9, v176, v179, vcc
	v_mov_b32_e32 v10, v14
	v_pk_mov_b32 v[14:15], v[14:15], v[40:41] op_sel:[1,0]
	v_lshlrev_b32_e32 v38, 2, v9
	v_pk_add_f32 v[10:11], v[10:11], v[14:15]
	s_nop 1
	v_mov_b32_e32 v254, v11
	v_mov_b32_e32 v15, v11
	v_cmp_gt_u32_e64 s[98:99], 32, v176
	s_nop 0
	v_permlane32_swap_b32_e32 v15, v254
	v_cndmask_b32_e64 v15, v15, v254, s[98:99]
	s_nop 1
	v_mov_b32_e32 v254, v10
	v_mov_b32_e32 v14, v10
	v_cmp_gt_u32_e64 s[98:99], 32, v176
	s_nop 0
	v_permlane32_swap_b32_e32 v14, v254
	v_cndmask_b32_e64 v14, v14, v254, s[98:99]
	v_cmp_lt_i32_e32 vcc, v180, v178
	v_readlane_b32 s0, v246, 25
	v_cmp_gt_u32_e64 s[38:39], 32, v12
	v_cndmask_b32_e32 v9, v176, v180, vcc
	v_lshlrev_b32_e32 v40, 2, v9
	s_waitcnt lgkmcnt(0)
	v_pk_add_f32 v[10:11], v[10:11], v[14:15]
	s_nop 1
	v_mov_b32_e32 v254, v11
	v_mov_b32_e32 v15, v11
	v_and_b32_e32 v255, 16, v176
	v_cmp_eq_u32_e64 s[98:99], 0, v255
	s_nop 0
	v_permlane16_swap_b32_e32 v15, v254
	v_cndmask_b32_e64 v15, v15, v254, s[98:99]
	s_nop 1
	v_mov_b32_e32 v254, v10
	v_mov_b32_e32 v14, v10
	v_and_b32_e32 v255, 16, v176
	v_cmp_eq_u32_e64 s[98:99], 0, v255
	s_nop 0
	v_permlane16_swap_b32_e32 v14, v254
	v_cndmask_b32_e64 v14, v14, v254, s[98:99]
	v_cmp_lt_i32_e32 vcc, v181, v178
	v_and_b32_e32 v12, 16, v5
	v_readlane_b32 s10, v246, 35
	v_cndmask_b32_e32 v9, v176, v181, vcc
	v_lshlrev_b32_e32 v9, 2, v9
	s_waitcnt lgkmcnt(0)
	v_pk_add_f32 v[10:11], v[10:11], v[14:15]
	s_nop 1
	v_mov_b32_dpp v15, v11 row_ror:8 row_mask:0xf bank_mask:0xf
	s_nop 1
	v_mov_b32_dpp v14, v10 row_ror:8 row_mask:0xf bank_mask:0xf
	v_cmp_lt_i32_e32 vcc, v182, v178
	v_readlane_b32 s11, v246, 36
	v_cmp_eq_u32_e64 s[42:43], 0, v12
	v_cndmask_b32_e32 v32, v176, v182, vcc
	v_lshlrev_b32_e32 v43, 2, v32
	s_waitcnt lgkmcnt(0)
	v_pk_add_f32 v[10:11], v[10:11], v[14:15]
	s_nop 1
	v_mov_b32_dpp v15, v11 row_shl:4 row_mask:0xf bank_mask:0x5
	v_mov_b32_dpp v15, v11 row_shr:4 row_mask:0xf bank_mask:0xa
	s_nop 1
	v_mov_b32_dpp v14, v10 row_shl:4 row_mask:0xf bank_mask:0x5
	v_mov_b32_dpp v14, v10 row_shr:4 row_mask:0xf bank_mask:0xa
	v_cmp_lt_i32_e32 vcc, v183, v178
	v_readlane_b32 s1, v246, 26
	s_movk_i32 s0, 0x280
	v_cndmask_b32_e32 v32, v176, v183, vcc
	v_lshlrev_b32_e32 v42, 2, v32
	s_waitcnt lgkmcnt(0)
	v_pk_add_f32 v[10:11], v[10:11], v[14:15]
	s_nop 1
	v_mov_b32_dpp v15, v11 quad_perm:[2,3,0,1] row_mask:0xf bank_mask:0xf
	s_nop 1
	v_mov_b32_dpp v14, v10 quad_perm:[2,3,0,1] row_mask:0xf bank_mask:0xf
	v_cmp_lt_i32_e32 vcc, v184, v178
	v_and_b32_e32 v39, 7, v5
	v_and_b32_e32 v5, 8, v5
	v_cndmask_b32_e32 v32, v176, v184, vcc
	v_lshlrev_b32_e32 v41, 2, v32
	s_waitcnt lgkmcnt(0)
	v_pk_add_f32 v[10:11], v[10:11], v[14:15]
	s_nop 1
	v_mov_b32_dpp v15, v11 quad_perm:[1,0,3,2] row_mask:0xf bank_mask:0xf
	s_nop 1
	v_mov_b32_dpp v14, v10 quad_perm:[1,0,3,2] row_mask:0xf bank_mask:0xf
	s_waitcnt vmcnt(10)
	v_lshlrev_b32_e32 v32, 16, v13
	v_mov_b64_e32 v[12:13], s[10:11]
	v_mad_i64_i32 v[12:13], s[0:1], v8, s0, v[12:13]
	s_brev_b32 s0, 60
	s_waitcnt lgkmcnt(0)
	v_pk_add_f32 v[10:11], v[10:11], v[14:15]
	s_mov_b32 s1, 0x3b800000
	v_pk_fma_f32 v[10:11], v[10:11], s[0:1], v[138:139] op_sel_hi:[1,1,0]
	v_cmp_eq_u32_e64 s[40:41], 0, v5
	v_mul_f32_e32 v5, 0x4b800000, v11
	v_cmp_gt_f32_e32 vcc, s33, v11
	v_lshlrev_b32_e32 v14, 1, v136
	v_mov_b32_e32 v15, v137
	v_cndmask_b32_e32 v5, v11, v5, vcc
	v_rsq_f32_e32 v5, v5
	v_readlane_b32 s14, v246, 39
	v_readlane_b32 s15, v246, 40
	v_lshl_add_u64 v[12:13], v[12:13], 0, v[14:15]
	v_mul_f32_e32 v11, 0x45800000, v5
	v_cndmask_b32_e32 v50, v5, v11, vcc
	v_mul_f32_e32 v5, 0x4b800000, v10
	v_cmp_gt_f32_e32 vcc, s33, v10
	v_pk_mul_f32 v[34:35], v[50:51], v[34:35] op_sel_hi:[0,1]
	v_pk_mul_f32 v[36:37], v[50:51], v[36:37] op_sel_hi:[0,1]
	v_cndmask_b32_e32 v5, v10, v5, vcc
	v_rsq_f32_e32 v5, v5
	v_pk_mul_f32 v[34:35], v[0:1], v[34:35]
	v_pk_mul_f32 v[10:11], v[2:3], v[36:37]
	v_cvt_pk_bf16_f32 v34, v34, v35
	v_cvt_pk_bf16_f32 v35, v10, v11
	v_mul_f32_e32 v10, 0x45800000, v5
	v_cndmask_b32_e32 v10, v5, v10, vcc
	v_pk_mul_f32 v[10:11], v[10:11], v[48:49] op_sel_hi:[0,1]
	global_store_dwordx2 v[12:13], v[34:35], off
	s_waitcnt vmcnt(2)
	v_pk_mul_f32 v[34:35], v[6:7], v[10:11]
	v_mov_b64_e32 v[10:11], s[14:15]
	v_mad_u64_u32 v[10:11], s[0:1], v30, s30, v[10:11]
	ds_bpermute_b32 v5, v9, v32
	v_mov_b32_e32 v12, v11
	v_mad_u64_u32 v[12:13], s[0:1], v31, s30, v[12:13]
	v_mov_b32_e32 v11, v12
	v_lshlrev_b32_e32 v12, 1, v4
	v_mov_b32_e32 v13, v137
	v_readlane_b32 s2, v246, 27
	v_readlane_b32 s3, v246, 28
	v_cvt_pk_bf16_f32 v15, v34, v35
	v_lshl_add_u64 v[10:11], v[10:11], 0, v[12:13]
	v_cmp_lt_i32_e32 vcc, 15, v33
	s_mov_b64 s[0:1], 0
	v_lshlrev_b32_e32 v39, 2, v39
	v_readlane_b32 s4, v246, 29
	v_readlane_b32 s5, v246, 30
	v_readlane_b32 s6, v246, 31
	v_readlane_b32 s7, v246, 32
	v_readlane_b32 s8, v246, 33
	v_readlane_b32 s9, v246, 34
	v_readlane_b32 s12, v246, 37
	v_readlane_b32 s13, v246, 38
	global_store_dword v[10:11], v15, off
	s_and_saveexec_b64 s[2:3], vcc
	s_xor_b64 s[2:3], exec, s[2:3]
	s_cbranch_execz .LBB0_699
	v_lshrrev_b32_e32 v10, 6, v27
	v_and_b32_e32 v11, 63, v27
	v_cndmask_b32_e64 v10, v11, v10, s[42:43]
	v_readlane_b32 s4, v246, 9
	v_lshl_or_b32 v11, v10, 5, v39
	v_readlane_b32 s14, v246, 19
	v_readlane_b32 s15, v246, 20
	v_readlane_b32 s16, v246, 21
	v_readlane_b32 s17, v246, 22
	s_nop 2
	global_load_dword v10, v11, s[14:15]
	s_nop 0
	global_load_dword v33, v11, s[16:17]
	s_waitcnt lgkmcnt(0)
	v_cndmask_b32_e64 v11, v5, -v5, s[40:41]
	s_mov_b64 s[0:1], exec
	v_readlane_b32 s5, v246, 10
	v_readlane_b32 s6, v246, 11
	v_readlane_b32 s7, v246, 12
	v_readlane_b32 s8, v246, 13
	v_readlane_b32 s9, v246, 14
	v_readlane_b32 s10, v246, 15
	v_readlane_b32 s11, v246, 16
	v_readlane_b32 s12, v246, 17
	v_readlane_b32 s13, v246, 18
	v_readlane_b32 s18, v246, 23
	v_readlane_b32 s19, v246, 24
	s_waitcnt vmcnt(0)
	v_pk_mul_f32 v[10:11], v[10:11], v[32:33]
	s_nop 0
	v_add_f32_e32 v32, v10, v11
	s_or_saveexec_b64 s[2:3], s[2:3]
	v_lshlrev_b32_e32 v10, 2, v4
	s_xor_b64 exec, exec, s[2:3]
	s_cbranch_execnz .LBB0_700

.LBB0_783:
	s_or_b64 exec, exec, s[2:3]
	s_movk_i32 s0, 0xfe3
	v_ashrrev_i32_e32 v19, 31, v18
	v_cmp_lt_i32_e32 vcc, s0, v8
	s_and_saveexec_b64 s[0:1], vcc
	s_xor_b64 s[0:1], exec, s[0:1]
	v_add_u32_e32 v5, 0xfffff01c, v8
	v_lshrrev_b32_e32 v8, 12, v5
	v_add_u32_e32 v11, 16, v8
	v_and_b32_e32 v5, 0xfff, v18
	v_mul_u32_u24_e32 v8, 0x1100, v8
	s_movk_i32 s2, 0x1000
	v_add3_u32 v16, v8, v5, s2
	v_mov_b32_e32 v17, v137
	s_andn2_saveexec_b64 s[0:1], s[0:1]
	v_ashrrev_i32_e32 v11, 8, v18
	v_and_b32_e32 v5, 0xff, v18
	v_mov_b64_e32 v[16:17], v[18:19]
	s_or_b64 exec, exec, s[0:1]
	s_waitcnt vmcnt(8)
	v_lshlrev_b32_e32 v22, 16, v20
	v_and_b32_e32 v23, 0xffff0000, v20
	v_and_b32_e32 v20, s0, v20
	v_readlane_b32 s0, v246, 25
	v_lshlrev_b32_e32 v24, 16, v21
	v_and_b32_e32 v21, 0xffff0000, v21
	v_readlane_b32 s10, v246, 35
	v_readlane_b32 s11, v246, 36
	v_mov_b32_e32 v25, v21
	v_pk_mul_f32 v[20:21], v[20:21], v[20:21]
	v_readlane_b32 s1, v246, 26
	v_mov_b64_e32 v[28:29], s[10:11]
	s_movk_i32 s0, 0x280
	v_mul_f32_e32 v20, v23, v23
	v_mad_i64_i32 v[18:19], s[0:1], v18, s0, v[28:29]
	s_waitcnt lgkmcnt(0)
	v_mov_b32_e32 v15, v137
	v_pk_fma_f32 v[26:27], v[22:23], v[22:23], v[20:21] op_sel_hi:[1,1,0]
	v_lshl_add_u64 v[14:15], v[18:19], 0, v[14:15]
	s_waitcnt vmcnt(7)
	v_lshlrev_b32_e32 v18, 16, v36
	v_and_b32_e32 v19, 0xffff0000, v36
	v_pk_fma_f32 v[26:27], v[24:25], v[24:25], v[26:27]
	v_pk_mul_f32 v[28:29], v[18:19], v[18:19]
	s_brev_b32 s0, 60
	v_mov_b32_e32 v20, v28
	v_pk_mov_b32 v[26:27], v[28:29], v[26:27] op_sel:[1,0]
	s_mov_b32 s1, 0x3b800000
	v_pk_add_f32 v[20:21], v[20:21], v[26:27]
	s_nop 1
	v_mov_b32_e32 v254, v21
	v_mov_b32_e32 v27, v21
	v_cmp_gt_u32_e64 s[98:99], 32, v176
	s_nop 0
	v_permlane32_swap_b32_e32 v27, v254
	v_cndmask_b32_e64 v27, v27, v254, s[98:99]
	s_nop 1
	v_mov_b32_e32 v254, v20
	v_mov_b32_e32 v26, v20
	v_cmp_gt_u32_e64 s[98:99], 32, v176
	s_nop 0
	v_permlane32_swap_b32_e32 v26, v254
	v_cndmask_b32_e64 v26, v26, v254, s[98:99]
	v_readlane_b32 s14, v246, 39
	v_readlane_b32 s15, v246, 40
	s_waitcnt vmcnt(6)
	v_lshlrev_b32_e32 v8, 16, v37
	v_readlane_b32 s2, v246, 27
	s_waitcnt lgkmcnt(0)
	v_pk_add_f32 v[20:21], v[20:21], v[26:27]
	s_nop 1
	v_mov_b32_e32 v254, v21
	v_mov_b32_e32 v27, v21
	v_and_b32_e32 v255, 16, v176
	v_cmp_eq_u32_e64 s[98:99], 0, v255
	s_nop 0
	v_permlane16_swap_b32_e32 v27, v254
	v_cndmask_b32_e64 v27, v27, v254, s[98:99]
	s_nop 1
	v_mov_b32_e32 v254, v20
	v_mov_b32_e32 v26, v20
	v_and_b32_e32 v255, 16, v176
	v_cmp_eq_u32_e64 s[98:99], 0, v255
	s_nop 0
	v_permlane16_swap_b32_e32 v26, v254
	v_cndmask_b32_e64 v26, v26, v254, s[98:99]
	v_readlane_b32 s3, v246, 28
	v_readlane_b32 s4, v246, 29
	v_readlane_b32 s5, v246, 30
	v_readlane_b32 s6, v246, 31
	s_waitcnt lgkmcnt(0)
	v_pk_add_f32 v[20:21], v[20:21], v[26:27]
	s_nop 1
	v_mov_b32_dpp v27, v21 row_ror:8 row_mask:0xf bank_mask:0xf
	s_nop 1
	v_mov_b32_dpp v26, v20 row_ror:8 row_mask:0xf bank_mask:0xf
	v_readlane_b32 s7, v246, 32
	v_readlane_b32 s8, v246, 33
	v_readlane_b32 s9, v246, 34
	v_readlane_b32 s12, v246, 37
	s_waitcnt lgkmcnt(0)
	v_pk_add_f32 v[20:21], v[20:21], v[26:27]
	s_nop 1
	v_mov_b32_dpp v27, v21 row_shl:4 row_mask:0xf bank_mask:0x5
	v_mov_b32_dpp v27, v21 row_shr:4 row_mask:0xf bank_mask:0xa
	s_nop 1
	v_mov_b32_dpp v26, v20 row_shl:4 row_mask:0xf bank_mask:0x5
	v_mov_b32_dpp v26, v20 row_shr:4 row_mask:0xf bank_mask:0xa
	v_readlane_b32 s13, v246, 38
	s_waitcnt lgkmcnt(0)
	v_pk_add_f32 v[20:21], v[20:21], v[26:27]
	s_nop 1
	v_mov_b32_dpp v27, v21 quad_perm:[2,3,0,1] row_mask:0xf bank_mask:0xf
	s_nop 1
	v_mov_b32_dpp v26, v20 quad_perm:[2,3,0,1] row_mask:0xf bank_mask:0xf
	s_waitcnt lgkmcnt(0)
	v_pk_add_f32 v[20:21], v[20:21], v[26:27]
	s_nop 1
	v_mov_b32_dpp v27, v21 quad_perm:[1,0,3,2] row_mask:0xf bank_mask:0xf
	s_nop 1
	v_mov_b32_dpp v26, v20 quad_perm:[1,0,3,2] row_mask:0xf bank_mask:0xf
	s_waitcnt lgkmcnt(0)
	v_pk_add_f32 v[20:21], v[20:21], v[26:27]
	s_nop 0
	v_pk_fma_f32 v[20:21], v[20:21], s[0:1], v[138:139] op_sel_hi:[1,1,0]
	s_nop 0
	v_mul_f32_e32 v13, 0x4b800000, v21
	v_cmp_gt_f32_e64 s[0:1], s33, v21
	v_cmp_gt_f32_e32 vcc, s33, v20
	s_nop 0
	v_cndmask_b32_e64 v13, v21, v13, s[0:1]
	v_rsq_f32_e32 v13, v13
	s_nop 0
	v_mul_f32_e32 v21, 0x45800000, v13
	v_cndmask_b32_e64 v26, v13, v21, s[0:1]
	v_pk_mul_f32 v[22:23], v[26:27], v[22:23] op_sel_hi:[0,1]
	v_pk_mul_f32 v[0:1], v[0:1], v[22:23]
	v_pk_mul_f32 v[22:23], v[26:27], v[24:25] op_sel_hi:[0,1]
	v_pk_mul_f32 v[2:3], v[2:3], v[22:23]
	v_cvt_pk_bf16_f32 v0, v0, v1
	v_cvt_pk_bf16_f32 v1, v2, v3
	global_store_dwordx2 v[14:15], v[0:1], off
	v_mul_f32_e32 v0, 0x4b800000, v20
	v_cndmask_b32_e32 v0, v20, v0, vcc
	v_rsq_f32_e32 v0, v0
	v_mov_b64_e32 v[2:3], s[14:15]
	v_mad_u64_u32 v[2:3], s[0:1], v16, s30, v[2:3]
	v_mul_f32_e32 v1, 0x45800000, v0
	v_cndmask_b32_e32 v0, v0, v1, vcc
	v_pk_mul_f32 v[0:1], v[0:1], v[18:19] op_sel_hi:[0,1]
	v_pk_mul_f32 v[0:1], v[6:7], v[0:1]
	v_mov_b32_e32 v6, v3
	v_mad_u64_u32 v[6:7], s[0:1], v17, s30, v[6:7]
	v_mov_b32_e32 v3, v6
	v_mov_b32_e32 v13, v137
	v_cvt_pk_bf16_f32 v14, v0, v1
	v_lshl_add_u64 v[2:3], v[2:3], 0, v[12:13]
	global_store_dword v[2:3], v14, off
	ds_bpermute_b32 v2, v9, v8
	v_cmp_lt_i32_e32 vcc, 15, v11
	s_mov_b64 s[0:1], 0
	s_and_saveexec_b64 s[2:3], vcc
	s_xor_b64 s[2:3], exec, s[2:3]
	s_cbranch_execz .LBB0_790
	v_lshrrev_b32_e32 v0, 6, v5
	v_and_b32_e32 v1, 63, v5
	v_cndmask_b32_e64 v0, v1, v0, s[42:43]
	v_readlane_b32 s4, v246, 9
	v_lshl_or_b32 v1, v0, 5, v39
	v_readlane_b32 s14, v246, 19
	v_readlane_b32 s15, v246, 20
	v_readlane_b32 s16, v246, 21
	v_readlane_b32 s17, v246, 22
	s_nop 2
	global_load_dword v0, v1, s[14:15]
	s_nop 0
	global_load_dword v9, v1, s[16:17]
	s_waitcnt lgkmcnt(0)
	v_cndmask_b32_e64 v1, v2, -v2, s[40:41]
	s_mov_b64 s[0:1], exec
	v_readlane_b32 s5, v246, 10
	v_readlane_b32 s6, v246, 11
	v_readlane_b32 s7, v246, 12
	v_readlane_b32 s8, v246, 13
	v_readlane_b32 s9, v246, 14
	v_readlane_b32 s10, v246, 15
	v_readlane_b32 s11, v246, 16
	v_readlane_b32 s12, v246, 17
	v_readlane_b32 s13, v246, 18
	v_readlane_b32 s18, v246, 23
	v_readlane_b32 s19, v246, 24
	s_waitcnt vmcnt(0)
	v_pk_mul_f32 v[0:1], v[0:1], v[8:9]
	s_nop 0
	v_add_f32_e32 v8, v0, v1
	s_andn2_saveexec_b64 s[2:3], s[2:3]
	s_cbranch_execnz .LBB0_791

.LBB0_972:
	s_add_i32 s3, s89, s2
	s_or_b32 s5, s2, s88
	s_add_i32 s4, s90, s2
	s_cmp_lt_u32 s3, s23
	s_cselect_b64 s[0:1], -1, 0
	s_cmp_lg_u32 s5, 0
	s_cselect_b64 s[6:7], -1, 0
	s_and_b64 vcc, s[0:1], s[6:7]
	s_and_b64 s[0:1], vcc, exec
	s_cselect_b32 s0, s4, s94
	v_mad_i64_i32 v[8:9], s[0:1], s0, v198, v[4:5]
	s_cmp_lt_u32 s5, s23
	s_cselect_b64 s[0:1], -1, 0
	s_and_b64 s[6:7], s[0:1], exec
	s_cselect_b32 s5, s2, 0
	s_or_b32 s5, s5, s94
	v_mad_i64_i32 v[10:11], s[6:7], s5, v198, v[4:5]
	s_add_i32 s5, s3, 2
	s_add_i32 s8, s4, 2
	s_cmp_lt_u32 s5, s23
	s_cselect_b64 s[40:41], -1, 0
	s_and_b64 s[6:7], s[40:41], exec
	s_cselect_b32 s5, s8, s94
	global_load_ushort v31, v[8:9], off offset:1536
	global_load_ushort v34, v[8:9], off offset:2048
	global_load_ushort v35, v[8:9], off offset:2560
	global_load_ushort v36, v[10:11], off offset:1536
	global_load_ushort v37, v[10:11], off offset:2048
	global_load_ushort v38, v[10:11], off offset:2560
	v_mad_i64_i32 v[8:9], s[6:7], s5, v198, v[4:5]
	global_load_ushort v39, v[8:9], off offset:1536
	global_load_ushort v40, v[8:9], off offset:2048
	global_load_ushort v41, v[8:9], off offset:2560
	s_add_i32 s5, s3, 3
	s_add_i32 s8, s4, 3
	s_cmp_lt_u32 s5, s23
	s_cselect_b64 s[68:69], -1, 0
	s_and_b64 s[6:7], s[68:69], exec
	s_cselect_b32 s5, s8, s94
	s_add_i32 s8, s3, 4
	s_add_i32 s9, s4, 4
	s_cmp_lt_u32 s8, s23
	s_cselect_b64 s[66:67], -1, 0
	s_and_b64 s[6:7], s[66:67], exec
	v_mad_i64_i32 v[8:9], s[6:7], s5, v198, v[4:5]
	s_cselect_b32 s5, s9, s94
	s_add_i32 s8, s3, 5
	s_add_i32 s9, s4, 5
	s_cmp_lt_u32 s8, s23
	s_cselect_b64 s[64:65], -1, 0
	s_and_b64 s[6:7], s[64:65], exec
	v_mad_i64_i32 v[10:11], s[6:7], s5, v198, v[4:5]
	s_cselect_b32 s5, s9, s94
	s_add_i32 s8, s3, 6
	s_add_i32 s9, s4, 6
	s_cmp_lt_u32 s8, s23
	s_cselect_b64 s[62:63], -1, 0
	s_and_b64 s[6:7], s[62:63], exec
	s_waitcnt vmcnt(58)
	v_mad_i64_i32 v[32:33], s[6:7], s5, v198, v[4:5]
	s_cselect_b32 s5, s9, s94
	s_add_i32 s8, s3, 7
	s_add_i32 s9, s4, 7
	s_cmp_lt_u32 s8, s23
	global_load_ushort v100, v[8:9], off offset:1536
	global_load_ushort v13, v[8:9], off offset:2048
	global_load_ushort v12, v[8:9], off offset:2560
	global_load_ushort v15, v[10:11], off offset:1536
	global_load_ushort v14, v[10:11], off offset:2048
	global_load_ushort v98, v[10:11], off offset:2560
	global_load_ushort v93, v[32:33], off offset:1536
	s_cselect_b64 s[60:61], -1, 0
	s_and_b64 s[6:7], s[60:61], exec
	v_mad_i64_i32 v[10:11], s[6:7], s5, v198, v[4:5]
	s_waitcnt vmcnt(15)
	v_lshlrev_b32_e32 v8, 16, v31
	s_waitcnt vmcnt(14)
	v_lshlrev_b32_e32 v9, 16, v34
	v_cndmask_b32_e32 v112, 0, v8, vcc
	v_cndmask_b32_e32 v113, 0, v9, vcc
	s_waitcnt vmcnt(12)
	v_lshlrev_b32_e32 v8, 16, v36
	s_waitcnt vmcnt(11)
	v_lshlrev_b32_e32 v9, 16, v37
	s_waitcnt vmcnt(10)
	v_lshlrev_b32_e32 v34, 16, v38
	v_lshlrev_b32_e32 v31, 16, v35
	v_cndmask_b32_e64 v105, 0, v8, s[0:1]
	v_cndmask_b32_e64 v104, 0, v9, s[0:1]
	v_cndmask_b32_e64 v103, 0, v34, s[0:1]
	s_waitcnt vmcnt(9)
	v_lshlrev_b32_e32 v8, 16, v39
	s_waitcnt vmcnt(8)
	v_lshlrev_b32_e32 v34, 16, v40
	s_waitcnt vmcnt(7)
	v_lshlrev_b32_e32 v35, 16, v41
	s_cselect_b32 s0, s9, s94
	v_cndmask_b32_e64 v9, 0, v8, s[40:41]
	v_cndmask_b32_e64 v8, 0, v34, s[40:41]
	v_cndmask_b32_e64 v99, 0, v35, s[40:41]
	v_mad_i64_i32 v[34:35], s[0:1], s0, v198, v[4:5]
	s_add_i32 s0, s3, 8
	s_add_i32 s5, s4, 8
	s_cmp_lt_u32 s0, s23
	s_cselect_b64 s[58:59], -1, 0
	s_and_b64 s[0:1], s[58:59], exec
	s_cselect_b32 s0, s5, s94
	global_load_ushort v95, v[32:33], off offset:2048
	global_load_ushort v94, v[32:33], off offset:2560
	global_load_ushort v90, v[10:11], off offset:1536
	global_load_ushort v89, v[10:11], off offset:2048
	global_load_ushort v88, v[10:11], off offset:2560
	global_load_ushort v85, v[34:35], off offset:1536
	global_load_ushort v84, v[34:35], off offset:2048
	global_load_ushort v83, v[34:35], off offset:2560
	v_mad_i64_i32 v[10:11], s[0:1], s0, v198, v[4:5]
	s_add_i32 s0, s3, 9
	s_add_i32 s5, s4, 9
	s_cmp_lt_u32 s0, s23
	s_cselect_b64 s[56:57], -1, 0
	s_and_b64 s[0:1], s[56:57], exec
	s_cselect_b32 s0, s5, s94
	v_mad_i64_i32 v[32:33], s[0:1], s0, v198, v[4:5]
	s_add_i32 s0, s3, 10
	s_add_i32 s5, s4, 10
	s_cmp_lt_u32 s0, s23
	s_cselect_b64 s[54:55], -1, 0
	s_and_b64 s[0:1], s[54:55], exec
	s_cselect_b32 s0, s5, s94
	v_mad_i64_i32 v[34:35], s[0:1], s0, v198, v[4:5]
	s_add_i32 s0, s3, 11
	s_add_i32 s5, s4, 11
	s_cmp_lt_u32 s0, s23
	s_cselect_b64 s[52:53], -1, 0
	s_and_b64 s[0:1], s[52:53], exec
	s_cselect_b32 s0, s5, s94
	global_load_ushort v80, v[10:11], off offset:1536
	global_load_ushort v79, v[10:11], off offset:2048
	global_load_ushort v78, v[10:11], off offset:2560
	global_load_ushort v75, v[32:33], off offset:1536
	global_load_ushort v73, v[32:33], off offset:2048
	global_load_ushort v74, v[32:33], off offset:2560
	global_load_ushort v69, v[34:35], off offset:1536
	global_load_ushort v68, v[34:35], off offset:2048
	v_mad_i64_i32 v[10:11], s[0:1], s0, v198, v[4:5]
	s_add_i32 s0, s3, 12
	s_add_i32 s5, s4, 12
	s_cmp_lt_u32 s0, s23
	s_cselect_b64 s[50:51], -1, 0
	s_and_b64 s[0:1], s[50:51], exec
	s_cselect_b32 s0, s5, s94
	v_mad_i64_i32 v[32:33], s[0:1], s0, v198, v[4:5]
	s_add_i32 s0, s3, 13
	s_add_i32 s5, s4, 13
	s_cmp_lt_u32 s0, s23
	s_cselect_b64 s[48:49], -1, 0
	s_and_b64 s[0:1], s[48:49], exec
	s_cselect_b32 s0, s5, s94
	v_mad_i64_i32 v[36:37], s[0:1], s0, v198, v[4:5]
	s_add_i32 s0, s3, 14
	s_add_i32 s5, s4, 14
	s_cmp_lt_u32 s0, s23
	s_cselect_b64 s[46:47], -1, 0
	s_and_b64 s[0:1], s[46:47], exec
	s_cselect_b32 s0, s5, s94
	global_load_ushort v70, v[34:35], off offset:2560
	global_load_ushort v65, v[10:11], off offset:1536
	global_load_ushort v64, v[10:11], off offset:2048
	global_load_ushort v63, v[10:11], off offset:2560
	global_load_ushort v60, v[32:33], off offset:1536
	global_load_ushort v59, v[32:33], off offset:2048
	global_load_ushort v58, v[32:33], off offset:2560
	global_load_ushort v53, v[36:37], off offset:1536
	v_mad_i64_i32 v[10:11], s[0:1], s0, v198, v[4:5]
	s_add_i32 s0, s3, 15
	s_add_i32 s5, s4, 15
	s_cmp_lt_u32 s0, s23
	s_cselect_b64 s[44:45], -1, 0
	s_and_b64 s[0:1], s[44:45], exec
	s_cselect_b32 s0, s5, s94
	v_mad_i64_i32 v[32:33], s[0:1], s0, v198, v[4:5]
	s_add_i32 s0, s3, 16
	s_add_i32 s5, s4, 16
	s_cmp_lt_u32 s0, s23
	s_cselect_b64 s[42:43], -1, 0
	s_and_b64 s[0:1], s[42:43], exec
	s_cselect_b32 s0, s5, s94
	s_add_i32 s3, s3, 17
	s_add_i32 s4, s4, 17
	s_cmp_lt_u32 s3, s23
	s_cselect_b64 s[40:41], -1, 0
	global_load_ushort v55, v[36:37], off offset:2048
	global_load_ushort v54, v[36:37], off offset:2560
	global_load_ushort v50, v[10:11], off offset:1536
	global_load_ushort v49, v[10:11], off offset:2048
	global_load_ushort v48, v[10:11], off offset:2560
	global_load_ushort v45, v[32:33], off offset:1536
	global_load_ushort v43, v[32:33], off offset:2048
	global_load_ushort v44, v[32:33], off offset:2560
	v_mad_i64_i32 v[10:11], s[0:1], s0, v198, v[4:5]
	s_and_b64 s[0:1], s[40:41], exec
	s_cselect_b32 s0, s4, s94
	v_mad_i64_i32 v[36:37], s[0:1], s0, v198, v[4:5]
	v_cndmask_b32_e32 v31, 0, v31, vcc
	s_or_b32 s0, s2, s94
	v_mul_f32_e32 v114, v21, v103
	s_or_b32 s16, s0, 1
	s_or_b32 s14, s0, 2
	v_fmac_f32_e32 v114, v20, v31
	v_mad_i64_i32 v[46:47], s[2:3], s0, v198, v[6:7]
	global_load_ushort v40, v[10:11], off offset:1536
	global_load_ushort v39, v[10:11], off offset:2048
	global_load_ushort v38, v[10:11], off offset:2560
	global_load_ushort v35, v[36:37], off offset:1536
	global_load_ushort v33, v[36:37], off offset:2048
	global_load_ushort v34, v[36:37], off offset:2560
	global_load_ushort v107, v[46:47], off offset:3072
	global_load_ushort v106, v[46:47], off offset:3088
	v_mad_i64_i32 v[10:11], s[2:3], s16, v198, v[6:7]
	v_mad_i64_i32 v[36:37], s[2:3], s14, v198, v[6:7]
	s_or_b32 s12, s0, 3
	s_or_b32 s10, s0, 4
	s_or_b32 s8, s0, 5
	s_or_b32 s6, s0, 6
	v_fmac_f32_e32 v114, v22, v99
	v_mad_i64_i32 v[46:47], s[2:3], s12, v198, v[6:7]
	v_mad_i64_i32 v[56:57], s[2:3], s10, v198, v[6:7]
	global_load_ushort v102, v[10:11], off offset:3072
	global_load_ushort v101, v[10:11], off offset:3088
	global_load_ushort v97, v[36:37], off offset:3072
	global_load_ushort v96, v[36:37], off offset:3088
	global_load_ushort v92, v[46:47], off offset:3072
	global_load_ushort v91, v[46:47], off offset:3088
	global_load_ushort v87, v[56:57], off offset:3072
	global_load_ushort v86, v[56:57], off offset:3088
	v_mad_i64_i32 v[10:11], s[2:3], s8, v198, v[6:7]
	v_mad_i64_i32 v[36:37], s[2:3], s6, v198, v[6:7]
	s_or_b32 s4, s0, 7
	s_or_b32 s92, s0, 8
	s_or_b32 s70, s0, 9
	s_or_b32 s96, s0, 10
	v_mul_f32_e32 v31, 0xbfb8aa3b, v114
	v_mad_i64_i32 v[46:47], s[2:3], s4, v198, v[6:7]
	v_mad_i64_i32 v[56:57], s[2:3], s92, v198, v[6:7]
	global_load_ushort v82, v[10:11], off offset:3072
	global_load_ushort v81, v[10:11], off offset:3088
	global_load_ushort v77, v[36:37], off offset:3072
	global_load_ushort v76, v[36:37], off offset:3088
	global_load_ushort v72, v[46:47], off offset:3072
	global_load_ushort v71, v[46:47], off offset:3088
	global_load_ushort v67, v[56:57], off offset:3072
	global_load_ushort v66, v[56:57], off offset:3088
	v_mad_i64_i32 v[10:11], s[2:3], s70, v198, v[6:7]
	v_mad_i64_i32 v[36:37], s[2:3], s96, v198, v[6:7]
	v_exp_f32_e32 v115, v31
	s_or_b32 s2, s0, 11
	s_or_b32 s26, s0, 12
	v_mad_i64_i32 v[46:47], s[20:21], s2, v198, v[6:7]
	v_mad_i64_i32 v[108:109], s[20:21], s26, v198, v[6:7]
	s_or_b32 s24, s0, 13
	s_or_b32 s30, s0, 14
	global_load_ushort v62, v[10:11], off offset:3072
	global_load_ushort v61, v[10:11], off offset:3088
	global_load_ushort v57, v[36:37], off offset:3072
	global_load_ushort v56, v[36:37], off offset:3088
	global_load_ushort v52, v[46:47], off offset:3072
	global_load_ushort v51, v[46:47], off offset:3088
	s_nop 0
	global_load_ushort v47, v[108:109], off offset:3072
	global_load_ushort v46, v[108:109], off offset:3088
	v_mad_i64_i32 v[10:11], s[20:21], s24, v198, v[6:7]
	v_mad_i64_i32 v[108:109], s[20:21], s30, v198, v[6:7]
	s_or_b32 s34, s0, 15
	v_mad_i64_i32 v[110:111], s[20:21], s34, v198, v[6:7]
	global_load_ushort v42, v[10:11], off offset:3072
	global_load_ushort v41, v[10:11], off offset:3088
	global_load_ushort v37, v[108:109], off offset:3072
	global_load_ushort v36, v[108:109], off offset:3088
	global_load_ushort v32, v[110:111], off offset:3072
	global_load_ushort v31, v[110:111], off offset:3088
	v_mul_f32_e32 v11, v16, v112
	v_add_f32_e32 v112, 1.0, v115
	v_mul_f32_e32 v109, v17, v105
	v_mul_f32_e32 v10, v18, v113
	v_mul_f32_e32 v108, v19, v104
	v_div_scale_f32 v110, s[20:21], v112, v112, v114
	v_pk_add_f32 v[10:11], v[10:11], v[108:109]
	v_rcp_f32_e32 v111, v110
	v_pk_fma_f32 v[10:11], v[2:3], v[8:9], v[10:11]
	s_ashr_i32 s1, s0, 31
	v_mul_f32_e32 v108, 0xbfb8aa3b, v11
	v_exp_f32_e32 v109, v108
	v_mul_f32_e32 v108, 0xbfb8aa3b, v10
	v_exp_f32_e32 v108, v108
	v_fma_f32 v113, -v110, v111, 1.0
	v_fmac_f32_e32 v111, v113, v111
	v_div_scale_f32 v113, vcc, v114, v112, v114
	v_mul_f32_e32 v115, v113, v111
	v_fma_f32 v116, -v110, v115, v113
	v_pk_add_f32 v[108:109], v[108:109], 1.0 op_sel_hi:[1,0]
	v_fmac_f32_e32 v115, v116, v111
	v_div_scale_f32 v116, s[20:21], v109, v109, v11
	v_rcp_f32_e32 v117, v116
	v_fma_f32 v110, -v110, v115, v113
	v_div_fmas_f32 v113, v110, v111, v115
	v_fma_f32 v110, -v116, v117, 1.0
	v_fmac_f32_e32 v117, v110, v117
	v_div_scale_f32 v110, vcc, v11, v109, v11
	v_mul_f32_e32 v111, v110, v117
	v_fma_f32 v115, -v116, v111, v110
	v_fmac_f32_e32 v111, v115, v117
	v_div_scale_f32 v115, s[20:21], v108, v108, v10
	v_fma_f32 v110, -v116, v111, v110
	v_rcp_f32_e32 v116, v115
	v_div_fmas_f32 v110, v110, v117, v111
	v_div_fixup_f32 v109, v110, v109, v11
	s_lshl_b64 s[20:21], s[0:1], 8
	v_fma_f32 v11, -v115, v116, 1.0
	v_fmac_f32_e32 v116, v11, v116
	v_div_scale_f32 v11, vcc, v10, v108, v10
	v_mul_f32_e32 v110, v11, v116
	v_fma_f32 v111, -v115, v110, v11
	v_fmac_f32_e32 v110, v111, v116
	v_fma_f32 v11, -v115, v110, v11
	v_div_fmas_f32 v11, v11, v116, v110
	v_div_fixup_f32 v108, v11, v108, v10
	v_pk_mul_f32 v[10:11], v[108:109], v[108:109]
	s_nop 1
	v_mov_b32_e32 v254, v11
	v_cmp_gt_u32_e64 s[98:99], 32, v176
	s_nop 0
	v_permlane32_swap_b32_e32 v11, v254
	v_cndmask_b32_e64 v11, v11, v254, s[98:99]
	s_nop 1
	v_mov_b32_e32 v254, v10
	v_cmp_gt_u32_e64 s[98:99], 32, v176
	s_nop 0
	v_permlane32_swap_b32_e32 v10, v254
	v_cndmask_b32_e64 v10, v10, v254, s[98:99]
	v_div_fixup_f32 v116, v113, v112, v114
	s_waitcnt lgkmcnt(0)
	v_pk_fma_f32 v[10:11], v[108:109], v[108:109], v[10:11]
	s_nop 1
	v_mov_b32_e32 v254, v11
	v_mov_b32_e32 v111, v11
	v_and_b32_e32 v255, 16, v176
	v_cmp_eq_u32_e64 s[98:99], 0, v255
	s_nop 0
	v_permlane16_swap_b32_e32 v111, v254
	v_cndmask_b32_e64 v111, v111, v254, s[98:99]
	s_nop 1
	v_mov_b32_e32 v254, v10
	v_mov_b32_e32 v110, v10
	v_and_b32_e32 v255, 16, v176
	v_cmp_eq_u32_e64 s[98:99], 0, v255
	s_nop 0
	v_permlane16_swap_b32_e32 v110, v254
	v_cndmask_b32_e64 v110, v110, v254, s[98:99]
	s_waitcnt lgkmcnt(0)
	v_pk_add_f32 v[10:11], v[10:11], v[110:111]
	s_nop 1
	v_mov_b32_dpp v111, v11 row_ror:8 row_mask:0xf bank_mask:0xf
	s_nop 1
	v_mov_b32_dpp v110, v10 row_ror:8 row_mask:0xf bank_mask:0xf
	s_waitcnt lgkmcnt(0)
	v_pk_add_f32 v[10:11], v[10:11], v[110:111]
	s_nop 1
	v_mov_b32_dpp v111, v11 row_shl:4 row_mask:0xf bank_mask:0x5
	v_mov_b32_dpp v111, v11 row_shr:4 row_mask:0xf bank_mask:0xa
	s_nop 1
	v_mov_b32_dpp v110, v10 row_shl:4 row_mask:0xf bank_mask:0x5
	v_mov_b32_dpp v110, v10 row_shr:4 row_mask:0xf bank_mask:0xa
	s_waitcnt lgkmcnt(0)
	v_pk_add_f32 v[10:11], v[10:11], v[110:111]
	s_nop 1
	v_mov_b32_dpp v111, v11 quad_perm:[2,3,0,1] row_mask:0xf bank_mask:0xf
	s_nop 1
	v_mov_b32_dpp v110, v10 quad_perm:[2,3,0,1] row_mask:0xf bank_mask:0xf
	s_waitcnt lgkmcnt(0)
	v_pk_add_f32 v[10:11], v[10:11], v[110:111]
	s_nop 1
	v_mov_b32_dpp v111, v11 quad_perm:[1,0,3,2] row_mask:0xf bank_mask:0xf
	s_nop 1
	v_mov_b32_dpp v110, v10 quad_perm:[1,0,3,2] row_mask:0xf bank_mask:0xf
	s_waitcnt lgkmcnt(0)
	v_pk_add_f32 v[10:11], v[10:11], v[110:111]
	s_nop 0
	v_pk_add_f32 v[110:111], v[10:11], s[22:23] op_sel_hi:[1,0]
	s_nop 0
	v_mul_f32_e32 v10, 0x4b800000, v111
	v_cmp_gt_f32_e32 vcc, s33, v111
	s_nop 1
	v_cndmask_b32_e32 v10, v111, v10, vcc
	v_rsq_f32_e32 v111, v10
	v_lshl_add_u64 v[10:11], s[20:21], 0, v[0:1]
	v_lshlrev_b64 v[112:113], 1, v[10:11]
	v_lshl_add_u64 v[114:115], s[78:79], 0, v[112:113]
	v_mul_f32_e32 v117, 0x45800000, v111
	v_cndmask_b32_e32 v111, v111, v117, vcc
	v_mul_f32_e32 v109, v109, v111
	v_mul_f32_e32 v111, 0x4b800000, v110
	v_cmp_gt_f32_e32 vcc, s33, v110
	v_mul_f32_e32 v109, 0x3e000000, v109
	v_cvt_pk_bf16_f32 v109, v109, s0
	v_cndmask_b32_e32 v110, v110, v111, vcc
	v_rsq_f32_e32 v110, v110
	global_store_short v[114:115], v109, off
	v_mul_f32_e32 v109, 0x45800000, v110
	v_cndmask_b32_e32 v109, v110, v109, vcc
	v_mul_f32_e32 v108, v108, v109
	v_cvt_pk_bf16_f32 v110, v108, s0
	v_lshl_add_u64 v[108:109], s[80:81], 0, v[112:113]
	global_store_short v[108:109], v110, off
	v_cvt_pk_bf16_f32 v110, v116, s0
	v_lshl_add_u64 v[108:109], s[82:83], 0, v[112:113]
	global_store_short v[108:109], v110, off
	s_and_saveexec_b64 s[20:21], s[38:39]
	s_cbranch_execz .LBB0_976
	s_waitcnt vmcnt(34)
	v_lshlrev_b32_e32 v107, 16, v107
	v_mul_f32_e32 v107, 0xbfb8aa3b, v107
	v_exp_f32_e32 v107, v107
	s_waitcnt vmcnt(33)
	v_lshlrev_b32_e32 v110, 16, v106
	v_mad_i64_i32 v[10:11], s[0:1], s0, v199, v[10:11]
	v_add_f32_e32 v107, 1.0, v107
	v_div_scale_f32 v108, vcc, v107, v107, 1.0
	v_rcp_f32_e32 v109, v108
	v_div_scale_f32 v106, vcc, 1.0, v107, 1.0
	s_mov_b32 s0, 0x41a00000
	v_fma_f32 v111, -v108, v109, 1.0
	v_fmac_f32_e32 v109, v111, v109
	v_mul_f32_e32 v111, v106, v109
	v_fma_f32 v112, -v108, v111, v106
	v_fmac_f32_e32 v111, v112, v109
	v_fma_f32 v106, -v108, v111, v106
	v_div_fmas_f32 v106, v106, v109, v111
	v_div_fixup_f32 v108, v106, v107, 1.0
	v_lshl_add_u64 v[106:107], v[10:11], 2, s[84:85]
	global_store_dword v[106:107], v108, off
	v_add_f32_e32 v106, v24, v110
	v_cmp_nlt_f32_e32 vcc, s0, v106
	s_and_saveexec_b64 s[0:1], vcc
	s_cbranch_execz .LBB0_975
	v_mul_f32_e32 v106, 0x3fb8aa3b, v106
	v_exp_f32_e32 v120, v106
	s_mov_b32 s3, 0x3f2aaaab
	v_add_f32_e32 v108, 1.0, v120
	v_frexp_mant_f32_e32 v110, v108
	v_cvt_f64_f32_e32 v[106:107], v108
	v_frexp_exp_i32_f64_e32 v106, v[106:107]
	v_cmp_gt_f32_e32 vcc, s3, v110
	v_add_f32_e32 v109, -1.0, v108
	v_sub_f32_e32 v111, v109, v108
	v_subbrev_co_u32_e32 v114, vcc, 0, v106, vcc
	v_sub_u32_e32 v106, 0, v114
	v_sub_f32_e32 v109, v120, v109
	v_add_f32_e32 v111, 1.0, v111
	v_ldexp_f32 v107, v108, v106
	v_add_f32_e32 v109, v109, v111
	v_add_f32_e32 v108, -1.0, v107
	v_add_f32_e32 v110, 1.0, v107
	v_ldexp_f32 v106, v109, v106
	v_add_f32_e32 v109, 1.0, v108
	v_add_f32_e32 v111, -1.0, v110
	v_sub_f32_e32 v109, v107, v109
	v_sub_f32_e32 v107, v107, v111
	v_add_f32_e32 v109, v106, v109
	v_add_f32_e32 v106, v106, v107
	v_add_f32_e32 v115, v110, v106
	v_rcp_f32_e32 v117, v115
	v_sub_f32_e32 v107, v115, v110
	v_sub_f32_e32 v116, v106, v107
	v_add_f32_e32 v107, v108, v109
	v_mul_f32_e32 v119, v107, v117
	v_sub_f32_e32 v106, v107, v108
	v_mul_f32_e32 v108, v115, v119
	v_fma_f32 v110, v119, v115, -v108
	v_fmac_f32_e32 v110, v119, v116
	v_sub_f32_e32 v118, v109, v106
	v_add_f32_e32 v106, v108, v110
	v_sub_f32_e32 v109, v107, v106
	v_pk_add_f32 v[112:113], v[106:107], v[108:109] neg_lo:[0,1] neg_hi:[0,1]
	v_mov_b32_e32 v111, v106
	v_pk_add_f32 v[106:107], v[112:113], v[110:111] neg_lo:[0,1] neg_hi:[0,1]
	s_mov_b32 s3, 0x3f317218
	v_add_f32_e32 v107, v118, v107
	v_add_f32_e32 v106, v106, v107
	v_add_f32_e32 v107, v109, v106
	v_mul_f32_e32 v118, v117, v107
	v_mul_f32_e32 v108, v115, v118
	v_fma_f32 v110, v118, v115, -v108
	v_fmac_f32_e32 v110, v118, v116
	v_sub_f32_e32 v109, v109, v107
	v_add_f32_e32 v115, v106, v109
	v_add_f32_e32 v106, v108, v110
	v_sub_f32_e32 v109, v107, v106
	v_pk_add_f32 v[112:113], v[106:107], v[108:109] neg_lo:[0,1] neg_hi:[0,1]
	v_mov_b32_e32 v111, v106
	v_pk_add_f32 v[106:107], v[112:113], v[110:111] neg_lo:[0,1] neg_hi:[0,1]
	v_cmp_neq_f32_e32 vcc, s36, v120
	v_add_f32_e32 v107, v115, v107
	v_add_f32_e32 v106, v106, v107
	v_add_f32_e32 v107, v119, v118
	v_add_f32_e32 v106, v109, v106
	v_sub_f32_e32 v108, v107, v119
	v_mul_f32_e32 v106, v117, v106
	v_sub_f32_e32 v108, v118, v108
	v_add_f32_e32 v108, v108, v106
	v_add_f32_e32 v110, v107, v108
	v_mul_f32_e32 v111, v110, v110
	v_fmamk_f32 v106, v111, 0x3e9b6dac, v172
	v_fmaak_f32 v143, v111, v106, 0x3f2aaada
	v_cvt_f32_i32_e32 v106, v114
	v_sub_f32_e32 v107, v110, v107
	v_sub_f32_e32 v107, v108, v107
	v_ldexp_f32 v112, v107, 1
	v_mul_f32_e32 v107, v110, v111
	v_ldexp_f32 v109, v110, 1
	v_pk_mul_f32 v[110:111], v[106:107], v[142:143]
	s_nop 0
	v_fma_f32 v108, v106, s3, -v110
	v_fmac_f32_e32 v108, 0xb102e308, v106
	v_pk_add_f32 v[106:107], v[110:111], v[108:109]
	s_mov_b32 s3, 0x33800000
	v_sub_f32_e32 v109, v107, v109
	v_sub_f32_e32 v109, v111, v109
	v_add_f32_e32 v113, v112, v109
	v_mov_b32_e32 v112, v110
	v_pk_add_f32 v[110:111], v[106:107], v[110:111] neg_lo:[0,1] neg_hi:[0,1]
	v_pk_add_f32 v[114:115], v[106:107], v[112:113]
	v_mov_b32_e32 v109, v106
	v_mov_b32_e32 v111, v115
	v_pk_add_f32 v[116:117], v[108:109], v[110:111] neg_lo:[0,1] neg_hi:[0,1]
	v_pk_add_f32 v[108:109], v[108:109], v[110:111]
	v_mov_b32_e32 v112, v113
	v_pk_add_f32 v[110:111], v[108:109], v[106:107] op_sel:[1,0] op_sel_hi:[0,1] neg_lo:[0,1] neg_hi:[0,1]
	v_pk_add_f32 v[118:119], v[114:115], v[110:111] op_sel_hi:[1,0] neg_lo:[0,1] neg_hi:[0,1]
	v_mov_b32_e32 v114, v115
	v_mov_b32_e32 v115, v109
	v_pk_mov_b32 v[110:111], v[106:107], v[110:111] op_sel:[1,0]
	v_mov_b32_e32 v113, v106
	v_pk_add_f32 v[110:111], v[114:115], v[110:111] neg_lo:[0,1] neg_hi:[0,1]
	v_mov_b32_e32 v118, v116
	v_pk_add_f32 v[106:107], v[112:113], v[110:111] neg_lo:[0,1] neg_hi:[0,1]
	v_mov_b32_e32 v117, v109
	v_pk_add_f32 v[110:111], v[118:119], v[106:107]
	s_nop 0
	v_pk_add_f32 v[112:113], v[110:111], v[110:111] op_sel:[0,1] op_sel_hi:[1,0]
	s_nop 0
	v_pk_add_f32 v[108:109], v[108:109], v[112:113] op_sel:[1,0] op_sel_hi:[0,1]
	v_mov_b32_e32 v111, v108
	v_pk_add_f32 v[114:115], v[110:111], v[116:117] neg_lo:[0,1] neg_hi:[0,1]
	v_mov_b32_e32 v107, v112
	v_sub_f32_e32 v109, v110, v114
	v_pk_add_f32 v[106:107], v[106:107], v[114:115] neg_lo:[0,1] neg_hi:[0,1]
	v_sub_f32_e32 v109, v116, v109
	v_add_f32_e32 v106, v106, v109
	v_add_f32_e32 v106, v106, v107
	v_add_f32_e32 v106, v108, v106
	v_cndmask_b32_e32 v106, v185, v106, vcc
	v_cmp_ngt_f32_e32 vcc, -1.0, v120
	s_nop 1
	v_cndmask_b32_e32 v106, v196, v106, vcc
	v_cmp_neq_f32_e32 vcc, -1.0, v120
	s_nop 1
	v_cndmask_b32_e32 v106, v197, v106, vcc
	v_cmp_lt_f32_e64 vcc, |v120|, s3
	s_nop 1
	v_cndmask_b32_e32 v106, v106, v120, vcc

.LBB0_976:
	s_or_b64 exec, exec, s[20:21]
	s_waitcnt vmcnt(62)
	v_lshlrev_b32_e32 v12, 16, v12
	v_lshlrev_b32_e32 v10, 16, v100
	v_cndmask_b32_e64 v100, 0, v12, s[68:69]
	v_mul_f32_e32 v12, v21, v99
	v_fmac_f32_e32 v12, v20, v103
	v_fmac_f32_e32 v12, v22, v100
	v_cndmask_b32_e64 v11, 0, v10, s[68:69]
	v_lshlrev_b32_e32 v10, 16, v13
	v_mul_f32_e32 v13, 0xbfb8aa3b, v12
	v_exp_f32_e32 v13, v13
	v_mul_f32_e32 v105, v16, v105
	s_waitcnt vmcnt(34)
	v_mul_f32_e32 v107, v17, v9
	v_mul_f32_e32 v104, v18, v104
	v_add_f32_e32 v13, 1.0, v13
	v_div_scale_f32 v103, s[0:1], v13, v13, v12
	v_rcp_f32_e32 v108, v103
	s_waitcnt vmcnt(33)
	v_mul_f32_e32 v106, v19, v8
	v_cndmask_b32_e64 v10, 0, v10, s[68:69]
	v_pk_add_f32 v[104:105], v[104:105], v[106:107]
	v_fma_f32 v109, -v103, v108, 1.0
	v_pk_fma_f32 v[104:105], v[2:3], v[10:11], v[104:105]
	v_fmac_f32_e32 v108, v109, v108
	v_mul_f32_e32 v106, 0xbfb8aa3b, v105
	v_div_scale_f32 v109, vcc, v12, v13, v12
	v_exp_f32_e32 v107, v106
	v_mul_f32_e32 v106, 0xbfb8aa3b, v104
	v_mul_f32_e32 v110, v109, v108
	v_exp_f32_e32 v106, v106
	v_fma_f32 v111, -v103, v110, v109
	v_fmac_f32_e32 v110, v111, v108
	s_ashr_i32 s17, s16, 31
	v_fma_f32 v103, -v103, v110, v109
	v_div_fmas_f32 v103, v103, v108, v110
	s_lshl_b64 s[0:1], s[16:17], 8
	v_pk_add_f32 v[106:107], v[106:107], 1.0 op_sel_hi:[1,0]
	v_div_fixup_f32 v103, v103, v13, v12
	v_lshl_add_u64 v[12:13], s[0:1], 0, v[0:1]
	v_div_scale_f32 v112, s[0:1], v107, v107, v105
	v_rcp_f32_e32 v113, v112
	v_lshlrev_b64 v[108:109], 1, v[12:13]
	v_lshl_add_u64 v[110:111], s[78:79], 0, v[108:109]
	s_xor_b64 s[20:21], s[18:19], -1
	v_fma_f32 v114, -v112, v113, 1.0
	v_fmac_f32_e32 v113, v114, v113
	v_div_scale_f32 v114, vcc, v105, v107, v105
	v_mul_f32_e32 v115, v114, v113
	v_fma_f32 v116, -v112, v115, v114
	v_fmac_f32_e32 v115, v116, v113
	v_fma_f32 v112, -v112, v115, v114
	v_div_fmas_f32 v112, v112, v113, v115
	v_div_fixup_f32 v105, v112, v107, v105
	v_div_scale_f32 v107, s[0:1], v106, v106, v104
	v_rcp_f32_e32 v112, v107
	s_ashr_i32 s15, s14, 31
	s_ashr_i32 s13, s12, 31
	s_ashr_i32 s11, s10, 31
	v_fma_f32 v113, -v107, v112, 1.0
	v_fmac_f32_e32 v112, v113, v112
	v_div_scale_f32 v113, vcc, v104, v106, v104
	v_mul_f32_e32 v114, v113, v112
	v_fma_f32 v115, -v107, v114, v113
	v_fmac_f32_e32 v114, v115, v112
	v_fma_f32 v107, -v107, v114, v113
	v_div_fmas_f32 v107, v107, v112, v114
	v_div_fixup_f32 v104, v107, v106, v104
	v_pk_mul_f32 v[106:107], v[104:105], v[104:105]
	s_nop 1
	v_mov_b32_e32 v254, v107
	v_cmp_gt_u32_e64 s[98:99], 32, v176
	s_nop 0
	v_permlane32_swap_b32_e32 v107, v254
	v_cndmask_b32_e64 v107, v107, v254, s[98:99]
	s_nop 1
	v_mov_b32_e32 v254, v106
	v_cmp_gt_u32_e64 s[98:99], 32, v176
	s_nop 0
	v_permlane32_swap_b32_e32 v106, v254
	v_cndmask_b32_e64 v106, v106, v254, s[98:99]
	s_ashr_i32 s9, s8, 31
	s_ashr_i32 s7, s6, 31
	s_ashr_i32 s5, s4, 31
	s_ashr_i32 s93, s92, 31
	s_waitcnt lgkmcnt(0)
	v_pk_fma_f32 v[106:107], v[104:105], v[104:105], v[106:107]
	s_nop 1
	v_mov_b32_e32 v254, v107
	v_mov_b32_e32 v113, v107
	v_and_b32_e32 v255, 16, v176
	v_cmp_eq_u32_e64 s[98:99], 0, v255
	s_nop 0
	v_permlane16_swap_b32_e32 v113, v254
	v_cndmask_b32_e64 v113, v113, v254, s[98:99]
	s_nop 1
	v_mov_b32_e32 v254, v106
	v_mov_b32_e32 v112, v106
	v_and_b32_e32 v255, 16, v176
	v_cmp_eq_u32_e64 s[98:99], 0, v255
	s_nop 0
	v_permlane16_swap_b32_e32 v112, v254
	v_cndmask_b32_e64 v112, v112, v254, s[98:99]
	s_ashr_i32 s71, s70, 31
	s_ashr_i32 s97, s96, 31
	s_ashr_i32 s3, s2, 31
	s_ashr_i32 s27, s26, 31
	s_waitcnt lgkmcnt(0)
	v_pk_add_f32 v[106:107], v[106:107], v[112:113]
	s_nop 1
	v_mov_b32_dpp v113, v107 row_ror:8 row_mask:0xf bank_mask:0xf
	s_nop 1
	v_mov_b32_dpp v112, v106 row_ror:8 row_mask:0xf bank_mask:0xf
	s_ashr_i32 s25, s24, 31
	s_ashr_i32 s31, s30, 31
	s_ashr_i32 s35, s34, 31
	s_waitcnt lgkmcnt(0)
	v_pk_add_f32 v[106:107], v[106:107], v[112:113]
	s_nop 1
	v_mov_b32_dpp v113, v107 row_shl:4 row_mask:0xf bank_mask:0x5
	v_mov_b32_dpp v113, v107 row_shr:4 row_mask:0xf bank_mask:0xa
	s_nop 1
	v_mov_b32_dpp v112, v106 row_shl:4 row_mask:0xf bank_mask:0x5
	v_mov_b32_dpp v112, v106 row_shr:4 row_mask:0xf bank_mask:0xa
	s_waitcnt lgkmcnt(0)
	v_pk_add_f32 v[106:107], v[106:107], v[112:113]
	s_nop 1
	v_mov_b32_dpp v113, v107 quad_perm:[2,3,0,1] row_mask:0xf bank_mask:0xf
	s_nop 1
	v_mov_b32_dpp v112, v106 quad_perm:[2,3,0,1] row_mask:0xf bank_mask:0xf
	s_waitcnt lgkmcnt(0)
	v_pk_add_f32 v[106:107], v[106:107], v[112:113]
	s_nop 1
	v_mov_b32_dpp v113, v107 quad_perm:[1,0,3,2] row_mask:0xf bank_mask:0xf
	s_nop 1
	v_mov_b32_dpp v112, v106 quad_perm:[1,0,3,2] row_mask:0xf bank_mask:0xf
	s_waitcnt lgkmcnt(0)
	v_pk_add_f32 v[106:107], v[106:107], v[112:113]
	s_nop 0
	v_pk_add_f32 v[106:107], v[106:107], s[22:23] op_sel_hi:[1,0]
	s_nop 0
	v_mul_f32_e32 v112, 0x4b800000, v107
	v_cmp_gt_f32_e64 s[0:1], s33, v107
	v_cmp_gt_f32_e32 vcc, s33, v106
	s_nop 0
	v_cndmask_b32_e64 v107, v107, v112, s[0:1]
	v_rsq_f32_e32 v107, v107
	v_cvt_pk_bf16_f32 v103, v103, s0
	v_mul_f32_e32 v112, 0x45800000, v107
	v_cndmask_b32_e64 v107, v107, v112, s[0:1]
	v_mul_f32_e32 v105, v105, v107
	v_mul_f32_e32 v105, 0x3e000000, v105
	v_cvt_pk_bf16_f32 v105, v105, s0
	global_store_short v[110:111], v105, off
	v_mul_f32_e32 v105, 0x4b800000, v106
	v_cndmask_b32_e32 v105, v106, v105, vcc
	v_rsq_f32_e32 v105, v105
	s_nop 0
	v_mul_f32_e32 v106, 0x45800000, v105
	v_cndmask_b32_e32 v105, v105, v106, vcc
	v_mul_f32_e32 v104, v104, v105
	v_cvt_pk_bf16_f32 v106, v104, s0
	v_lshl_add_u64 v[104:105], s[80:81], 0, v[108:109]
	global_store_short v[104:105], v106, off
	v_lshl_add_u64 v[104:105], s[82:83], 0, v[108:109]
	global_store_short v[104:105], v103, off
	s_and_saveexec_b64 s[0:1], s[38:39]
	s_cbranch_execz .LBB0_980
	s_waitcnt vmcnt(35)
	v_lshlrev_b32_e32 v102, 16, v102
	v_mul_f32_e32 v102, 0xbfb8aa3b, v102
	v_exp_f32_e32 v102, v102
	s_waitcnt vmcnt(34)
	v_lshlrev_b32_e32 v101, 16, v101
	v_mad_i64_i32 v[12:13], s[16:17], s16, v199, v[12:13]
	v_add_f32_e32 v102, 1.0, v102
	v_div_scale_f32 v103, s[18:19], v102, v102, 1.0
	v_rcp_f32_e32 v104, v103
	v_div_scale_f32 v105, vcc, 1.0, v102, 1.0
	v_add_f32_e32 v101, v24, v101
	v_fma_f32 v106, -v103, v104, 1.0
	v_fmac_f32_e32 v104, v106, v104
	v_mul_f32_e32 v106, v105, v104
	v_fma_f32 v107, -v103, v106, v105
	v_fmac_f32_e32 v106, v107, v104
	v_fma_f32 v103, -v103, v106, v105
	v_div_fmas_f32 v103, v103, v104, v106
	s_mov_b32 s16, 0x41a00000
	v_div_fixup_f32 v104, v103, v102, 1.0
	v_lshl_add_u64 v[102:103], v[12:13], 2, s[84:85]
	v_cmp_nlt_f32_e32 vcc, s16, v101
	global_store_dword v[102:103], v104, off
	s_and_saveexec_b64 s[16:17], vcc
	s_cbranch_execz .LBB0_979
	v_mul_f32_e32 v101, 0x3fb8aa3b, v101
	v_exp_f32_e32 v101, v101
	s_mov_b32 s18, 0x3f2aaaab
	v_add_f32_e32 v104, 1.0, v101
	v_frexp_mant_f32_e32 v106, v104
	v_cvt_f64_f32_e32 v[102:103], v104
	v_frexp_exp_i32_f64_e32 v102, v[102:103]
	v_cmp_gt_f32_e32 vcc, s18, v106
	v_add_f32_e32 v105, -1.0, v104
	v_sub_f32_e32 v107, v105, v104
	v_subbrev_co_u32_e32 v110, vcc, 0, v102, vcc
	v_sub_u32_e32 v102, 0, v110
	v_sub_f32_e32 v105, v101, v105
	v_add_f32_e32 v107, 1.0, v107
	v_ldexp_f32 v103, v104, v102
	v_add_f32_e32 v105, v105, v107
	v_add_f32_e32 v104, -1.0, v103
	v_add_f32_e32 v106, 1.0, v103
	v_ldexp_f32 v102, v105, v102
	v_add_f32_e32 v105, 1.0, v104
	v_add_f32_e32 v107, -1.0, v106
	v_sub_f32_e32 v105, v103, v105
	v_sub_f32_e32 v103, v103, v107
	v_add_f32_e32 v105, v102, v105
	v_add_f32_e32 v102, v102, v103
	v_add_f32_e32 v111, v106, v102
	v_rcp_f32_e32 v113, v111
	v_sub_f32_e32 v103, v111, v106
	v_sub_f32_e32 v112, v102, v103
	v_add_f32_e32 v103, v104, v105
	v_mul_f32_e32 v115, v103, v113
	v_sub_f32_e32 v102, v103, v104
	v_mul_f32_e32 v104, v111, v115
	v_fma_f32 v106, v115, v111, -v104
	v_fmac_f32_e32 v106, v115, v112
	v_sub_f32_e32 v114, v105, v102
	v_add_f32_e32 v102, v104, v106
	v_sub_f32_e32 v105, v103, v102
	v_pk_add_f32 v[108:109], v[102:103], v[104:105] neg_lo:[0,1] neg_hi:[0,1]
	v_mov_b32_e32 v107, v102
	v_pk_add_f32 v[102:103], v[108:109], v[106:107] neg_lo:[0,1] neg_hi:[0,1]
	s_mov_b32 s18, 0x3f317218
	v_add_f32_e32 v103, v114, v103
	v_add_f32_e32 v102, v102, v103
	v_add_f32_e32 v103, v105, v102
	v_mul_f32_e32 v114, v113, v103
	v_mul_f32_e32 v104, v111, v114
	v_fma_f32 v106, v114, v111, -v104
	v_fmac_f32_e32 v106, v114, v112
	v_sub_f32_e32 v105, v105, v103
	v_add_f32_e32 v111, v102, v105
	v_add_f32_e32 v102, v104, v106
	v_sub_f32_e32 v105, v103, v102
	v_pk_add_f32 v[108:109], v[102:103], v[104:105] neg_lo:[0,1] neg_hi:[0,1]
	v_mov_b32_e32 v107, v102
	v_pk_add_f32 v[102:103], v[108:109], v[106:107] neg_lo:[0,1] neg_hi:[0,1]
	v_cmp_neq_f32_e32 vcc, s36, v101
	v_add_f32_e32 v103, v111, v103
	v_add_f32_e32 v102, v102, v103
	v_add_f32_e32 v103, v115, v114
	v_add_f32_e32 v102, v105, v102
	v_sub_f32_e32 v104, v103, v115
	v_mul_f32_e32 v102, v113, v102
	v_sub_f32_e32 v104, v114, v104
	v_add_f32_e32 v104, v104, v102
	v_add_f32_e32 v106, v103, v104
	v_mul_f32_e32 v107, v106, v106
	v_fmamk_f32 v102, v107, 0x3e9b6dac, v172
	v_fmaak_f32 v143, v107, v102, 0x3f2aaada
	v_cvt_f32_i32_e32 v102, v110
	v_sub_f32_e32 v103, v106, v103
	v_sub_f32_e32 v103, v104, v103
	v_ldexp_f32 v108, v103, 1
	v_mul_f32_e32 v103, v106, v107
	v_ldexp_f32 v105, v106, 1
	v_pk_mul_f32 v[106:107], v[102:103], v[142:143]
	s_nop 0
	v_fma_f32 v104, v102, s18, -v106
	v_fmac_f32_e32 v104, 0xb102e308, v102
	v_pk_add_f32 v[102:103], v[106:107], v[104:105]
	s_mov_b32 s18, 0x33800000
	v_sub_f32_e32 v105, v103, v105
	v_sub_f32_e32 v105, v107, v105
	v_add_f32_e32 v109, v108, v105
	v_mov_b32_e32 v108, v106
	v_pk_add_f32 v[106:107], v[102:103], v[106:107] neg_lo:[0,1] neg_hi:[0,1]
	v_pk_add_f32 v[110:111], v[102:103], v[108:109]
	v_mov_b32_e32 v105, v102
	v_mov_b32_e32 v107, v111
	v_pk_add_f32 v[112:113], v[104:105], v[106:107] neg_lo:[0,1] neg_hi:[0,1]
	v_pk_add_f32 v[104:105], v[104:105], v[106:107]
	v_mov_b32_e32 v108, v109
	v_pk_add_f32 v[106:107], v[104:105], v[102:103] op_sel:[1,0] op_sel_hi:[0,1] neg_lo:[0,1] neg_hi:[0,1]
	v_pk_add_f32 v[114:115], v[110:111], v[106:107] op_sel_hi:[1,0] neg_lo:[0,1] neg_hi:[0,1]
	v_mov_b32_e32 v110, v111
	v_mov_b32_e32 v111, v105
	v_pk_mov_b32 v[106:107], v[102:103], v[106:107] op_sel:[1,0]
	v_mov_b32_e32 v109, v102
	v_pk_add_f32 v[106:107], v[110:111], v[106:107] neg_lo:[0,1] neg_hi:[0,1]
	v_mov_b32_e32 v114, v112
	v_pk_add_f32 v[102:103], v[108:109], v[106:107] neg_lo:[0,1] neg_hi:[0,1]
	v_mov_b32_e32 v113, v105
	v_pk_add_f32 v[106:107], v[114:115], v[102:103]
	s_nop 0
	v_pk_add_f32 v[108:109], v[106:107], v[106:107] op_sel:[0,1] op_sel_hi:[1,0]
	s_nop 0
	v_pk_add_f32 v[104:105], v[104:105], v[108:109] op_sel:[1,0] op_sel_hi:[0,1]
	v_mov_b32_e32 v107, v104
	v_pk_add_f32 v[110:111], v[106:107], v[112:113] neg_lo:[0,1] neg_hi:[0,1]
	v_mov_b32_e32 v103, v108
	v_sub_f32_e32 v105, v106, v110
	v_pk_add_f32 v[102:103], v[102:103], v[110:111] neg_lo:[0,1] neg_hi:[0,1]
	v_sub_f32_e32 v105, v112, v105
	v_add_f32_e32 v102, v102, v105
	v_add_f32_e32 v102, v102, v103
	v_add_f32_e32 v102, v104, v102
	v_cndmask_b32_e32 v102, v185, v102, vcc
	v_cmp_ngt_f32_e32 vcc, -1.0, v101
	s_nop 1
	v_cndmask_b32_e32 v102, v196, v102, vcc
	v_cmp_neq_f32_e32 vcc, -1.0, v101
	s_nop 1
	v_cndmask_b32_e32 v102, v197, v102, vcc
	v_cmp_lt_f32_e64 vcc, |v101|, s18
	s_nop 1
	v_cndmask_b32_e32 v101, v102, v101, vcc

.LBB0_1000:
	s_or_b64 exec, exec, s[0:1]
	v_lshlrev_b32_e32 v10, 16, v75
	v_cndmask_b32_e64 v11, 0, v10, s[56:57]
	v_lshlrev_b32_e32 v10, 16, v74
	v_mul_f32_e32 v75, v21, v78
	v_cndmask_b32_e64 v74, 0, v10, s[56:57]
	v_fmac_f32_e32 v75, v20, v14
	v_fmac_f32_e32 v75, v22, v74
	v_mul_f32_e32 v10, 0xbfb8aa3b, v75
	v_exp_f32_e32 v14, v10
	v_lshlrev_b32_e32 v10, 16, v73
	v_mul_f32_e32 v9, v16, v9
	v_mul_f32_e32 v15, v17, v13
	v_add_f32_e32 v73, 1.0, v14
	v_mul_f32_e32 v8, v18, v8
	v_mul_f32_e32 v14, v19, v12
	v_cndmask_b32_e64 v10, 0, v10, s[56:57]
	s_waitcnt vmcnt(39)
	v_div_scale_f32 v76, s[0:1], v73, v73, v75
	v_pk_add_f32 v[8:9], v[8:9], v[14:15]
	v_rcp_f32_e32 v77, v76
	v_pk_fma_f32 v[8:9], v[2:3], v[10:11], v[8:9]
	v_fma_f32 v79, -v76, v77, 1.0
	v_mul_f32_e32 v14, 0xbfb8aa3b, v9
	v_exp_f32_e32 v15, v14
	v_mul_f32_e32 v14, 0xbfb8aa3b, v8
	v_exp_f32_e32 v14, v14
	v_fmac_f32_e32 v77, v79, v77
	v_div_scale_f32 v79, vcc, v75, v73, v75
	v_mul_f32_e32 v80, v79, v77
	v_fma_f32 v81, -v76, v80, v79
	v_pk_add_f32 v[14:15], v[14:15], 1.0 op_sel_hi:[1,0]
	v_fmac_f32_e32 v80, v81, v77
	v_div_scale_f32 v81, s[0:1], v15, v15, v9
	v_rcp_f32_e32 v82, v81
	v_fma_f32 v76, -v76, v80, v79
	v_div_fmas_f32 v79, v76, v77, v80
	v_div_fixup_f32 v73, v79, v73, v75
	v_fma_f32 v76, -v81, v82, 1.0
	v_fmac_f32_e32 v82, v76, v82
	v_div_scale_f32 v76, vcc, v9, v15, v9
	v_mul_f32_e32 v77, v76, v82
	v_fma_f32 v80, -v81, v77, v76
	v_fmac_f32_e32 v77, v80, v82
	v_div_scale_f32 v80, s[0:1], v14, v14, v8
	v_fma_f32 v76, -v81, v77, v76
	v_rcp_f32_e32 v81, v80
	v_div_fmas_f32 v76, v76, v82, v77
	v_div_fixup_f32 v15, v76, v15, v9
	s_lshl_b64 s[0:1], s[4:5], 8
	v_fma_f32 v9, -v80, v81, 1.0
	v_fmac_f32_e32 v81, v9, v81
	v_div_scale_f32 v9, vcc, v8, v14, v8
	v_mul_f32_e32 v76, v9, v81
	v_fma_f32 v77, -v80, v76, v9
	v_fmac_f32_e32 v76, v77, v81
	v_fma_f32 v9, -v80, v76, v9
	v_div_fmas_f32 v9, v9, v81, v76
	v_div_fixup_f32 v14, v9, v14, v8
	v_pk_mul_f32 v[8:9], v[14:15], v[14:15]
	s_nop 1
	v_mov_b32_e32 v254, v9
	v_cmp_gt_u32_e64 s[98:99], 32, v176
	s_nop 0
	v_permlane32_swap_b32_e32 v9, v254
	v_cndmask_b32_e64 v9, v9, v254, s[98:99]
	s_nop 1
	v_mov_b32_e32 v254, v8
	v_cmp_gt_u32_e64 s[98:99], 32, v176
	s_nop 0
	v_permlane32_swap_b32_e32 v8, v254
	v_cndmask_b32_e64 v8, v8, v254, s[98:99]
	v_cvt_pk_bf16_f32 v73, v73, s0
	s_waitcnt lgkmcnt(0)
	v_pk_fma_f32 v[8:9], v[14:15], v[14:15], v[8:9]
	s_nop 1
	v_mov_b32_e32 v254, v9
	v_mov_b32_e32 v77, v9
	v_and_b32_e32 v255, 16, v176
	v_cmp_eq_u32_e64 s[98:99], 0, v255
	s_nop 0
	v_permlane16_swap_b32_e32 v77, v254
	v_cndmask_b32_e64 v77, v77, v254, s[98:99]
	s_nop 1
	v_mov_b32_e32 v254, v8
	v_mov_b32_e32 v76, v8
	v_and_b32_e32 v255, 16, v176
	v_cmp_eq_u32_e64 s[98:99], 0, v255
	s_nop 0
	v_permlane16_swap_b32_e32 v76, v254
	v_cndmask_b32_e64 v76, v76, v254, s[98:99]
	s_waitcnt lgkmcnt(0)
	v_pk_add_f32 v[8:9], v[8:9], v[76:77]
	s_nop 1
	v_mov_b32_dpp v77, v9 row_ror:8 row_mask:0xf bank_mask:0xf
	s_nop 1
	v_mov_b32_dpp v76, v8 row_ror:8 row_mask:0xf bank_mask:0xf
	s_waitcnt lgkmcnt(0)
	v_pk_add_f32 v[8:9], v[8:9], v[76:77]
	s_nop 1
	v_mov_b32_dpp v77, v9 row_shl:4 row_mask:0xf bank_mask:0x5
	v_mov_b32_dpp v77, v9 row_shr:4 row_mask:0xf bank_mask:0xa
	s_nop 1
	v_mov_b32_dpp v76, v8 row_shl:4 row_mask:0xf bank_mask:0x5
	v_mov_b32_dpp v76, v8 row_shr:4 row_mask:0xf bank_mask:0xa
	s_waitcnt lgkmcnt(0)
	v_pk_add_f32 v[8:9], v[8:9], v[76:77]
	s_nop 1
	v_mov_b32_dpp v77, v9 quad_perm:[2,3,0,1] row_mask:0xf bank_mask:0xf
	s_nop 1
	v_mov_b32_dpp v76, v8 quad_perm:[2,3,0,1] row_mask:0xf bank_mask:0xf
	s_waitcnt lgkmcnt(0)
	v_pk_add_f32 v[8:9], v[8:9], v[76:77]
	s_nop 1
	v_mov_b32_dpp v77, v9 quad_perm:[1,0,3,2] row_mask:0xf bank_mask:0xf
	s_nop 1
	v_mov_b32_dpp v76, v8 quad_perm:[1,0,3,2] row_mask:0xf bank_mask:0xf
	s_waitcnt lgkmcnt(0)
	v_pk_add_f32 v[8:9], v[8:9], v[76:77]
	s_nop 0
	v_pk_add_f32 v[76:77], v[8:9], s[22:23] op_sel_hi:[1,0]
	s_nop 0
	v_mul_f32_e32 v8, 0x4b800000, v77
	v_cmp_gt_f32_e32 vcc, s33, v77
	s_nop 1
	v_cndmask_b32_e32 v8, v77, v8, vcc
	v_rsq_f32_e32 v75, v8
	v_lshl_add_u64 v[8:9], s[0:1], 0, v[0:1]
	v_lshlrev_b64 v[80:81], 1, v[8:9]
	v_lshl_add_u64 v[82:83], s[78:79], 0, v[80:81]
	v_mul_f32_e32 v77, 0x45800000, v75
	v_cndmask_b32_e32 v75, v75, v77, vcc
	v_mul_f32_e32 v15, v15, v75
	v_mul_f32_e32 v75, 0x4b800000, v76
	v_cmp_gt_f32_e32 vcc, s33, v76
	v_mul_f32_e32 v15, 0x3e000000, v15
	v_cvt_pk_bf16_f32 v15, v15, s0
	v_cndmask_b32_e32 v75, v76, v75, vcc
	v_rsq_f32_e32 v75, v75
	global_store_short v[82:83], v15, off
	v_mul_f32_e32 v15, 0x45800000, v75
	v_cndmask_b32_e32 v15, v75, v15, vcc
	v_mul_f32_e32 v14, v14, v15
	v_cvt_pk_bf16_f32 v75, v14, s0
	v_lshl_add_u64 v[14:15], s[80:81], 0, v[80:81]
	global_store_short v[14:15], v75, off
	v_lshl_add_u64 v[14:15], s[82:83], 0, v[80:81]
	global_store_short v[14:15], v73, off
	s_and_saveexec_b64 s[0:1], s[38:39]
	s_cbranch_execz .LBB0_1004
	s_waitcnt vmcnt(41)
	v_lshlrev_b32_e32 v14, 16, v72
	v_mul_f32_e32 v14, 0xbfb8aa3b, v14
	v_exp_f32_e32 v14, v14
	v_mad_i64_i32 v[8:9], s[4:5], s4, v199, v[8:9]
	s_waitcnt vmcnt(40)
	v_lshlrev_b32_e32 v71, 16, v71
	v_add_f32_e32 v14, 1.0, v14
	v_div_scale_f32 v15, s[6:7], v14, v14, 1.0
	v_rcp_f32_e32 v72, v15
	v_div_scale_f32 v73, vcc, 1.0, v14, 1.0
	s_mov_b32 s4, 0x41a00000
	v_fma_f32 v75, -v15, v72, 1.0
	v_fmac_f32_e32 v72, v75, v72
	v_mul_f32_e32 v75, v73, v72
	v_fma_f32 v76, -v15, v75, v73
	v_fmac_f32_e32 v75, v76, v72
	v_fma_f32 v15, -v15, v75, v73
	v_div_fmas_f32 v15, v15, v72, v75
	v_div_fixup_f32 v72, v15, v14, 1.0
	v_lshl_add_u64 v[14:15], v[8:9], 2, s[84:85]
	global_store_dword v[14:15], v72, off
	v_add_f32_e32 v14, v24, v71
	v_cmp_nlt_f32_e32 vcc, s4, v14
	s_and_saveexec_b64 s[4:5], vcc
	s_cbranch_execz .LBB0_1003
	v_mul_f32_e32 v14, 0x3fb8aa3b, v14
	v_exp_f32_e32 v71, v14
	s_mov_b32 s6, 0x3f2aaaab
	v_add_f32_e32 v72, 1.0, v71
	v_frexp_mant_f32_e32 v75, v72
	v_cvt_f64_f32_e32 v[14:15], v72
	v_frexp_exp_i32_f64_e32 v14, v[14:15]
	v_cmp_gt_f32_e32 vcc, s6, v75
	v_add_f32_e32 v73, -1.0, v72
	v_sub_f32_e32 v76, v73, v72
	v_subbrev_co_u32_e32 v75, vcc, 0, v14, vcc
	v_sub_u32_e32 v14, 0, v75
	v_sub_f32_e32 v73, v71, v73
	v_add_f32_e32 v76, 1.0, v76
	v_ldexp_f32 v15, v72, v14
	v_add_f32_e32 v73, v73, v76
	v_add_f32_e32 v72, -1.0, v15
	v_add_f32_e32 v76, 1.0, v15
	v_ldexp_f32 v14, v73, v14
	v_add_f32_e32 v73, 1.0, v72
	v_add_f32_e32 v77, -1.0, v76
	v_sub_f32_e32 v73, v15, v73
	v_sub_f32_e32 v15, v15, v77
	v_add_f32_e32 v73, v14, v73
	v_add_f32_e32 v14, v14, v15
	v_add_f32_e32 v79, v76, v14
	v_rcp_f32_e32 v83, v79
	v_sub_f32_e32 v15, v79, v76
	v_sub_f32_e32 v82, v14, v15
	v_add_f32_e32 v15, v72, v73
	v_mul_f32_e32 v85, v15, v83
	v_sub_f32_e32 v14, v15, v72
	v_mul_f32_e32 v72, v79, v85
	v_fma_f32 v76, v85, v79, -v72
	v_fmac_f32_e32 v76, v85, v82
	v_sub_f32_e32 v84, v73, v14
	v_add_f32_e32 v14, v72, v76
	v_sub_f32_e32 v73, v15, v14
	v_pk_add_f32 v[80:81], v[14:15], v[72:73] neg_lo:[0,1] neg_hi:[0,1]
	v_mov_b32_e32 v77, v14
	v_pk_add_f32 v[14:15], v[80:81], v[76:77] neg_lo:[0,1] neg_hi:[0,1]
	s_mov_b32 s6, 0x3f317218
	v_add_f32_e32 v15, v84, v15
	v_add_f32_e32 v14, v14, v15
	v_add_f32_e32 v15, v73, v14
	v_mul_f32_e32 v84, v83, v15
	v_mul_f32_e32 v72, v79, v84
	v_fma_f32 v76, v84, v79, -v72
	v_fmac_f32_e32 v76, v84, v82
	v_sub_f32_e32 v73, v73, v15
	v_add_f32_e32 v79, v14, v73
	v_add_f32_e32 v14, v72, v76
	v_sub_f32_e32 v73, v15, v14
	v_pk_add_f32 v[80:81], v[14:15], v[72:73] neg_lo:[0,1] neg_hi:[0,1]
	v_mov_b32_e32 v77, v14
	v_pk_add_f32 v[14:15], v[80:81], v[76:77] neg_lo:[0,1] neg_hi:[0,1]
	v_cmp_neq_f32_e32 vcc, s36, v71
	v_add_f32_e32 v15, v79, v15
	v_add_f32_e32 v14, v14, v15
	v_add_f32_e32 v15, v85, v84
	v_add_f32_e32 v14, v73, v14
	v_sub_f32_e32 v72, v15, v85
	v_mul_f32_e32 v14, v83, v14
	v_sub_f32_e32 v72, v84, v72
	v_add_f32_e32 v72, v72, v14
	v_add_f32_e32 v76, v15, v72
	v_mul_f32_e32 v77, v76, v76
	v_fmamk_f32 v14, v77, 0x3e9b6dac, v172
	v_fmaak_f32 v143, v77, v14, 0x3f2aaada
	v_cvt_f32_i32_e32 v14, v75
	v_sub_f32_e32 v15, v76, v15
	v_sub_f32_e32 v15, v72, v15
	v_ldexp_f32 v75, v15, 1
	v_mul_f32_e32 v15, v76, v77
	v_ldexp_f32 v73, v76, 1
	v_pk_mul_f32 v[76:77], v[14:15], v[142:143]
	s_nop 0
	v_fma_f32 v72, v14, s6, -v76
	v_fmac_f32_e32 v72, 0xb102e308, v14
	v_pk_add_f32 v[14:15], v[76:77], v[72:73]
	v_mov_b32_e32 v80, v76
	v_sub_f32_e32 v73, v15, v73
	v_sub_f32_e32 v73, v77, v73
	v_add_f32_e32 v81, v75, v73
	v_pk_add_f32 v[76:77], v[14:15], v[76:77] neg_lo:[0,1] neg_hi:[0,1]
	v_pk_add_f32 v[82:83], v[14:15], v[80:81]
	v_mov_b32_e32 v73, v14
	v_mov_b32_e32 v77, v83
	v_pk_add_f32 v[84:85], v[72:73], v[76:77] neg_lo:[0,1] neg_hi:[0,1]
	v_pk_add_f32 v[72:73], v[72:73], v[76:77]
	v_mov_b32_e32 v80, v81
	v_pk_add_f32 v[76:77], v[72:73], v[14:15] op_sel:[1,0] op_sel_hi:[0,1] neg_lo:[0,1] neg_hi:[0,1]
	v_pk_add_f32 v[86:87], v[82:83], v[76:77] op_sel_hi:[1,0] neg_lo:[0,1] neg_hi:[0,1]
	v_mov_b32_e32 v82, v83
	v_mov_b32_e32 v83, v73
	v_pk_mov_b32 v[76:77], v[14:15], v[76:77] op_sel:[1,0]
	v_mov_b32_e32 v81, v14
	v_pk_add_f32 v[76:77], v[82:83], v[76:77] neg_lo:[0,1] neg_hi:[0,1]
	v_mov_b32_e32 v86, v84
	v_pk_add_f32 v[14:15], v[80:81], v[76:77] neg_lo:[0,1] neg_hi:[0,1]
	v_mov_b32_e32 v85, v73
	v_pk_add_f32 v[76:77], v[86:87], v[14:15]
	s_mov_b32 s6, 0x33800000
	v_pk_add_f32 v[80:81], v[76:77], v[76:77] op_sel:[0,1] op_sel_hi:[1,0]
	s_nop 0
	v_pk_add_f32 v[72:73], v[72:73], v[80:81] op_sel:[1,0] op_sel_hi:[0,1]
	v_mov_b32_e32 v77, v72
	v_pk_add_f32 v[82:83], v[76:77], v[84:85] neg_lo:[0,1] neg_hi:[0,1]
	v_mov_b32_e32 v15, v80
	v_sub_f32_e32 v73, v76, v82
	v_pk_add_f32 v[14:15], v[14:15], v[82:83] neg_lo:[0,1] neg_hi:[0,1]
	v_sub_f32_e32 v73, v84, v73
	v_add_f32_e32 v14, v14, v73
	v_add_f32_e32 v14, v14, v15
	v_add_f32_e32 v14, v72, v14
	v_cndmask_b32_e32 v14, v185, v14, vcc
	v_cmp_ngt_f32_e32 vcc, -1.0, v71
	s_nop 1
	v_cndmask_b32_e32 v14, v196, v14, vcc
	v_cmp_neq_f32_e32 vcc, -1.0, v71
	s_nop 1
	v_cndmask_b32_e32 v14, v197, v14, vcc
	v_cmp_lt_f32_e64 vcc, |v71|, s6
	s_nop 1
	v_cndmask_b32_e32 v14, v14, v71, vcc

.LBB0_1024:
	s_or_b64 exec, exec, s[0:1]
	v_lshlrev_b32_e32 v10, 16, v45
	v_cndmask_b32_e64 v11, 0, v10, s[44:45]
	v_lshlrev_b32_e32 v10, 16, v44
	v_mul_f32_e32 v49, v21, v48
	v_cndmask_b32_e64 v14, 0, v10, s[44:45]
	v_fmac_f32_e32 v49, v20, v15
	v_fmac_f32_e32 v49, v22, v14
	v_mul_f32_e32 v10, 0xbfb8aa3b, v49
	v_exp_f32_e32 v15, v10
	v_lshlrev_b32_e32 v10, 16, v43
	v_mul_f32_e32 v9, v16, v9
	v_mul_f32_e32 v45, v17, v13
	v_add_f32_e32 v15, 1.0, v15
	v_mul_f32_e32 v8, v18, v8
	v_mul_f32_e32 v44, v19, v12
	v_cndmask_b32_e64 v10, 0, v10, s[44:45]
	v_div_scale_f32 v43, s[0:1], v15, v15, v49
	v_pk_add_f32 v[8:9], v[8:9], v[44:45]
	s_waitcnt vmcnt(45)
	v_rcp_f32_e32 v46, v43
	v_pk_fma_f32 v[8:9], v[2:3], v[10:11], v[8:9]
	v_fma_f32 v47, -v43, v46, 1.0
	v_mul_f32_e32 v44, 0xbfb8aa3b, v9
	v_exp_f32_e32 v45, v44
	v_mul_f32_e32 v44, 0xbfb8aa3b, v8
	v_exp_f32_e32 v44, v44
	v_fmac_f32_e32 v46, v47, v46
	v_div_scale_f32 v47, vcc, v49, v15, v49
	v_mul_f32_e32 v50, v47, v46
	v_fma_f32 v51, -v43, v50, v47
	v_pk_add_f32 v[44:45], v[44:45], 1.0 op_sel_hi:[1,0]
	v_fmac_f32_e32 v50, v51, v46
	v_div_scale_f32 v51, s[0:1], v45, v45, v9
	v_rcp_f32_e32 v52, v51
	v_fma_f32 v43, -v43, v50, v47
	v_div_fmas_f32 v43, v43, v46, v50
	v_div_fixup_f32 v15, v43, v15, v49
	v_fma_f32 v46, -v51, v52, 1.0
	v_fmac_f32_e32 v52, v46, v52
	v_div_scale_f32 v46, vcc, v9, v45, v9
	v_mul_f32_e32 v47, v46, v52
	v_fma_f32 v50, -v51, v47, v46
	v_fmac_f32_e32 v47, v50, v52
	v_div_scale_f32 v50, s[0:1], v44, v44, v8
	v_fma_f32 v46, -v51, v47, v46
	v_rcp_f32_e32 v51, v50
	v_div_fmas_f32 v46, v46, v52, v47
	v_div_fixup_f32 v45, v46, v45, v9
	s_lshl_b64 s[0:1], s[24:25], 8
	v_fma_f32 v9, -v50, v51, 1.0
	v_fmac_f32_e32 v51, v9, v51
	v_div_scale_f32 v9, vcc, v8, v44, v8
	v_mul_f32_e32 v46, v9, v51
	v_fma_f32 v47, -v50, v46, v9
	v_fmac_f32_e32 v46, v47, v51
	v_fma_f32 v9, -v50, v46, v9
	v_div_fmas_f32 v9, v9, v51, v46
	v_div_fixup_f32 v44, v9, v44, v8
	v_pk_mul_f32 v[8:9], v[44:45], v[44:45]
	s_nop 1
	v_mov_b32_e32 v254, v9
	v_cmp_gt_u32_e64 s[98:99], 32, v176
	s_nop 0
	v_permlane32_swap_b32_e32 v9, v254
	v_cndmask_b32_e64 v9, v9, v254, s[98:99]
	s_nop 1
	v_mov_b32_e32 v254, v8
	v_cmp_gt_u32_e64 s[98:99], 32, v176
	s_nop 0
	v_permlane32_swap_b32_e32 v8, v254
	v_cndmask_b32_e64 v8, v8, v254, s[98:99]
	v_cvt_pk_bf16_f32 v15, v15, s0
	s_waitcnt lgkmcnt(0)
	v_pk_fma_f32 v[8:9], v[44:45], v[44:45], v[8:9]
	s_nop 1
	v_mov_b32_e32 v254, v9
	v_mov_b32_e32 v47, v9
	v_and_b32_e32 v255, 16, v176
	v_cmp_eq_u32_e64 s[98:99], 0, v255
	s_nop 0
	v_permlane16_swap_b32_e32 v47, v254
	v_cndmask_b32_e64 v47, v47, v254, s[98:99]
	s_nop 1
	v_mov_b32_e32 v254, v8
	v_mov_b32_e32 v46, v8
	v_and_b32_e32 v255, 16, v176
	v_cmp_eq_u32_e64 s[98:99], 0, v255
	s_nop 0
	v_permlane16_swap_b32_e32 v46, v254
	v_cndmask_b32_e64 v46, v46, v254, s[98:99]
	s_waitcnt lgkmcnt(0)
	v_pk_add_f32 v[8:9], v[8:9], v[46:47]
	s_nop 1
	v_mov_b32_dpp v47, v9 row_ror:8 row_mask:0xf bank_mask:0xf
	s_nop 1
	v_mov_b32_dpp v46, v8 row_ror:8 row_mask:0xf bank_mask:0xf
	s_waitcnt lgkmcnt(0)
	v_pk_add_f32 v[8:9], v[8:9], v[46:47]
	s_nop 1
	v_mov_b32_dpp v47, v9 row_shl:4 row_mask:0xf bank_mask:0x5
	v_mov_b32_dpp v47, v9 row_shr:4 row_mask:0xf bank_mask:0xa
	s_nop 1
	v_mov_b32_dpp v46, v8 row_shl:4 row_mask:0xf bank_mask:0x5
	v_mov_b32_dpp v46, v8 row_shr:4 row_mask:0xf bank_mask:0xa
	s_waitcnt lgkmcnt(0)
	v_pk_add_f32 v[8:9], v[8:9], v[46:47]
	s_nop 1
	v_mov_b32_dpp v47, v9 quad_perm:[2,3,0,1] row_mask:0xf bank_mask:0xf
	s_nop 1
	v_mov_b32_dpp v46, v8 quad_perm:[2,3,0,1] row_mask:0xf bank_mask:0xf
	s_waitcnt lgkmcnt(0)
	v_pk_add_f32 v[8:9], v[8:9], v[46:47]
	s_nop 1
	v_mov_b32_dpp v47, v9 quad_perm:[1,0,3,2] row_mask:0xf bank_mask:0xf
	s_nop 1
	v_mov_b32_dpp v46, v8 quad_perm:[1,0,3,2] row_mask:0xf bank_mask:0xf
	s_waitcnt lgkmcnt(0)
	v_pk_add_f32 v[8:9], v[8:9], v[46:47]
	s_nop 0
	v_pk_add_f32 v[46:47], v[8:9], s[22:23] op_sel_hi:[1,0]
	s_nop 0
	v_mul_f32_e32 v8, 0x4b800000, v47
	v_cmp_gt_f32_e32 vcc, s33, v47
	s_nop 1
	v_cndmask_b32_e32 v8, v47, v8, vcc
	v_rsq_f32_e32 v43, v8
	v_lshl_add_u64 v[8:9], s[0:1], 0, v[0:1]
	v_lshlrev_b64 v[50:51], 1, v[8:9]
	v_lshl_add_u64 v[52:53], s[78:79], 0, v[50:51]
	v_mul_f32_e32 v47, 0x45800000, v43
	v_cndmask_b32_e32 v43, v43, v47, vcc
	v_mul_f32_e32 v43, v45, v43
	v_mul_f32_e32 v45, 0x4b800000, v46
	v_cmp_gt_f32_e32 vcc, s33, v46
	v_mul_f32_e32 v43, 0x3e000000, v43
	v_cvt_pk_bf16_f32 v43, v43, s0
	v_cndmask_b32_e32 v45, v46, v45, vcc
	v_rsq_f32_e32 v45, v45
	global_store_short v[52:53], v43, off
	v_mul_f32_e32 v43, 0x45800000, v45
	v_cndmask_b32_e32 v43, v45, v43, vcc
	v_mul_f32_e32 v43, v44, v43
	v_cvt_pk_bf16_f32 v43, v43, s0
	v_lshl_add_u64 v[44:45], s[80:81], 0, v[50:51]
	global_store_short v[44:45], v43, off
	v_lshl_add_u64 v[44:45], s[82:83], 0, v[50:51]
	global_store_short v[44:45], v15, off
	s_and_saveexec_b64 s[0:1], s[38:39]
	s_cbranch_execz .LBB0_1028
	s_waitcnt vmcnt(47)
	v_lshlrev_b32_e32 v15, 16, v42
	v_mul_f32_e32 v15, 0xbfb8aa3b, v15
	v_exp_f32_e32 v15, v15
	v_mad_i64_i32 v[8:9], s[2:3], s24, v199, v[8:9]
	s_waitcnt vmcnt(46)
	v_lshlrev_b32_e32 v41, 16, v41
	v_add_f32_e32 v15, 1.0, v15
	v_div_scale_f32 v42, s[2:3], v15, v15, 1.0
	v_rcp_f32_e32 v43, v42
	v_div_scale_f32 v44, vcc, 1.0, v15, 1.0
	s_mov_b32 s2, 0x41a00000
	v_fma_f32 v45, -v42, v43, 1.0
	v_fmac_f32_e32 v43, v45, v43
	v_mul_f32_e32 v45, v44, v43
	v_fma_f32 v46, -v42, v45, v44
	v_fmac_f32_e32 v45, v46, v43
	v_fma_f32 v42, -v42, v45, v44
	v_div_fmas_f32 v42, v42, v43, v45
	v_div_fixup_f32 v15, v42, v15, 1.0
	v_lshl_add_u64 v[42:43], v[8:9], 2, s[84:85]
	global_store_dword v[42:43], v15, off
	v_add_f32_e32 v15, v24, v41
	v_cmp_nlt_f32_e32 vcc, s2, v15
	s_and_saveexec_b64 s[2:3], vcc
	s_cbranch_execz .LBB0_1027
	v_mul_f32_e32 v15, 0x3fb8aa3b, v15
	v_exp_f32_e32 v15, v15
	s_mov_b32 s4, 0x3f2aaaab
	v_add_f32_e32 v41, 1.0, v15
	v_frexp_mant_f32_e32 v45, v41
	v_cvt_f64_f32_e32 v[42:43], v41
	v_add_f32_e32 v44, -1.0, v41
	v_frexp_exp_i32_f64_e32 v42, v[42:43]
	v_cmp_gt_f32_e32 vcc, s4, v45
	v_sub_f32_e32 v46, v44, v41
	v_sub_f32_e32 v44, v15, v44
	v_subbrev_co_u32_e32 v49, vcc, 0, v42, vcc
	v_add_f32_e32 v46, 1.0, v46
	v_sub_u32_e32 v42, 0, v49
	v_add_f32_e32 v44, v44, v46
	v_ldexp_f32 v41, v41, v42
	v_ldexp_f32 v42, v44, v42
	v_add_f32_e32 v44, -1.0, v41
	v_add_f32_e32 v43, 1.0, v44
	v_sub_f32_e32 v43, v41, v43
	v_add_f32_e32 v45, v42, v43
	v_add_f32_e32 v43, 1.0, v41
	v_add_f32_e32 v46, -1.0, v43
	v_sub_f32_e32 v41, v41, v46
	v_add_f32_e32 v41, v42, v41
	v_add_f32_e32 v52, v43, v41
	v_rcp_f32_e32 v53, v52
	v_sub_f32_e32 v42, v52, v43
	v_add_f32_e32 v43, v44, v45
	v_sub_f32_e32 v41, v41, v42
	v_mul_f32_e32 v55, v43, v53
	v_sub_f32_e32 v42, v43, v44
	v_mul_f32_e32 v44, v52, v55
	v_fma_f32 v46, v55, v52, -v44
	v_fmac_f32_e32 v46, v55, v41
	v_sub_f32_e32 v54, v45, v42
	v_add_f32_e32 v42, v44, v46
	v_sub_f32_e32 v45, v43, v42
	v_pk_add_f32 v[50:51], v[42:43], v[44:45] neg_lo:[0,1] neg_hi:[0,1]
	v_mov_b32_e32 v47, v42
	v_pk_add_f32 v[42:43], v[50:51], v[46:47] neg_lo:[0,1] neg_hi:[0,1]
	s_mov_b32 s4, 0x3f317218
	v_add_f32_e32 v43, v54, v43
	v_add_f32_e32 v42, v42, v43
	v_add_f32_e32 v43, v45, v42
	v_mul_f32_e32 v54, v53, v43
	v_mul_f32_e32 v44, v52, v54
	v_fma_f32 v46, v54, v52, -v44
	v_fmac_f32_e32 v46, v54, v41
	v_sub_f32_e32 v41, v45, v43
	v_add_f32_e32 v41, v42, v41
	v_add_f32_e32 v42, v44, v46
	v_sub_f32_e32 v45, v43, v42
	v_pk_add_f32 v[50:51], v[42:43], v[44:45] neg_lo:[0,1] neg_hi:[0,1]
	v_mov_b32_e32 v47, v42
	v_pk_add_f32 v[42:43], v[50:51], v[46:47] neg_lo:[0,1] neg_hi:[0,1]
	v_cmp_neq_f32_e32 vcc, s36, v15
	v_add_f32_e32 v41, v41, v43
	v_add_f32_e32 v41, v42, v41
	v_add_f32_e32 v43, v55, v54
	v_add_f32_e32 v41, v45, v41
	v_sub_f32_e32 v42, v43, v55
	v_mul_f32_e32 v41, v53, v41
	v_sub_f32_e32 v42, v54, v42
	v_add_f32_e32 v41, v42, v41
	v_add_f32_e32 v44, v43, v41
	v_mul_f32_e32 v46, v44, v44
	v_fmamk_f32 v42, v46, 0x3e9b6dac, v172
	v_fmaak_f32 v143, v46, v42, 0x3f2aaada
	v_cvt_f32_i32_e32 v42, v49
	v_sub_f32_e32 v43, v44, v43
	v_sub_f32_e32 v41, v41, v43
	v_mul_f32_e32 v43, v44, v46
	v_pk_mul_f32 v[46:47], v[42:43], v[142:143]
	v_ldexp_f32 v45, v44, 1
	v_fma_f32 v44, v42, s4, -v46
	v_fmac_f32_e32 v44, 0xb102e308, v42
	v_pk_add_f32 v[42:43], v[46:47], v[44:45]
	v_ldexp_f32 v41, v41, 1
	v_sub_f32_e32 v45, v43, v45
	v_sub_f32_e32 v45, v47, v45
	v_add_f32_e32 v51, v41, v45
	v_mov_b32_e32 v50, v46
	v_pk_add_f32 v[46:47], v[42:43], v[46:47] neg_lo:[0,1] neg_hi:[0,1]
	v_pk_add_f32 v[52:53], v[42:43], v[50:51]
	v_mov_b32_e32 v45, v42
	v_mov_b32_e32 v47, v53
	v_pk_add_f32 v[54:55], v[44:45], v[46:47] neg_lo:[0,1] neg_hi:[0,1]
	v_pk_add_f32 v[44:45], v[44:45], v[46:47]
	v_mov_b32_e32 v50, v51
	v_pk_add_f32 v[46:47], v[44:45], v[42:43] op_sel:[1,0] op_sel_hi:[0,1] neg_lo:[0,1] neg_hi:[0,1]
	v_pk_add_f32 v[56:57], v[52:53], v[46:47] op_sel_hi:[1,0] neg_lo:[0,1] neg_hi:[0,1]
	v_mov_b32_e32 v52, v53
	v_mov_b32_e32 v53, v45
	v_pk_mov_b32 v[46:47], v[42:43], v[46:47] op_sel:[1,0]
	v_mov_b32_e32 v51, v42
	v_pk_add_f32 v[46:47], v[52:53], v[46:47] neg_lo:[0,1] neg_hi:[0,1]
	v_mov_b32_e32 v56, v54
	v_pk_add_f32 v[42:43], v[50:51], v[46:47] neg_lo:[0,1] neg_hi:[0,1]
	v_mov_b32_e32 v55, v45
	v_pk_add_f32 v[46:47], v[56:57], v[42:43]
	s_mov_b32 s4, 0x33800000
	v_pk_add_f32 v[50:51], v[46:47], v[46:47] op_sel:[0,1] op_sel_hi:[1,0]
	s_nop 0
	v_pk_add_f32 v[44:45], v[44:45], v[50:51] op_sel:[1,0] op_sel_hi:[0,1]
	v_mov_b32_e32 v47, v44
	v_pk_add_f32 v[52:53], v[46:47], v[54:55] neg_lo:[0,1] neg_hi:[0,1]
	v_mov_b32_e32 v43, v50
	v_sub_f32_e32 v41, v46, v52
	v_pk_add_f32 v[42:43], v[42:43], v[52:53] neg_lo:[0,1] neg_hi:[0,1]
	v_sub_f32_e32 v41, v54, v41
	v_add_f32_e32 v41, v42, v41
	v_add_f32_e32 v41, v41, v43
	v_add_f32_e32 v41, v44, v41
	v_cndmask_b32_e32 v41, v185, v41, vcc
	v_cmp_ngt_f32_e32 vcc, -1.0, v15
	s_nop 1
	v_cndmask_b32_e32 v41, v196, v41, vcc
	v_cmp_neq_f32_e32 vcc, -1.0, v15
	s_nop 1
	v_cndmask_b32_e32 v41, v197, v41, vcc
	v_cmp_lt_f32_e64 vcc, |v15|, s4
	s_nop 1
	v_cndmask_b32_e32 v15, v41, v15, vcc

.LBB0_1056:
	v_mov_b32_e32 v0, v139
	v_cmp_lt_i32_e32 vcc, v179, v178
	v_ashrrev_i32_e32 v1, 5, v0
	v_and_b32_e32 v1, -2, v1
	v_add_u32_e32 v38, s11, v1
	v_lshlrev_b32_e32 v0, 2, v0
	v_ashrrev_i32_e32 v39, 31, v38
	s_waitcnt lgkmcnt(0)
	v_and_b32_e32 v2, 0xfc, v0
	v_lshlrev_b64 v[0:1], 12, v[38:39]
	v_lshl_add_u64 v[0:1], s[46:47], 0, v[0:1]
	v_lshlrev_b32_e32 v136, 1, v2
	v_lshl_add_u64 v[36:37], v[0:1], 0, v[136:137]
	global_load_dwordx2 v[42:43], v[36:37], off offset:2048
	global_load_dwordx2 v[44:45], v[36:37], off offset:2560
	global_load_dwordx2 v[46:47], v[36:37], off offset:3072
	global_load_dwordx2 v[48:49], v[36:37], off offset:3584
	s_waitcnt vmcnt(12)
	v_add_u32_e32 v34, 1, v38
	v_ashrrev_i32_e32 v35, 31, v34
	v_lshlrev_b64 v[0:1], 12, v[34:35]
	v_lshl_add_u64 v[0:1], s[46:47], 0, v[0:1]
	v_lshl_add_u64 v[32:33], v[0:1], 0, v[136:137]
	global_load_dwordx2 v[50:51], v[32:33], off offset:2048
	global_load_dwordx2 v[52:53], v[32:33], off offset:2560
	global_load_dwordx2 v[54:55], v[32:33], off offset:3072
	global_load_dwordx2 v[56:57], v[32:33], off offset:3584
	v_cndmask_b32_e32 v35, v176, v179, vcc
	v_cmp_lt_i32_e32 vcc, v180, v178
	v_lshlrev_b32_e32 v35, 2, v35
	v_lshlrev_b32_e32 v40, 2, v2
	v_cndmask_b32_e32 v39, v176, v180, vcc
	v_cmp_lt_i32_e32 vcc, v181, v178
	v_lshlrev_b32_e32 v39, 2, v39
	global_load_dwordx4 v[24:27], v40, s[4:5]
	global_load_dwordx4 v[28:31], v40, s[6:7]
	global_load_dwordx4 v[16:19], v40, s[4:5] offset:1024
	global_load_dwordx4 v[20:23], v40, s[6:7] offset:1024
	global_load_dwordx4 v[8:11], v40, s[4:5] offset:2048
	global_load_dwordx4 v[12:15], v40, s[6:7] offset:2048
	global_load_dwordx4 v[0:3], v40, s[4:5] offset:3072
	global_load_dwordx4 v[4:7], v40, s[6:7] offset:3072
	v_cndmask_b32_e32 v58, v176, v181, vcc
	v_cmp_lt_i32_e32 vcc, v182, v178
	v_lshlrev_b32_e32 v86, 2, v58
	v_mov_b32_e32 v41, v137
	v_cndmask_b32_e32 v58, v176, v182, vcc
	v_cmp_lt_i32_e32 vcc, v183, v178
	v_lshlrev_b32_e32 v87, 2, v58
	s_add_i32 s12, s12, s90
	v_cndmask_b32_e32 v58, v176, v183, vcc
	v_cmp_lt_i32_e32 vcc, v184, v178
	v_lshlrev_b32_e32 v88, 2, v58
	s_add_i32 s11, s11, s10
	v_cndmask_b32_e32 v58, v176, v184, vcc
	v_lshlrev_b32_e32 v89, 2, v58
	s_cmpk_gt_i32 s12, 0xbf
	s_waitcnt vmcnt(15)
	v_lshlrev_b32_e32 v68, 16, v42
	s_waitcnt vmcnt(14)
	v_lshlrev_b32_e32 v66, 16, v44
	s_waitcnt vmcnt(13)
	v_lshlrev_b32_e32 v62, 16, v46
	s_waitcnt vmcnt(12)
	v_lshlrev_b32_e32 v60, 16, v48
	v_and_b32_e32 v61, 0xffff0000, v48
	v_and_b32_e32 v63, 0xffff0000, v46
	v_lshlrev_b32_e32 v58, 16, v49
	v_and_b32_e32 v59, 0xffff0000, v49
	v_lshlrev_b32_e32 v48, 16, v47
	v_and_b32_e32 v49, 0xffff0000, v47
	v_mov_b32_e32 v46, v62
	v_mov_b32_e32 v47, v60
	v_mov_b32_e32 v64, v63
	v_mov_b32_e32 v65, v61
	v_pk_add_f32 v[46:47], v[46:47], v[64:65]
	v_mov_b32_e32 v64, v48
	v_mov_b32_e32 v65, v58
	v_pk_add_f32 v[46:47], v[46:47], v[64:65]
	v_mov_b32_e32 v64, v49
	v_mov_b32_e32 v65, v59
	v_and_b32_e32 v67, 0xffff0000, v44
	v_and_b32_e32 v69, 0xffff0000, v42
	v_pk_add_f32 v[46:47], v[46:47], v[64:65]
	v_lshlrev_b32_e32 v64, 16, v45
	v_and_b32_e32 v65, 0xffff0000, v45
	v_lshlrev_b32_e32 v44, 16, v43
	v_and_b32_e32 v45, 0xffff0000, v43
	v_mov_b32_e32 v42, v68
	v_mov_b32_e32 v43, v66
	v_mov_b32_e32 v70, v69
	v_mov_b32_e32 v71, v67
	v_pk_add_f32 v[42:43], v[42:43], v[70:71]
	v_mov_b32_e32 v70, v44
	v_mov_b32_e32 v71, v64
	v_pk_add_f32 v[42:43], v[42:43], v[70:71]
	v_mov_b32_e32 v70, v45
	v_mov_b32_e32 v71, v65
	s_waitcnt vmcnt(8)
	v_lshlrev_b32_e32 v72, 16, v56
	v_and_b32_e32 v73, 0xffff0000, v56
	v_lshlrev_b32_e32 v74, 16, v54
	v_and_b32_e32 v75, 0xffff0000, v54
	v_pk_add_f32 v[42:43], v[42:43], v[70:71]
	v_lshlrev_b32_e32 v70, 16, v57
	v_and_b32_e32 v71, 0xffff0000, v57
	v_lshlrev_b32_e32 v56, 16, v55
	v_and_b32_e32 v57, 0xffff0000, v55
	v_mov_b32_e32 v54, v74
	v_mov_b32_e32 v55, v72
	v_mov_b32_e32 v76, v75
	v_mov_b32_e32 v77, v73
	v_pk_add_f32 v[54:55], v[54:55], v[76:77]
	v_mov_b32_e32 v76, v56
	v_mov_b32_e32 v77, v70
	v_pk_add_f32 v[54:55], v[54:55], v[76:77]
	v_mov_b32_e32 v76, v57
	v_mov_b32_e32 v77, v71
	v_lshlrev_b32_e32 v78, 16, v52
	v_and_b32_e32 v79, 0xffff0000, v52
	v_lshlrev_b32_e32 v80, 16, v50
	v_and_b32_e32 v81, 0xffff0000, v50
	v_pk_add_f32 v[54:55], v[54:55], v[76:77]
	v_lshlrev_b32_e32 v76, 16, v53
	v_and_b32_e32 v77, 0xffff0000, v53
	v_lshlrev_b32_e32 v52, 16, v51
	v_and_b32_e32 v53, 0xffff0000, v51
	v_mov_b32_e32 v50, v80
	v_mov_b32_e32 v51, v78
	v_mov_b32_e32 v82, v81
	v_mov_b32_e32 v83, v79
	v_pk_add_f32 v[50:51], v[50:51], v[82:83]
	v_mov_b32_e32 v82, v52
	v_mov_b32_e32 v83, v76
	v_pk_add_f32 v[50:51], v[50:51], v[82:83]
	v_mov_b32_e32 v82, v53
	v_mov_b32_e32 v83, v77
	v_pk_add_f32 v[50:51], v[50:51], v[82:83]
	v_add_f32_e32 v42, 0, v42
	v_add_f32_e32 v50, 0, v50
	v_add_f32_e32 v42, v42, v43
	v_add_f32_e32 v50, v50, v51
	v_add_f32_e32 v42, v42, v46
	v_add_f32_e32 v50, v50, v54
	v_add_f32_e32 v42, v42, v47
	v_add_f32_e32 v50, v50, v55
	s_nop 1
	v_mov_b32_e32 v254, v42
	v_mov_b32_e32 v43, v42
	v_cmp_gt_u32_e64 s[98:99], 32, v176
	s_nop 0
	v_permlane32_swap_b32_e32 v43, v254
	v_cndmask_b32_e64 v43, v43, v254, s[98:99]
	s_nop 1
	v_mov_b32_e32 v254, v50
	v_mov_b32_e32 v51, v50
	v_cmp_gt_u32_e64 s[98:99], 32, v176
	s_nop 0
	v_permlane32_swap_b32_e32 v51, v254
	v_cndmask_b32_e64 v51, v51, v254, s[98:99]
	s_waitcnt lgkmcnt(1)
	v_add_f32_e32 v42, v42, v43
	s_waitcnt lgkmcnt(0)
	v_add_f32_e32 v50, v50, v51
	s_nop 1
	v_mov_b32_e32 v254, v42
	v_mov_b32_e32 v43, v42
	v_and_b32_e32 v255, 16, v176
	v_cmp_eq_u32_e64 s[98:99], 0, v255
	s_nop 0
	v_permlane16_swap_b32_e32 v43, v254
	v_cndmask_b32_e64 v43, v43, v254, s[98:99]
	s_nop 1
	v_mov_b32_e32 v254, v50
	v_mov_b32_e32 v51, v50
	v_and_b32_e32 v255, 16, v176
	v_cmp_eq_u32_e64 s[98:99], 0, v255
	s_nop 0
	v_permlane16_swap_b32_e32 v51, v254
	v_cndmask_b32_e64 v51, v51, v254, s[98:99]
	s_waitcnt lgkmcnt(1)
	v_add_f32_e32 v42, v42, v43
	s_waitcnt lgkmcnt(0)
	v_add_f32_e32 v50, v50, v51
	s_nop 1
	v_mov_b32_dpp v43, v42 row_ror:8 row_mask:0xf bank_mask:0xf
	s_nop 1
	v_mov_b32_dpp v51, v50 row_ror:8 row_mask:0xf bank_mask:0xf
	s_waitcnt lgkmcnt(1)
	v_add_f32_e32 v42, v42, v43
	s_waitcnt lgkmcnt(0)
	v_add_f32_e32 v50, v50, v51
	s_nop 1
	v_mov_b32_dpp v43, v42 row_shl:4 row_mask:0xf bank_mask:0x5
	v_mov_b32_dpp v43, v42 row_shr:4 row_mask:0xf bank_mask:0xa
	s_nop 1
	v_mov_b32_dpp v51, v50 row_shl:4 row_mask:0xf bank_mask:0x5
	v_mov_b32_dpp v51, v50 row_shr:4 row_mask:0xf bank_mask:0xa
	s_waitcnt lgkmcnt(1)
	v_add_f32_e32 v42, v42, v43
	s_waitcnt lgkmcnt(0)
	v_add_f32_e32 v50, v50, v51
	s_nop 1
	v_mov_b32_dpp v43, v42 quad_perm:[2,3,0,1] row_mask:0xf bank_mask:0xf
	s_nop 1
	v_mov_b32_dpp v51, v50 quad_perm:[2,3,0,1] row_mask:0xf bank_mask:0xf
	s_waitcnt lgkmcnt(1)
	v_add_f32_e32 v42, v42, v43
	s_waitcnt lgkmcnt(0)
	v_add_f32_e32 v50, v50, v51
	s_nop 1
	v_mov_b32_dpp v43, v42 quad_perm:[1,0,3,2] row_mask:0xf bank_mask:0xf
	s_nop 1
	v_mov_b32_dpp v51, v50 quad_perm:[1,0,3,2] row_mask:0xf bank_mask:0xf
	s_waitcnt lgkmcnt(1)
	v_add_f32_e32 v42, v42, v43
	s_waitcnt lgkmcnt(0)
	v_add_f32_e32 v50, v50, v51
	v_mul_f32_e32 v42, 0x3a800000, v42
	v_mul_f32_e32 v50, 0x3a800000, v50
	v_pk_add_f32 v[46:47], v[68:69], v[42:43] op_sel_hi:[1,0] neg_lo:[0,1] neg_hi:[0,1]
	v_pk_add_f32 v[80:81], v[80:81], v[50:51] op_sel_hi:[1,0] neg_lo:[0,1] neg_hi:[0,1]
	v_mov_b32_e32 v83, v47
	v_mov_b32_e32 v82, v81
	v_mov_b32_e32 v54, v80
	v_mov_b32_e32 v55, v46
	v_pk_mul_f32 v[82:83], v[82:83], v[82:83]
	v_pk_add_f32 v[44:45], v[44:45], v[42:43] op_sel_hi:[1,0] neg_lo:[0,1] neg_hi:[0,1]
	v_pk_fma_f32 v[54:55], v[54:55], v[54:55], v[82:83]
	v_pk_add_f32 v[82:83], v[52:53], v[50:51] op_sel_hi:[1,0] neg_lo:[0,1] neg_hi:[0,1]
	v_mov_b32_e32 v53, v44
	v_mov_b32_e32 v52, v82
	v_pk_add_f32 v[66:67], v[66:67], v[42:43] op_sel_hi:[1,0] neg_lo:[0,1] neg_hi:[0,1]
	v_pk_add_f32 v[78:79], v[78:79], v[50:51] op_sel_hi:[1,0] neg_lo:[0,1] neg_hi:[0,1]
	v_pk_fma_f32 v[52:53], v[52:53], v[52:53], v[54:55]
	v_mov_b32_e32 v54, v83
	v_mov_b32_e32 v55, v45
	v_pk_fma_f32 v[52:53], v[54:55], v[54:55], v[52:53]
	v_mov_b32_e32 v54, v78
	v_mov_b32_e32 v55, v66
	v_pk_add_f32 v[64:65], v[64:65], v[42:43] op_sel_hi:[1,0] neg_lo:[0,1] neg_hi:[0,1]
	v_pk_add_f32 v[76:77], v[76:77], v[50:51] op_sel_hi:[1,0] neg_lo:[0,1] neg_hi:[0,1]
	v_pk_fma_f32 v[52:53], v[54:55], v[54:55], v[52:53]
	v_mov_b32_e32 v54, v79
	v_mov_b32_e32 v55, v67
	v_pk_fma_f32 v[52:53], v[54:55], v[54:55], v[52:53]
	v_mov_b32_e32 v54, v76
	v_mov_b32_e32 v55, v64
	v_pk_add_f32 v[62:63], v[62:63], v[42:43] op_sel_hi:[1,0] neg_lo:[0,1] neg_hi:[0,1]
	v_pk_add_f32 v[74:75], v[74:75], v[50:51] op_sel_hi:[1,0] neg_lo:[0,1] neg_hi:[0,1]
	v_pk_fma_f32 v[52:53], v[54:55], v[54:55], v[52:53]
	v_mov_b32_e32 v54, v77
	v_mov_b32_e32 v55, v65
	v_pk_fma_f32 v[52:53], v[54:55], v[54:55], v[52:53]
	v_mov_b32_e32 v54, v74
	v_mov_b32_e32 v55, v62
	v_pk_add_f32 v[68:69], v[48:49], v[42:43] op_sel_hi:[1,0] neg_lo:[0,1] neg_hi:[0,1]
	v_pk_add_f32 v[84:85], v[56:57], v[50:51] op_sel_hi:[1,0] neg_lo:[0,1] neg_hi:[0,1]
	v_pk_fma_f32 v[52:53], v[54:55], v[54:55], v[52:53]
	v_mov_b32_e32 v54, v75
	v_mov_b32_e32 v55, v63
	v_pk_add_f32 v[60:61], v[60:61], v[42:43] op_sel_hi:[1,0] neg_lo:[0,1] neg_hi:[0,1]
	v_pk_add_f32 v[72:73], v[72:73], v[50:51] op_sel_hi:[1,0] neg_lo:[0,1] neg_hi:[0,1]
	v_pk_fma_f32 v[52:53], v[54:55], v[54:55], v[52:53]
	v_mov_b32_e32 v54, v84
	v_mov_b32_e32 v55, v68
	v_pk_mul_f32 v[48:49], v[60:61], v[60:61]
	v_pk_mul_f32 v[56:57], v[72:73], v[72:73]
	v_pk_fma_f32 v[52:53], v[54:55], v[54:55], v[52:53]
	v_mov_b32_e32 v54, v85
	v_mov_b32_e32 v55, v69
	v_pk_add_f32 v[42:43], v[58:59], v[42:43] op_sel_hi:[1,0] neg_lo:[0,1] neg_hi:[0,1]
	v_pk_fma_f32 v[52:53], v[54:55], v[54:55], v[52:53]
	v_mov_b32_e32 v54, v56
	v_mov_b32_e32 v55, v48
	v_pk_add_f32 v[70:71], v[70:71], v[50:51] op_sel_hi:[1,0] neg_lo:[0,1] neg_hi:[0,1]
	v_pk_mul_f32 v[58:59], v[42:43], v[42:43]
	v_pk_add_f32 v[52:53], v[54:55], v[52:53]
	v_pk_mul_f32 v[50:51], v[70:71], v[70:71]
	v_mov_b32_e32 v48, v57
	v_pk_add_f32 v[48:49], v[48:49], v[52:53]
	v_mov_b32_e32 v52, v50
	v_mov_b32_e32 v53, v58
	v_pk_add_f32 v[48:49], v[52:53], v[48:49]
	v_mov_b32_e32 v58, v51
	v_pk_add_f32 v[48:49], v[58:59], v[48:49]
	v_mov_b32_e32 v50, v48
	v_mov_b32_e32 v51, v49
	s_nop 1
	v_permlane32_swap_b32_e32 v50, v48
	v_permlane32_swap_b32_e32 v51, v49
	v_pk_add_f32 v[48:49], v[48:49], v[50:51]
	v_mov_b32_e32 v50, v48
	v_mov_b32_e32 v51, v49
	s_nop 1
	v_permlane16_swap_b32_e32 v50, v48
	v_permlane16_swap_b32_e32 v51, v49
	v_pk_add_f32 v[48:49], v[48:49], v[50:51]
	s_nop 1
	v_add_f32_dpp v48, v48, v48 row_ror:8 row_mask:0xf bank_mask:0xf
	v_add_f32_dpp v49, v49, v49 row_ror:8 row_mask:0xf bank_mask:0xf
	s_nop 0
	v_add_f32_dpp v48, v48, v48 row_ror:4 row_mask:0xf bank_mask:0xf
	v_add_f32_dpp v49, v49, v49 row_ror:4 row_mask:0xf bank_mask:0xf
	s_nop 0
	v_add_f32_dpp v48, v48, v48 row_ror:2 row_mask:0xf bank_mask:0xf
	v_add_f32_dpp v49, v49, v49 row_ror:2 row_mask:0xf bank_mask:0xf
	s_nop 0
	v_add_f32_dpp v48, v48, v48 row_ror:1 row_mask:0xf bank_mask:0xf
	v_add_f32_dpp v49, v49, v49 row_ror:1 row_mask:0xf bank_mask:0xf
	s_nop 0
	v_pk_fma_f32 v[58:59], v[48:49], s[24:25], v[138:139] op_sel_hi:[1,0,0]
	s_nop 0
	v_mul_f32_e32 v35, 0x4b800000, v59
	v_cmp_gt_f32_e64 s[0:1], s33, v59
	v_cmp_gt_f32_e32 vcc, s33, v58
	s_nop 0
	v_cndmask_b32_e64 v35, v59, v35, s[0:1]
	v_rsq_f32_e32 v35, v35
	s_nop 0
	v_mul_f32_e32 v39, 0x45800000, v35
	v_cndmask_b32_e64 v86, v35, v39, s[0:1]
	v_mul_f32_e32 v35, 0x4b800000, v58
	v_cndmask_b32_e32 v35, v58, v35, vcc
	v_rsq_f32_e32 v35, v35
	v_pk_mul_f32 v[44:45], v[44:45], v[86:87] op_sel_hi:[1,0]
	v_pk_mul_f32 v[46:47], v[46:47], v[86:87] op_sel_hi:[1,0]
	s_waitcnt vmcnt(6)
	v_pk_fma_f32 v[54:55], v[26:27], v[44:45], v[30:31]
	v_pk_mul_f32 v[44:45], v[66:67], v[86:87] op_sel_hi:[1,0]
	v_mul_f32_e32 v39, 0x45800000, v35
	s_waitcnt vmcnt(4)
	v_pk_fma_f32 v[52:53], v[16:17], v[44:45], v[20:21]
	v_pk_mul_f32 v[44:45], v[64:65], v[86:87] op_sel_hi:[1,0]
	v_cndmask_b32_e32 v58, v35, v39, vcc
	v_pk_fma_f32 v[50:51], v[18:19], v[44:45], v[22:23]
	v_pk_mul_f32 v[44:45], v[62:63], v[86:87] op_sel_hi:[1,0]
	v_pk_fma_f32 v[56:57], v[24:25], v[46:47], v[28:29]
	s_waitcnt vmcnt(2)
	v_pk_fma_f32 v[48:49], v[8:9], v[44:45], v[12:13]
	v_pk_mul_f32 v[44:45], v[68:69], v[86:87] op_sel_hi:[1,0]
	v_pk_mul_f32 v[42:43], v[42:43], v[86:87] op_sel_hi:[1,0]
	v_pk_fma_f32 v[46:47], v[10:11], v[44:45], v[14:15]
	v_pk_mul_f32 v[44:45], v[60:61], v[86:87] op_sel_hi:[1,0]
	v_pk_mul_f32 v[60:61], v[80:81], v[58:59] op_sel_hi:[1,0]
	s_waitcnt vmcnt(0)
	v_pk_fma_f32 v[44:45], v[0:1], v[44:45], v[4:5]
	v_pk_fma_f32 v[24:25], v[24:25], v[60:61], v[28:29]
	v_pk_mul_f32 v[28:29], v[82:83], v[58:59] op_sel_hi:[1,0]
	v_pk_fma_f32 v[42:43], v[2:3], v[42:43], v[6:7]
	v_pk_fma_f32 v[26:27], v[26:27], v[28:29], v[30:31]
	v_pk_mul_f32 v[28:29], v[78:79], v[58:59] op_sel_hi:[1,0]
	v_cmp_lt_i32_e32 vcc, s17, v38
	v_pk_fma_f32 v[16:17], v[16:17], v[28:29], v[20:21]
	v_pk_mul_f32 v[20:21], v[76:77], v[58:59] op_sel_hi:[1,0]
	s_nop 0
	v_pk_fma_f32 v[18:19], v[18:19], v[20:21], v[22:23]
	v_pk_mul_f32 v[20:21], v[74:75], v[58:59] op_sel_hi:[1,0]
	s_nop 0
	v_pk_fma_f32 v[8:9], v[8:9], v[20:21], v[12:13]
	v_pk_mul_f32 v[12:13], v[84:85], v[58:59] op_sel_hi:[1,0]
	s_nop 0
	v_pk_fma_f32 v[10:11], v[10:11], v[12:13], v[14:15]
	v_pk_mul_f32 v[12:13], v[72:73], v[58:59] op_sel_hi:[1,0]
	s_nop 0
	v_pk_fma_f32 v[0:1], v[0:1], v[12:13], v[4:5]
	v_pk_mul_f32 v[4:5], v[70:71], v[58:59] op_sel_hi:[1,0]
	s_nop 0
	v_pk_fma_f32 v[2:3], v[2:3], v[4:5], v[6:7]
	v_add_u32_e32 v4, 0xfffff000, v38
	v_lshrrev_b32_e32 v4, 12, v4
	v_add_u32_e32 v4, 1, v4
	v_cndmask_b32_e32 v4, 0, v4, vcc
	v_mov_b32_e32 v5, v137
	v_lshl_add_u64 v[4:5], v[4:5], 0, s[8:9]
	v_mov_b64_e32 v[6:7], s[56:57]
	v_mad_u64_u32 v[6:7], s[0:1], v4, s16, v[6:7]
	v_mad_i32_i24 v7, v5, s16, v7
	v_lshl_add_u64 v[40:41], v[6:7], 0, v[40:41]
	global_load_dwordx4 v[4:7], v[40:41], off
	v_add_co_u32_e32 v12, vcc, s13, v40
	v_lshl_add_u64 v[70:71], v[40:41], 0, s[18:19]
	s_nop 0
	v_addc_co_u32_e32 v13, vcc, 0, v41, vcc
	global_load_dwordx4 v[12:15], v[12:13], off
	s_nop 0
	global_load_dwordx4 v[20:23], v[40:41], off offset:1024
	global_load_dwordx4 v[28:31], v[70:71], off offset:1024
	global_load_dwordx4 v[58:61], v[40:41], off offset:2048
	global_load_dwordx4 v[62:65], v[70:71], off offset:2048
	global_load_dwordx4 v[66:69], v[40:41], off offset:3072
	s_nop 0
	global_load_dwordx4 v[70:73], v[70:71], off offset:3072
	v_cvt_pk_bf16_f32 v40, v56, v57
	v_cvt_pk_bf16_f32 v41, v54, v55
	global_store_dwordx2 v[36:37], v[40:41], off
	s_waitcnt vmcnt(7)
	v_pk_add_f32 v[12:13], v[12:13], 1.0 op_sel_hi:[1,0]
	v_pk_add_f32 v[14:15], v[14:15], 1.0 op_sel_hi:[1,0]
	v_pk_fma_f32 v[40:41], v[12:13], v[56:57], v[4:5]
	v_pk_fma_f32 v[54:55], v[14:15], v[54:55], v[6:7]
	v_cvt_pk_bf16_f32 v40, v40, v41
	v_cvt_pk_bf16_f32 v41, v54, v55
	v_mov_b64_e32 v[54:55], s[62:63]
	v_mad_i64_i32 v[38:39], s[0:1], v38, s36, v[54:55]
	v_lshl_add_u64 v[38:39], v[38:39], 0, v[136:137]
	global_store_dwordx2 v[38:39], v[40:41], off
	v_cvt_pk_bf16_f32 v40, v52, v53
	v_cvt_pk_bf16_f32 v41, v50, v51
	s_waitcnt vmcnt(6)
	v_pk_add_f32 v[28:29], v[28:29], 1.0 op_sel_hi:[1,0]
	v_pk_add_f32 v[30:31], v[30:31], 1.0 op_sel_hi:[1,0]
	global_store_dwordx2 v[36:37], v[40:41], off offset:512
	v_pk_fma_f32 v[40:41], v[28:29], v[52:53], v[20:21]
	v_pk_fma_f32 v[50:51], v[30:31], v[50:51], v[22:23]
	v_cvt_pk_bf16_f32 v40, v40, v41
	v_cvt_pk_bf16_f32 v41, v50, v51
	global_store_dwordx2 v[38:39], v[40:41], off offset:512
	v_cvt_pk_bf16_f32 v40, v48, v49
	v_cvt_pk_bf16_f32 v41, v46, v47
	global_store_dwordx2 v[36:37], v[40:41], off offset:1024
	s_waitcnt vmcnt(7)
	v_pk_add_f32 v[40:41], v[62:63], 1.0 op_sel_hi:[1,0]
	v_pk_add_f32 v[50:51], v[64:65], 1.0 op_sel_hi:[1,0]
	v_pk_fma_f32 v[48:49], v[40:41], v[48:49], v[58:59]
	v_pk_fma_f32 v[46:47], v[50:51], v[46:47], v[60:61]
	v_cvt_pk_bf16_f32 v48, v48, v49
	v_cvt_pk_bf16_f32 v49, v46, v47
	v_cvt_pk_bf16_f32 v46, v44, v45
	v_cvt_pk_bf16_f32 v47, v42, v43
	global_store_dwordx2 v[38:39], v[48:49], off offset:1024
	global_store_dwordx2 v[36:37], v[46:47], off offset:1536
	s_waitcnt vmcnt(7)
	v_pk_add_f32 v[36:37], v[70:71], 1.0 op_sel_hi:[1,0]
	v_pk_add_f32 v[46:47], v[72:73], 1.0 op_sel_hi:[1,0]
	v_pk_fma_f32 v[44:45], v[36:37], v[44:45], v[66:67]
	v_pk_fma_f32 v[42:43], v[46:47], v[42:43], v[68:69]
	v_pk_fma_f32 v[4:5], v[12:13], v[24:25], v[4:5]
	v_pk_fma_f32 v[6:7], v[14:15], v[26:27], v[6:7]
	v_cvt_pk_bf16_f32 v44, v44, v45
	v_cvt_pk_bf16_f32 v45, v42, v43
	v_cvt_pk_bf16_f32 v4, v4, v5
	v_cvt_pk_bf16_f32 v5, v6, v7
	v_mad_i64_i32 v[6:7], s[0:1], v34, s36, v[54:55]
	global_store_dwordx2 v[38:39], v[44:45], off offset:1536
	v_cvt_pk_bf16_f32 v38, v24, v25
	v_cvt_pk_bf16_f32 v39, v26, v27
	v_lshl_add_u64 v[6:7], v[6:7], 0, v[136:137]
	global_store_dwordx2 v[32:33], v[38:39], off
	global_store_dwordx2 v[6:7], v[4:5], off
	v_cvt_pk_bf16_f32 v4, v16, v17
	v_cvt_pk_bf16_f32 v5, v18, v19
	global_store_dwordx2 v[32:33], v[4:5], off offset:512
	v_pk_fma_f32 v[4:5], v[28:29], v[16:17], v[20:21]
	v_pk_fma_f32 v[12:13], v[30:31], v[18:19], v[22:23]
	v_cvt_pk_bf16_f32 v4, v4, v5
	v_cvt_pk_bf16_f32 v5, v12, v13
	global_store_dwordx2 v[6:7], v[4:5], off offset:512
	v_cvt_pk_bf16_f32 v4, v8, v9
	v_cvt_pk_bf16_f32 v5, v10, v11
	global_store_dwordx2 v[32:33], v[4:5], off offset:1024
	v_pk_fma_f32 v[4:5], v[40:41], v[8:9], v[58:59]
	v_pk_fma_f32 v[8:9], v[50:51], v[10:11], v[60:61]
	v_cvt_pk_bf16_f32 v4, v4, v5
	v_cvt_pk_bf16_f32 v5, v8, v9
	global_store_dwordx2 v[6:7], v[4:5], off offset:1024
	v_cvt_pk_bf16_f32 v4, v0, v1
	v_cvt_pk_bf16_f32 v5, v2, v3
	v_pk_fma_f32 v[0:1], v[36:37], v[0:1], v[66:67]
	v_pk_fma_f32 v[2:3], v[46:47], v[2:3], v[68:69]
	v_cvt_pk_bf16_f32 v0, v0, v1
	v_cvt_pk_bf16_f32 v1, v2, v3
	global_store_dwordx2 v[32:33], v[4:5], off offset:1536
	global_store_dwordx2 v[6:7], v[0:1], off offset:1536
	s_cbranch_scc0 .LBB0_1056
